# GEMM mainloops: per-MFMA-block s_setprio flips deleted, one static s_setprio 1 for the trailing half (waves 4-7) per phase; on top of v2
# speedup vs baseline: 1.0053x; 1.0053x over previous
; __device__ __forceinline__ float rstd_of(const u64* ss, int row) { return __builtin_amdgcn_rsqf((float)ss[row] * (1.0f / (2048.0f * SS_SCALE)) + RMS_EPS); }
; #define LAS __attribute__((address_space(3)))
; __device__ __forceinline__ void fill_rstd(LAS unsigned char* L, const pg8::StaticOrder& S, const pg8::u64* ssx, int tid) {
;     LAS float* tabl = (LAS float*)(L + pg8::RSTD_OFF); pg8::Unit u; int last = -1;
;     for (int i = 0; S.next(i, u); ++i) { if (u.pm != last) { last = u.pm; if (tid < 256) tabl[((u.pm >> 3) & 3) * 256 + tid] = pg8::rstd_of(ssx, u.pm * 256 + tid); } }
;     __syncthreads();
.LBB0_65:
	s_or_b64 exec, exec, s[6:7]
	s_setprio 0
	v_mov_b32_e32 v0, v252
	s_movk_i32 s6, 0xff
	v_add_u32_e32 v2, s81, v0
	s_ashr_i32 s3, s2, 31
	s_add_i32 s82, 0, 0x24800
	v_cmp_lt_i32_e32 vcc, s6, v2
	s_ashr_i32 s23, s24, 31
	s_mov_b32 s80, s24
	v_lshl_add_u32 v3, v2, 2, s82
	s_mov_b32 s15, -1
	v_mov_b64_e32 v[0:1], 0xbff
	s_movk_i32 s14, 0x181
	s_xor_b64 s[6:7], vcc, -1
	v_mov_b32_e32 v4, 0x358637bd
	s_mov_b64 s[8:9], s[2:3]
	s_branch .LBB0_68

; #define PG8_STAGE(bufoff, gbase, voff) do { _Pragma("unroll") for (int _i = 0; _i < 2; ++_i) \
;         __builtin_amdgcn_global_load_lds((const unsigned*)((const char*)(gbase) + (voff)[_i]), (PG8_LAS unsigned*)(lds + (bufoff) + ldsw + _i * 8192), 16, 0, 0); } while (0)
; #define PG8_WAIT_V(n) asm volatile("s_waitcnt vmcnt(" #n ")" ::: "memory")
; #define PG8_BAR __builtin_amdgcn_s_barrier()
; template <class Epi, class Sched, bool ALIGN_EPI = false, bool SP2 = false>
; __device__ __forceinline__ void gemm_phase(PG8_LAS unsigned char* lds, const Gemm g, const Sched& S, const Epi& E, int tid_in) {
;     int tid_ = tid_in; asm volatile("" : "+v"(tid_)); const int tid = tid_, wid = __builtin_amdgcn_readfirstlane(tid >> 6), lane = tid & 63, wr = wid >> 2, wc = wid & 3, fr = lane & 15, fq = lane >> 4;
;     const int K = g.K, nt = K / BK;
;     unsigned voffA[2], voffB[2];
; #pragma unroll
;     for (int i = 0; i < 2; ++i) { int R, C; stage_rc(tid * 16 + i * 8192, R, C); const int Rb = 2 * (R & ~31) + (Epi::PERM ? perm32(R & 31) : (R & 31));
;         voffA[i] = (unsigned)(R * g.lda + C) * 2u; voffB[i] = (unsigned)(Rb * K + C) * 2u; }
;     const size_t kstep = (size_t)(BK * 2);
;     const size_t hstep = (size_t)HALF * g.lda * 2;
;     const size_t hstepB = (size_t)32 * K * 2;
;     const size_t tstep = 2 * hstep, tstepB = (size_t)BM * K * 2;
;     const unsigned ldsw = (unsigned)wid * 1024u;
;     const int aoff = lds_byte(wr * 64 + fr, fq * 8), boff = lds_byte(wc * 32 + fr, fq * 8);
;     ...
;     const char* cA = (const char*)g.A + (size_t)cur.pm * tstep; const char* cB = (const char*)g.Bt + (size_t)cur.pn * tstepB;
;     S.a_ready(cur);
;     if constexpr (SP2) {
;         PG8_STAGE(PG8_SB(0, 0), cB, voffB); PG8_STAGE(PG8_SB(0, 1), cB + hstepB, voffB); PG8_STAGE(PG8_SA(0, 0), cA, voffA); PG8_STAGE(PG8_SA(0, 1), cA + hstep, voffA);
;         if (wr == 1) PG8_BAR;
;         PG8_WAIT_V(2); PG8_BAR;
;         PG8_STAGE(PG8_SB(1, 0), cB + kstep, voffB); PG8_STAGE(PG8_SA(1, 0), cA + kstep, voffA); PG8_STAGE(PG8_SB(1, 1), cB + hstepB + kstep, voffB);
;         PG8_WAIT_V(6); PG8_BAR;
.LBB0_71:
	s_add_u32 s28, s18, 0x8800000
	s_addc_u32 s29, s19, 0
	s_add_u32 s34, s18, 0x18800000
	s_setprio 0
	v_mov_b32_e32 v0, v252
	s_addc_u32 s35, s19, 0
	s_waitcnt lgkmcnt(0)
	s_barrier
	s_cmpk_gt_i32 s2, 0xbff
	s_waitcnt vmcnt(9)
	v_add_u32_e32 v10, s81, v0
	s_nop 0
	v_readfirstlane_b32 s14, v10
	s_cbranch_scc1 .LBB0_87
	v_lshlrev_b32_e32 v12, 4, v10
	v_add_u32_e32 v0, 0x2000, v12
	v_ashrrev_i32_e32 v1, 31, v0
	v_lshrrev_b32_e32 v1, 22, v1
	v_add_u32_e32 v1, v0, v1
	v_ashrrev_i32_e32 v8, 10, v1
	v_mul_i32_i24_e32 v1, 0x400, v8
	v_sub_u32_e32 v0, v0, v1
	v_lshrrev_b32_e32 v1, 4, v0
	v_bitop3_b32 v0, v1, v0, 32 bitop3:0x6c
	v_ashrrev_i32_e32 v1, 31, v0
	v_lshrrev_b32_e32 v1, 26, v1
	v_add_u32_e32 v1, v0, v1
	v_lshlrev_b32_e32 v3, 3, v8
	v_ashrrev_i32_e32 v9, 6, v1
	v_and_b32_e32 v3, -16, v3
	s_lshr_b32 s6, s3, 29
	v_add_u32_e32 v3, v9, v3
	s_add_i32 s6, s2, s6
	s_ashr_i32 s7, s14, 6
	v_lshrrev_b32_e32 v4, 2, v3
	v_lshlrev_b32_e32 v5, 1, v3
	v_and_b32_e32 v1, 0xc0, v1
	s_ashr_i32 s8, s6, 3
	s_and_b32 s6, s6, -8
	s_ashr_i32 s38, s14, 8
	s_lshl_b32 s54, s7, 10
	v_and_b32_e32 v2, 3, v9
	v_and_b32_e32 v4, 4, v4
	v_and_b32_e32 v5, 0xfffd8, v5
	v_sub_u32_e32 v0, v0, v1
	v_mov_b32_e32 v1, 1
	s_sub_i32 s6, s2, s6
	v_or3_b32 v2, v2, v4, v5
	v_lshlrev_b32_e32 v4, 5, v8
	v_ashrrev_i16_sdwa v0, v1, sext(v0) dst_sel:DWORD dst_unused:UNUSED_PAD src0_sel:DWORD src1_sel:BYTE_0
	s_cmp_lt_i32 s6, 0
	s_movk_i32 s55, 0x181
	v_and_b32_e32 v4, 32, v4
	v_bfe_i32 v11, v0, 0, 16
	s_cselect_b32 s9, s55, 0x180
	v_add_lshl_u32 v0, v4, v11, 1
	s_mul_i32 s6, s6, s9
	v_lshl_add_u32 v128, v2, 12, v0
	v_lshl_add_u32 v130, v3, 12, v0
	v_bfe_i32 v0, v10, 27, 1
	s_add_i32 s6, s6, s8
	v_lshrrev_b32_e32 v0, 22, v0
	s_mul_hi_i32 s8, s6, 0x2aaaaaab
	v_add_u32_e32 v0, v12, v0
	s_lshr_b32 s9, s8, 31
	s_ashr_i32 s8, s8, 5
	v_and_b32_e32 v0, 0xfffffc00, v0
	s_add_i32 s8, s8, s9
	v_sub_u32_e32 v0, v12, v0
	s_lshl_b32 s9, s8, 3
	s_mulk_i32 s8, 0xc0
	v_lshrrev_b32_e32 v2, 4, v0
	v_ashrrev_i32_e32 v4, 31, v10
	s_sub_i32 s8, s6, s8
	v_bitop3_b32 v0, v2, v0, 32 bitop3:0x6c
	v_lshrrev_b32_e32 v4, 26, v4
	s_sext_i32_i16 s6, s8
	v_ashrrev_i32_e32 v2, 31, v0
	v_add_u32_e32 v4, v10, v4
	s_bfe_u32 s6, s6, 0x3001c
	v_lshrrev_b32_e32 v2, 26, v2
	s_waitcnt vmcnt(8)
	v_ashrrev_i32_e32 v14, 6, v4
	s_add_i32 s10, s8, s6
	v_add_u32_e32 v2, v0, v2
	v_lshlrev_b32_e32 v4, 3, v14
	s_sext_i32_i16 s6, s10
	s_and_b32 s10, s10, 0xfff8
	v_ashrrev_i32_e32 v13, 6, v2
	v_and_b32_e32 v4, -16, v4
	s_sub_i32 s8, s8, s10
	v_add_u32_e32 v4, v13, v4
	s_sext_i32_i16 s8, s8
	v_lshrrev_b32_e32 v5, 2, v4
	v_lshlrev_b32_e32 v6, 1, v4
	v_and_b32_e32 v2, 0xc0, v2
	s_lshr_b32 s6, s6, 3
	s_add_i32 s46, s9, s8
	v_and_b32_e32 v3, 3, v13
	v_and_b32_e32 v5, 4, v5
	v_and_b32_e32 v6, 0xfffd8, v6
	v_sub_u32_e32 v0, v0, v2
	s_ashr_i32 s47, s46, 31
	s_bfe_i64 s[10:11], s[6:7], 0x100000
	v_or3_b32 v3, v3, v5, v6
	v_lshlrev_b32_e32 v5, 5, v14
	v_ashrrev_i16_sdwa v0, v1, sext(v0) dst_sel:DWORD dst_unused:UNUSED_PAD src0_sel:DWORD src1_sel:BYTE_0
	s_lshl_b64 s[8:9], s[46:47], 20
	s_lshl_b64 s[10:11], s[10:11], 20
	v_and_b32_e32 v5, 32, v5
	v_bfe_i32 v15, v0, 0, 16
	s_add_u32 s50, s36, s10
	v_add_lshl_u32 v0, v5, v15, 1
	s_addc_u32 s51, s37, s11
	s_add_i32 s47, s54, 0
	v_lshl_add_u32 v132, v3, 12, v0
	s_add_i32 m0, s47, 0x10000
	v_lshl_add_u32 v134, v4, 12, v0
	global_load_lds_dwordx4 v132, s[50:51]
	s_add_i32 m0, s47, 0x12000
	s_add_u32 s10, s50, 0x20000
	global_load_lds_dwordx4 v128, s[50:51]
	s_addc_u32 s11, s51, 0
	s_add_i32 m0, s47, 0x14000
	v_mov_b32_e32 v133, 0
	global_load_lds_dwordx4 v132, s[10:11]
	s_add_i32 m0, s47, 0x16000
	s_add_u32 s48, s28, s8
	s_addc_u32 s49, s29, s9
	s_add_i32 s56, s47, 0x2000
	global_load_lds_dwordx4 v128, s[10:11]
	s_mov_b32 m0, s47
	s_add_u32 s8, s48, 0x80000
	global_load_lds_dwordx4 v134, s[48:49]
	s_mov_b32 m0, s56
	s_addc_u32 s9, s49, 0
	s_add_i32 s57, s47, 0x4000
	global_load_lds_dwordx4 v130, s[48:49]
	s_mov_b32 m0, s57
	s_add_i32 s58, s47, 0x6000
	global_load_lds_dwordx4 v134, s[8:9]
	s_mov_b32 m0, s58
	v_mov_b32_e32 v129, v133
	global_load_lds_dwordx4 v130, s[8:9]
	v_mov_b32_e32 v135, v133
	v_mov_b32_e32 v131, v133
	s_cmp_eq_u32 s38, 1
	s_mov_b32 s59, 0
	v_lshl_add_u64 v[6:7], s[50:51], 0, v[132:133]
	v_lshl_add_u64 v[4:5], s[50:51], 0, v[128:129]
	v_lshl_add_u64 v[0:1], s[48:49], 0, v[134:135]
	s_cselect_b64 s[8:9], -1, 0
	s_cmp_lg_u32 s38, 1
	v_lshl_add_u64 v[2:3], s[48:49], 0, v[130:131]
	s_cbranch_scc1 .LBB0_74
	s_barrier
	s_setprio 1

; #define PG8_STAGE(bufoff, gbase, voff) do { _Pragma("unroll") for (int _i = 0; _i < 2; ++_i) \
;         __builtin_amdgcn_global_load_lds((const unsigned*)((const char*)(gbase) + (voff)[_i]), (PG8_LAS unsigned*)(lds + (bufoff) + ldsw + _i * 8192), 16, 0, 0); } while (0)
; #define PG8_LDA(dst, b, h) do { _Pragma("unroll") for (int m = 0; m < 4; ++m) _Pragma("unroll") for (int k = 0; k < 2; ++k) dst[m][k] = *(const PG8_LAS bf16x8*)(lds + PG8_SA(b, h) + aoff + m * 2048 + k * 1024); } while (0)
; #define PG8_LDB(dst, b, h) do { _Pragma("unroll") for (int n = 0; n < 2; ++n) _Pragma("unroll") for (int k = 0; k < 2; ++k) dst[n][k] = *(const PG8_LAS bf16x8*)(lds + PG8_SB(b, h) + boff + n * 2048 + k * 1024); } while (0)
; #define PG8_MMA(ai, bj, At, Bt) do { __builtin_amdgcn_s_setprio(1); _Pragma("unroll") for (int m = 0; m < 4; ++m) _Pragma("unroll") for (int n = 0; n < 2; ++n) _Pragma("unroll") for (int k = 0; k < 2; ++k) \
;         acc[ai][bj][m][n] = __builtin_amdgcn_mfma_f32_16x16x32_bf16(Bt[n][k], At[m][k], acc[ai][bj][m][n], 0, 0, 0); __builtin_amdgcn_s_setprio(0); } while (0)
; #define PG8_WAIT_V(n) asm volatile("s_waitcnt vmcnt(" #n ")" ::: "memory")
; #define PG8_WAIT_L(n) asm volatile("s_waitcnt lgkmcnt(" #n ")" ::: "memory")
; #define PG8_BAR __builtin_amdgcn_s_barrier()
; #define PG8_SCHED __builtin_amdgcn_sched_barrier(0)
; template <class Epi, class Sched, bool ALIGN_EPI = false, bool SP2 = false>
; __device__ __forceinline__ void gemm_phase(PG8_LAS unsigned char* lds, const Gemm g, const Sched& S, const Epi& E, int tid_in) {
;     ...
;             PG8_LDB(B0, 0, 0); PG8_LDB(B1, 0, 1); PG8_SCHED; PG8_LDA(At, 0, 0); PG8_STAGE(PG8_SA(1, 1), a1 + hstep, voffA);
;             PG8_WAIT_V(8); PG8_WAIT_L(0); PG8_BAR; PG8_MMA(0, 0, At, B0); PG8_MMA(0, 1, At, B1); PG8_BAR; PG8_SCHED;
;             PG8_LDA(At, 0, 1); PG8_STAGE(PG8_SB(0, 0), b2, voffB); PG8_STAGE(PG8_SB(0, 1), b2 + hstepB, voffB); PG8_STAGE(PG8_SA(0, 0), a2, voffA);
;             PG8_WAIT_V(8); PG8_WAIT_L(0); PG8_BAR; PG8_MMA(1, 0, At, B0); PG8_MMA(1, 1, At, B1); PG8_BAR; PG8_SCHED;
.Lkb_skip_0:
.LBB0_80:
	ds_read_b128 v[156:159], v150
	ds_read_b128 v[160:163], v150 offset:1024
	ds_read_b128 v[164:167], v150 offset:2048
	ds_read_b128 v[168:171], v150 offset:3072
	ds_read_b128 v[172:175], v151
	ds_read_b128 v[176:179], v151 offset:1024
	ds_read_b128 v[180:183], v151 offset:2048
	ds_read_b128 v[184:187], v151 offset:3072
	s_add_u32 s26, s48, 0xfff80080
	s_addc_u32 s27, s49, -1
	s_cmp_eq_u32 s76, 28
	s_cselect_b32 s53, s41, s27
	s_cselect_b32 s52, s70, s26
	s_cselect_b32 s51, s39, s75
	s_cselect_b32 s50, s71, s74
	v_lshl_add_u64 v[204:205], s[48:49], 0, v[138:139]
	s_add_i32 m0, s47, 0xc000
	ds_read_b128 v[188:191], v152
	ds_read_b128 v[192:195], v152 offset:1024
	ds_read_b128 v[196:199], v152 offset:2048
	ds_read_b128 v[200:203], v152 offset:3072
	ds_read_b128 v[212:215], v152 offset:4096
	ds_read_b128 v[216:219], v152 offset:5120
	ds_read_b128 v[220:223], v152 offset:6144
	ds_read_b128 v[224:227], v152 offset:7168
	global_load_lds_dwordx4 v[204:205], off
	v_lshl_add_u64 v[204:205], s[48:49], 0, v[140:141]
	s_add_i32 m0, s47, 0xe000
	s_nop 0
	global_load_lds_dwordx4 v[204:205], off
	s_waitcnt vmcnt(8)
	s_waitcnt lgkmcnt(0)
	s_barrier
	s_waitcnt lgkmcnt(0)
	v_mfma_f32_16x16x32_bf16 v[124:127], v[156:159], v[188:191], v[124:127]
	v_mfma_f32_16x16x32_bf16 v[120:123], v[164:167], v[188:191], v[120:123]
	v_mfma_f32_16x16x32_bf16 v[108:111], v[156:159], v[196:199], v[108:111]
	v_mfma_f32_16x16x32_bf16 v[104:107], v[164:167], v[196:199], v[104:107]
	v_mfma_f32_16x16x32_bf16 v[92:95], v[156:159], v[212:215], v[92:95]
	v_mfma_f32_16x16x32_bf16 v[88:91], v[164:167], v[212:215], v[88:91]
	v_mfma_f32_16x16x32_bf16 v[76:79], v[156:159], v[220:223], v[76:79]
	v_mfma_f32_16x16x32_bf16 v[72:75], v[164:167], v[220:223], v[72:75]
	v_mfma_f32_16x16x32_bf16 v[124:127], v[160:163], v[192:195], v[124:127]
	v_mfma_f32_16x16x32_bf16 v[120:123], v[168:171], v[192:195], v[120:123]
	v_mfma_f32_16x16x32_bf16 v[108:111], v[160:163], v[200:203], v[108:111]
	v_mfma_f32_16x16x32_bf16 v[104:107], v[168:171], v[200:203], v[104:107]
	v_mfma_f32_16x16x32_bf16 v[92:95], v[160:163], v[216:219], v[92:95]
	v_mfma_f32_16x16x32_bf16 v[88:91], v[168:171], v[216:219], v[88:91]
	v_mfma_f32_16x16x32_bf16 v[76:79], v[160:163], v[224:227], v[76:79]
	v_mfma_f32_16x16x32_bf16 v[72:75], v[168:171], v[224:227], v[72:75]
	v_mfma_f32_16x16x32_bf16 v[116:119], v[172:175], v[188:191], v[116:119]
	v_mfma_f32_16x16x32_bf16 v[112:115], v[180:183], v[188:191], v[112:115]
	v_mfma_f32_16x16x32_bf16 v[100:103], v[172:175], v[196:199], v[100:103]
	v_mfma_f32_16x16x32_bf16 v[96:99], v[180:183], v[196:199], v[96:99]
	v_mfma_f32_16x16x32_bf16 v[84:87], v[172:175], v[212:215], v[84:87]
	v_mfma_f32_16x16x32_bf16 v[80:83], v[180:183], v[212:215], v[80:83]
	v_mfma_f32_16x16x32_bf16 v[68:71], v[172:175], v[220:223], v[68:71]
	v_mfma_f32_16x16x32_bf16 v[64:67], v[180:183], v[220:223], v[64:67]
	v_mfma_f32_16x16x32_bf16 v[116:119], v[176:179], v[192:195], v[116:119]
	v_mfma_f32_16x16x32_bf16 v[112:115], v[184:187], v[192:195], v[112:115]
	v_mfma_f32_16x16x32_bf16 v[100:103], v[176:179], v[200:203], v[100:103]
	v_mfma_f32_16x16x32_bf16 v[96:99], v[184:187], v[200:203], v[96:99]
	v_mfma_f32_16x16x32_bf16 v[84:87], v[176:179], v[216:219], v[84:87]
	v_mfma_f32_16x16x32_bf16 v[80:83], v[184:187], v[216:219], v[80:83]
	v_mfma_f32_16x16x32_bf16 v[68:71], v[176:179], v[224:227], v[68:71]
	v_mfma_f32_16x16x32_bf16 v[64:67], v[184:187], v[224:227], v[64:67]
	s_barrier
	s_add_i32 s26, s67, s54
	v_lshl_add_u64 v[204:205], s[50:51], 0, v[132:133]
	s_mov_b32 m0, s26
	ds_read_b128 v[188:191], v152 offset:16384
	ds_read_b128 v[192:195], v152 offset:17408
	ds_read_b128 v[196:199], v152 offset:18432
	ds_read_b128 v[200:203], v152 offset:19456
	ds_read_b128 v[212:215], v152 offset:20480
	ds_read_b128 v[216:219], v152 offset:21504
	ds_read_b128 v[220:223], v152 offset:22528
	ds_read_b128 v[224:227], v152 offset:23552
	global_load_lds_dwordx4 v[204:205], off
	s_add_i32 m0, s26, 0x2000
	s_add_u32 s26, s50, 0x20000
	v_lshl_add_u64 v[206:207], s[50:51], 0, v[128:129]
	s_addc_u32 s27, s51, 0
	s_add_i32 s33, s68, s54
	global_load_lds_dwordx4 v[206:207], off
	v_lshl_add_u64 v[208:209], s[26:27], 0, v[132:133]
	s_mov_b32 m0, s33
	v_lshl_add_u64 v[228:229], s[52:53], 0, v[130:131]
	global_load_lds_dwordx4 v[208:209], off
	v_lshl_add_u64 v[208:209], s[26:27], 0, v[128:129]
	s_add_i32 m0, s33, 0x2000
	s_nop 0
	global_load_lds_dwordx4 v[208:209], off
	v_lshl_add_u64 v[208:209], s[52:53], 0, v[134:135]
	s_mov_b32 m0, s47
	s_nop 0
	global_load_lds_dwordx4 v[208:209], off
	s_mov_b32 m0, s56
	s_nop 0
	global_load_lds_dwordx4 v[228:229], off
	s_waitcnt vmcnt(8)
	s_waitcnt lgkmcnt(0)
	s_barrier
; #define PG8_STAGE(bufoff, gbase, voff) do { _Pragma("unroll") for (int _i = 0; _i < 2; ++_i) \
;         __builtin_amdgcn_global_load_lds((const unsigned*)((const char*)(gbase) + (voff)[_i]), (PG8_LAS unsigned*)(lds + (bufoff) + ldsw + _i * 8192), 16, 0, 0); } while (0)
; #define PG8_LDA(dst, b, h) do { _Pragma("unroll") for (int m = 0; m < 4; ++m) _Pragma("unroll") for (int k = 0; k < 2; ++k) dst[m][k] = *(const PG8_LAS bf16x8*)(lds + PG8_SA(b, h) + aoff + m * 2048 + k * 1024); } while (0)
; #define PG8_LDB(dst, b, h) do { _Pragma("unroll") for (int n = 0; n < 2; ++n) _Pragma("unroll") for (int k = 0; k < 2; ++k) dst[n][k] = *(const PG8_LAS bf16x8*)(lds + PG8_SB(b, h) + boff + n * 2048 + k * 1024); } while (0)
; #define PG8_MMA(ai, bj, At, Bt) do { __builtin_amdgcn_s_setprio(1); _Pragma("unroll") for (int m = 0; m < 4; ++m) _Pragma("unroll") for (int n = 0; n < 2; ++n) _Pragma("unroll") for (int k = 0; k < 2; ++k) \
;         acc[ai][bj][m][n] = __builtin_amdgcn_mfma_f32_16x16x32_bf16(Bt[n][k], At[m][k], acc[ai][bj][m][n], 0, 0, 0); __builtin_amdgcn_s_setprio(0); } while (0)
; #define PG8_WAIT_V(n) asm volatile("s_waitcnt vmcnt(" #n ")" ::: "memory")
; #define PG8_WAIT_L(n) asm volatile("s_waitcnt lgkmcnt(" #n ")" ::: "memory")
; #define PG8_BAR __builtin_amdgcn_s_barrier()
; #define PG8_SCHED __builtin_amdgcn_sched_barrier(0)
; template <class Epi, class Sched, bool ALIGN_EPI = false, bool SP2 = false>
; __device__ __forceinline__ void gemm_phase(PG8_LAS unsigned char* lds, const Gemm g, const Sched& S, const Epi& E, int tid_in) {
;     ...
;             PG8_WAIT_V(8); PG8_WAIT_L(0); PG8_BAR; PG8_MMA(1, 0, At, B0); PG8_MMA(1, 1, At, B1); PG8_BAR; PG8_SCHED;
;             PG8_LDB(B0, 1, 0); PG8_LDB(B1, 1, 1); PG8_SCHED; PG8_LDA(At, 1, 0); PG8_STAGE(PG8_SA(0, 1), a2 + hstep, voffA);
;             PG8_WAIT_V(8); PG8_WAIT_L(0); PG8_BAR; PG8_MMA(0, 0, At, B0); PG8_MMA(0, 1, At, B1); PG8_BAR; PG8_SCHED;
	s_waitcnt lgkmcnt(0)
	v_mfma_f32_16x16x32_bf16 v[60:63], v[156:159], v[188:191], v[60:63]
	v_mfma_f32_16x16x32_bf16 v[56:59], v[164:167], v[188:191], v[56:59]
	v_mfma_f32_16x16x32_bf16 v[44:47], v[156:159], v[196:199], v[44:47]
	v_mfma_f32_16x16x32_bf16 v[40:43], v[164:167], v[196:199], v[40:43]
	v_mfma_f32_16x16x32_bf16 v[28:31], v[156:159], v[212:215], v[28:31]
	v_mfma_f32_16x16x32_bf16 v[24:27], v[164:167], v[212:215], v[24:27]
	v_mfma_f32_16x16x32_bf16 v[12:15], v[156:159], v[220:223], v[12:15]
	v_mfma_f32_16x16x32_bf16 v[8:11], v[164:167], v[220:223], v[8:11]
	v_mfma_f32_16x16x32_bf16 v[60:63], v[160:163], v[192:195], v[60:63]
	v_mfma_f32_16x16x32_bf16 v[56:59], v[168:171], v[192:195], v[56:59]
	v_mfma_f32_16x16x32_bf16 v[44:47], v[160:163], v[200:203], v[44:47]
	v_mfma_f32_16x16x32_bf16 v[40:43], v[168:171], v[200:203], v[40:43]
	v_mfma_f32_16x16x32_bf16 v[28:31], v[160:163], v[216:219], v[28:31]
	v_mfma_f32_16x16x32_bf16 v[24:27], v[168:171], v[216:219], v[24:27]
	v_mfma_f32_16x16x32_bf16 v[12:15], v[160:163], v[224:227], v[12:15]
	v_mfma_f32_16x16x32_bf16 v[8:11], v[168:171], v[224:227], v[8:11]
	v_mfma_f32_16x16x32_bf16 v[52:55], v[172:175], v[188:191], v[52:55]
	v_mfma_f32_16x16x32_bf16 v[48:51], v[180:183], v[188:191], v[48:51]
	v_mfma_f32_16x16x32_bf16 v[36:39], v[172:175], v[196:199], v[36:39]
	v_mfma_f32_16x16x32_bf16 v[32:35], v[180:183], v[196:199], v[32:35]
	v_mfma_f32_16x16x32_bf16 v[20:23], v[172:175], v[212:215], v[20:23]
	v_mfma_f32_16x16x32_bf16 v[16:19], v[180:183], v[212:215], v[16:19]
	v_mfma_f32_16x16x32_bf16 v[4:7], v[172:175], v[220:223], v[4:7]
	v_mfma_f32_16x16x32_bf16 v[0:3], v[180:183], v[220:223], v[0:3]
	v_mfma_f32_16x16x32_bf16 v[52:55], v[176:179], v[192:195], v[52:55]
	v_mfma_f32_16x16x32_bf16 v[48:51], v[184:187], v[192:195], v[48:51]
	v_mfma_f32_16x16x32_bf16 v[36:39], v[176:179], v[200:203], v[36:39]
	v_mfma_f32_16x16x32_bf16 v[32:35], v[184:187], v[200:203], v[32:35]
	v_mfma_f32_16x16x32_bf16 v[20:23], v[176:179], v[216:219], v[20:23]
	v_mfma_f32_16x16x32_bf16 v[16:19], v[184:187], v[216:219], v[16:19]
	v_mfma_f32_16x16x32_bf16 v[4:7], v[176:179], v[224:227], v[4:7]
	v_mfma_f32_16x16x32_bf16 v[0:3], v[184:187], v[224:227], v[0:3]
	s_barrier
	s_add_i32 s33, 0, 0x18000
	v_add_u32_e32 v155, s33, v146
	s_add_i32 s77, 0, 0x1c000
	ds_read_b128 v[156:159], v155
	ds_read_b128 v[160:163], v155 offset:1024
	ds_read_b128 v[164:167], v155 offset:2048
	ds_read_b128 v[168:171], v155 offset:3072
	v_add_u32_e32 v155, s77, v146
	ds_read_b128 v[172:175], v155
	ds_read_b128 v[176:179], v155 offset:1024
	ds_read_b128 v[180:183], v155 offset:2048
	ds_read_b128 v[184:187], v155 offset:3072
	s_add_u32 s26, s52, 0x80000
	s_addc_u32 s27, s53, 0
	s_mov_b32 m0, s57
	v_lshl_add_u64 v[230:231], s[26:27], 0, v[134:135]
	ds_read_b128 v[188:191], v152 offset:32768
	ds_read_b128 v[192:195], v152 offset:33792
	ds_read_b128 v[196:199], v152 offset:34816
	ds_read_b128 v[200:203], v152 offset:35840
	ds_read_b128 v[212:215], v152 offset:36864
	ds_read_b128 v[216:219], v152 offset:37888
	ds_read_b128 v[220:223], v152 offset:38912
	ds_read_b128 v[224:227], v152 offset:39936
	global_load_lds_dwordx4 v[230:231], off
	v_lshl_add_u64 v[230:231], s[26:27], 0, v[130:131]
	s_mov_b32 m0, s58
	s_nop 0
	global_load_lds_dwordx4 v[230:231], off
	s_waitcnt vmcnt(8)
	s_waitcnt lgkmcnt(0)
	s_barrier
	s_waitcnt lgkmcnt(0)
	v_mfma_f32_16x16x32_bf16 v[124:127], v[156:159], v[188:191], v[124:127]
	v_mfma_f32_16x16x32_bf16 v[120:123], v[164:167], v[188:191], v[120:123]
	v_mfma_f32_16x16x32_bf16 v[108:111], v[156:159], v[196:199], v[108:111]
	v_mfma_f32_16x16x32_bf16 v[104:107], v[164:167], v[196:199], v[104:107]
	v_mfma_f32_16x16x32_bf16 v[92:95], v[156:159], v[212:215], v[92:95]
	v_mfma_f32_16x16x32_bf16 v[88:91], v[164:167], v[212:215], v[88:91]
	v_mfma_f32_16x16x32_bf16 v[76:79], v[156:159], v[220:223], v[76:79]
	v_mfma_f32_16x16x32_bf16 v[72:75], v[164:167], v[220:223], v[72:75]
	v_mfma_f32_16x16x32_bf16 v[124:127], v[160:163], v[192:195], v[124:127]
	v_mfma_f32_16x16x32_bf16 v[120:123], v[168:171], v[192:195], v[120:123]
	v_mfma_f32_16x16x32_bf16 v[108:111], v[160:163], v[200:203], v[108:111]
	v_mfma_f32_16x16x32_bf16 v[104:107], v[168:171], v[200:203], v[104:107]
	v_mfma_f32_16x16x32_bf16 v[92:95], v[160:163], v[216:219], v[92:95]
	v_mfma_f32_16x16x32_bf16 v[88:91], v[168:171], v[216:219], v[88:91]
	v_mfma_f32_16x16x32_bf16 v[76:79], v[160:163], v[224:227], v[76:79]
	v_mfma_f32_16x16x32_bf16 v[72:75], v[168:171], v[224:227], v[72:75]
	v_mfma_f32_16x16x32_bf16 v[116:119], v[172:175], v[188:191], v[116:119]
	v_mfma_f32_16x16x32_bf16 v[112:115], v[180:183], v[188:191], v[112:115]
	v_mfma_f32_16x16x32_bf16 v[100:103], v[172:175], v[196:199], v[100:103]
	v_mfma_f32_16x16x32_bf16 v[96:99], v[180:183], v[196:199], v[96:99]
	v_mfma_f32_16x16x32_bf16 v[84:87], v[172:175], v[212:215], v[84:87]
	v_mfma_f32_16x16x32_bf16 v[80:83], v[180:183], v[212:215], v[80:83]
	v_mfma_f32_16x16x32_bf16 v[68:71], v[172:175], v[220:223], v[68:71]
	v_mfma_f32_16x16x32_bf16 v[64:67], v[180:183], v[220:223], v[64:67]
	v_mfma_f32_16x16x32_bf16 v[116:119], v[176:179], v[192:195], v[116:119]
	v_mfma_f32_16x16x32_bf16 v[112:115], v[184:187], v[192:195], v[112:115]
	v_mfma_f32_16x16x32_bf16 v[100:103], v[176:179], v[200:203], v[100:103]
	v_mfma_f32_16x16x32_bf16 v[96:99], v[184:187], v[200:203], v[96:99]
	v_mfma_f32_16x16x32_bf16 v[84:87], v[176:179], v[216:219], v[84:87]
	v_mfma_f32_16x16x32_bf16 v[80:83], v[184:187], v[216:219], v[80:83]
	v_mfma_f32_16x16x32_bf16 v[68:71], v[176:179], v[224:227], v[68:71]
	v_mfma_f32_16x16x32_bf16 v[64:67], v[184:187], v[224:227], v[64:67]
	s_barrier
; #define PG8_STAGE(bufoff, gbase, voff) do { _Pragma("unroll") for (int _i = 0; _i < 2; ++_i) \
;         __builtin_amdgcn_global_load_lds((const unsigned*)((const char*)(gbase) + (voff)[_i]), (PG8_LAS unsigned*)(lds + (bufoff) + ldsw + _i * 8192), 16, 0, 0); } while (0)
; #define PG8_LDA(dst, b, h) do { _Pragma("unroll") for (int m = 0; m < 4; ++m) _Pragma("unroll") for (int k = 0; k < 2; ++k) dst[m][k] = *(const PG8_LAS bf16x8*)(lds + PG8_SA(b, h) + aoff + m * 2048 + k * 1024); } while (0)
; #define PG8_MMA(ai, bj, At, Bt) do { __builtin_amdgcn_s_setprio(1); _Pragma("unroll") for (int m = 0; m < 4; ++m) _Pragma("unroll") for (int n = 0; n < 2; ++n) _Pragma("unroll") for (int k = 0; k < 2; ++k) \
;         acc[ai][bj][m][n] = __builtin_amdgcn_mfma_f32_16x16x32_bf16(Bt[n][k], At[m][k], acc[ai][bj][m][n], 0, 0, 0); __builtin_amdgcn_s_setprio(0); } while (0)
; #define PG8_WAIT_V(n) asm volatile("s_waitcnt vmcnt(" #n ")" ::: "memory")
; #define PG8_WAIT_L(n) asm volatile("s_waitcnt lgkmcnt(" #n ")" ::: "memory")
; #define PG8_BAR __builtin_amdgcn_s_barrier()
; #define PG8_SCHED __builtin_amdgcn_sched_barrier(0)
; template <class Epi, class Sched, bool ALIGN_EPI = false, bool SP2 = false>
; __device__ __forceinline__ void gemm_phase(PG8_LAS unsigned char* lds, const Gemm g, const Sched& S, const Epi& E, int tid_in) {
;     ...
;             PG8_LDA(At, 1, 1); PG8_STAGE(PG8_SB(1, 0), b3, voffB); PG8_STAGE(PG8_SB(1, 1), b3 + hstepB, voffB); PG8_STAGE(PG8_SA(1, 0), a3, voffA);
;             PG8_WAIT_V(8); PG8_WAIT_L(0); PG8_BAR; PG8_MMA(1, 0, At, B0); PG8_MMA(1, 1, At, B1); PG8_BAR; PG8_SCHED;
	s_add_i32 s26, s33, s54
	v_lshl_add_u64 v[204:205], v[204:205], 0, s[10:11]
	s_mov_b32 m0, s26
	ds_read_b128 v[188:191], v152 offset:49152
	ds_read_b128 v[192:195], v152 offset:50176
	ds_read_b128 v[196:199], v152 offset:51200
	ds_read_b128 v[200:203], v152 offset:52224
	ds_read_b128 v[212:215], v152 offset:53248
	ds_read_b128 v[216:219], v152 offset:54272
	ds_read_b128 v[220:223], v152 offset:55296
	ds_read_b128 v[224:227], v152 offset:56320
	global_load_lds_dwordx4 v[204:205], off
	s_add_i32 m0, s26, 0x2000
	s_add_u32 s26, s50, 0x20080
	v_lshl_add_u64 v[204:205], v[206:207], 0, s[10:11]
	s_addc_u32 s27, s51, 0
	s_add_i32 s33, s77, s54
	global_load_lds_dwordx4 v[204:205], off
	v_lshl_add_u64 v[204:205], s[26:27], 0, v[132:133]
	s_mov_b32 m0, s33
	s_nop 0
	global_load_lds_dwordx4 v[204:205], off
	v_lshl_add_u64 v[204:205], s[26:27], 0, v[128:129]
	s_add_i32 m0, s33, 0x2000
	s_nop 0
	global_load_lds_dwordx4 v[204:205], off
	v_lshl_add_u64 v[204:205], v[208:209], 0, s[10:11]
	s_mov_b32 m0, s61
	s_nop 0
	global_load_lds_dwordx4 v[204:205], off
	v_lshl_add_u64 v[204:205], v[228:229], 0, s[10:11]
	s_mov_b32 m0, s62
	s_nop 0
	global_load_lds_dwordx4 v[204:205], off
	s_waitcnt vmcnt(8)
	s_waitcnt lgkmcnt(0)
	s_barrier
	s_waitcnt lgkmcnt(0)
	v_mfma_f32_16x16x32_bf16 v[60:63], v[156:159], v[188:191], v[60:63]
	v_mfma_f32_16x16x32_bf16 v[56:59], v[164:167], v[188:191], v[56:59]
	v_mfma_f32_16x16x32_bf16 v[44:47], v[156:159], v[196:199], v[44:47]
	v_mfma_f32_16x16x32_bf16 v[40:43], v[164:167], v[196:199], v[40:43]
	v_mfma_f32_16x16x32_bf16 v[28:31], v[156:159], v[212:215], v[28:31]
	v_mfma_f32_16x16x32_bf16 v[24:27], v[164:167], v[212:215], v[24:27]
	v_mfma_f32_16x16x32_bf16 v[12:15], v[156:159], v[220:223], v[12:15]
	v_mfma_f32_16x16x32_bf16 v[8:11], v[164:167], v[220:223], v[8:11]
	v_mfma_f32_16x16x32_bf16 v[60:63], v[160:163], v[192:195], v[60:63]
	v_mfma_f32_16x16x32_bf16 v[56:59], v[168:171], v[192:195], v[56:59]
	v_mfma_f32_16x16x32_bf16 v[44:47], v[160:163], v[200:203], v[44:47]
	v_mfma_f32_16x16x32_bf16 v[40:43], v[168:171], v[200:203], v[40:43]
	v_mfma_f32_16x16x32_bf16 v[28:31], v[160:163], v[216:219], v[28:31]
	v_mfma_f32_16x16x32_bf16 v[24:27], v[168:171], v[216:219], v[24:27]
	v_mfma_f32_16x16x32_bf16 v[12:15], v[160:163], v[224:227], v[12:15]
	v_mfma_f32_16x16x32_bf16 v[8:11], v[168:171], v[224:227], v[8:11]
	v_mfma_f32_16x16x32_bf16 v[52:55], v[172:175], v[188:191], v[52:55]
	v_mfma_f32_16x16x32_bf16 v[48:51], v[180:183], v[188:191], v[48:51]
	v_mfma_f32_16x16x32_bf16 v[36:39], v[172:175], v[196:199], v[36:39]
	v_mfma_f32_16x16x32_bf16 v[32:35], v[180:183], v[196:199], v[32:35]
	v_mfma_f32_16x16x32_bf16 v[20:23], v[172:175], v[212:215], v[20:23]
	v_mfma_f32_16x16x32_bf16 v[16:19], v[180:183], v[212:215], v[16:19]
	v_mfma_f32_16x16x32_bf16 v[4:7], v[172:175], v[220:223], v[4:7]
	v_mfma_f32_16x16x32_bf16 v[0:3], v[180:183], v[220:223], v[0:3]
	v_mfma_f32_16x16x32_bf16 v[52:55], v[176:179], v[192:195], v[52:55]
	v_mfma_f32_16x16x32_bf16 v[48:51], v[184:187], v[192:195], v[48:51]
	v_mfma_f32_16x16x32_bf16 v[36:39], v[176:179], v[200:203], v[36:39]
	v_mfma_f32_16x16x32_bf16 v[32:35], v[184:187], v[200:203], v[32:35]
	v_mfma_f32_16x16x32_bf16 v[20:23], v[176:179], v[216:219], v[20:23]
	v_mfma_f32_16x16x32_bf16 v[16:19], v[184:187], v[216:219], v[16:19]
	v_mfma_f32_16x16x32_bf16 v[4:7], v[176:179], v[224:227], v[4:7]
	v_mfma_f32_16x16x32_bf16 v[0:3], v[184:187], v[224:227], v[0:3]
	s_barrier
	s_add_i32 s76, s76, 2
	s_add_u32 s48, s48, 0x100
	s_addc_u32 s49, s49, 0
	s_add_u32 s74, s74, 0x100
	s_addc_u32 s75, s75, 0
	s_cmp_gt_u32 s76, 29
	s_cbranch_scc0 .LBB0_80
	s_and_b64 vcc, exec, s[14:15]
	s_cbranch_vccz .LBB0_83
	s_barrier

; #define ALDS __attribute__((address_space(3)))
; __device__ __forceinline__ void na_phase(const bf16* qkv, bf16* out, const float* rpb, ldsp lds, int vcu, int G, int tid_in) {
;     int tid_ = tid_in; asm volatile("" : "+v"(tid_)); const int tid = tid_, lane = tid & 63, wave = __builtin_amdgcn_readfirstlane(tid >> 6), r32 = lane & 31, hh = lane >> 5;
;     ATT_BASES((unsigned)(unsigned long)lds); ALDS float* tb = (ALDS float*)(lds + 131072);
;     for (int i = tid; i < 16 * 465; i += 512) tb[i] = rpb[i] * LOG2E;
;     __syncthreads();
.LBB0_139:
	s_or_b64 exec, exec, s[6:7]
	s_waitcnt lgkmcnt(0)
	s_setprio 0
	v_mov_b32_e32 v0, v252
	s_barrier
	s_movk_i32 s6, 0x1d10
	v_add_u32_e32 v0, s81, v0
	s_nop 0
	v_readfirstlane_b32 s41, v0
	v_cmp_gt_i32_e32 vcc, s6, v0
	s_and_saveexec_b64 s[6:7], vcc
	s_cbranch_execz .LBB0_152
	s_load_dwordx2 s[8:9], s[0:1], 0x18
	v_max_i32_e32 v1, 0x1b10, v0
	v_sub_u32_e32 v1, v1, v0
	s_movk_i32 s10, 0x1ff
	v_add_u32_e32 v1, 0x1ff, v1
	v_cmp_lt_u32_e32 vcc, s10, v1
	s_mov_b64 s[14:15], -1
	v_mov_b32_e32 v2, v0
	s_and_saveexec_b64 s[10:11], vcc
	s_cbranch_execz .LBB0_149
	v_lshrrev_b32_e32 v4, 9, v1
	v_add_u32_e32 v2, -1, v4
	v_add_u32_e32 v1, 0x200, v0
	v_lshrrev_b32_e32 v3, 1, v2
	v_add_u32_e32 v5, 1, v3
	v_cmp_lt_u32_e32 vcc, 13, v2
	v_mov_b32_e32 v8, 0
	v_mov_b64_e32 v[2:3], v[0:1]
	s_and_saveexec_b64 s[14:15], vcc
	s_cbranch_execz .LBB0_145
	v_lshl_add_u32 v2, v0, 2, 0
	v_and_b32_e32 v6, -8, v5
	s_mov_b32 s42, 0
	v_add_u32_e32 v7, 0x20000, v2
	s_mov_b64 s[38:39], 0
	s_mov_b32 s40, 0x3fb8aa3b
	v_mov_b64_e32 v[2:3], v[0:1]

; #define LAS __attribute__((address_space(3)))
; __device__ __forceinline__ void tr_load(const float* W, int N, int nblk, int item, int lane, f32x4 (&wv)[8]) {
;     const int kb = item / nblk, nb = item % nblk, k0 = 64 * kb, n0 = 32 * nb;
; #pragma unroll
;     for (int i = 0; i < 8; ++i) wv[i] = *(const f32x4*)(W + (size_t)(k0 + 8 * i + (lane >> 3)) * N + n0 + 4 * (lane & 7));
; }
; __device__ __forceinline__ void convert_matrix(const float* W, int K, int N, bf16* WT, const float* gain, int qmode, float qs, LAS float* scr, int gw, int NGW, int lane) {
;     const int nblk = N / 32, nitems = (K / 64) * nblk;
;     int it = gw; if (it >= nitems) return;
;     f32x4 wv[8]; tr_load(W, N, nblk, it, lane, wv);
.LBB0_169:
	s_cmpk_gt_u32 s72, 0xff
	s_cbranch_scc0 .LBB0_221
	s_lshl_b32 s6, s83, 2
	s_setprio 0
	v_mov_b32_e32 v0, v252
	s_add_i32 s6, s73, s6
	s_add_i32 s41, s6, -4
	v_and_b32_e32 v38, 63, v0
	s_lshl_b32 s40, s24, 2
	s_cmpk_gt_i32 s41, 0x7ff
	v_lshrrev_b32_e32 v32, 3, v38
	v_lshlrev_b32_e32 v45, 4, v38
	v_lshlrev_b32_e32 v33, 3, v38
	s_cbranch_scc1 .LBB0_175
	s_ashr_i32 s8, s41, 31
	s_lshr_b32 s8, s8, 26
	s_add_i32 s8, s41, s8
	s_load_dwordx2 s[6:7], s[0:1], 0x20
	s_and_b32 s9, s8, 0xffffffc0
	s_sub_i32 s8, s41, s9
	s_lshl_b32 s8, s8, 5
	v_lshrrev_b32_e32 v39, 3, v38
	v_or_b32_e32 v24, s9, v39
	s_ashr_i32 s9, s8, 31
	s_lshl_b64 s[8:9], s[8:9], 2
	s_waitcnt lgkmcnt(0)
	s_add_u32 s8, s6, s8
	s_addc_u32 s9, s7, s9
	v_and_b32_e32 v36, 0x70, v45
	v_mov_b32_e32 v37, 0
	v_ashrrev_i32_e32 v25, 31, v24
	v_lshl_add_u64 v[26:27], s[8:9], 0, v[36:37]
	v_lshlrev_b64 v[0:1], 13, v[24:25]
	v_lshl_add_u64 v[8:9], v[26:27], 0, v[0:1]
	v_or_b32_e32 v0, 8, v24
	v_ashrrev_i32_e32 v1, 31, v0
	v_lshlrev_b64 v[0:1], 13, v[0:1]
	v_lshl_add_u64 v[10:11], v[26:27], 0, v[0:1]
	global_load_dwordx4 v[0:3], v[8:9], off
	global_load_dwordx4 v[4:7], v[10:11], off
	v_or_b32_e32 v8, 16, v24
	v_ashrrev_i32_e32 v9, 31, v8
	v_lshlrev_b64 v[8:9], 13, v[8:9]
	v_lshl_add_u64 v[16:17], v[26:27], 0, v[8:9]
	v_or_b32_e32 v8, 24, v24
	v_ashrrev_i32_e32 v9, 31, v8
	v_lshlrev_b64 v[8:9], 13, v[8:9]
	v_lshl_add_u64 v[18:19], v[26:27], 0, v[8:9]
	global_load_dwordx4 v[8:11], v[16:17], off
	global_load_dwordx4 v[12:15], v[18:19], off
	v_or_b32_e32 v16, 32, v24
	v_ashrrev_i32_e32 v17, 31, v16
	v_lshlrev_b64 v[16:17], 13, v[16:17]
	v_lshl_add_u64 v[28:29], v[26:27], 0, v[16:17]
	v_or_b32_e32 v16, 40, v24
	v_ashrrev_i32_e32 v17, 31, v16
	v_lshlrev_b64 v[16:17], 13, v[16:17]
	v_lshl_add_u64 v[30:31], v[26:27], 0, v[16:17]
	global_load_dwordx4 v[16:19], v[28:29], off
	global_load_dwordx4 v[20:23], v[30:31], off
	v_or_b32_e32 v28, 48, v24
	v_ashrrev_i32_e32 v29, 31, v28
	v_or_b32_e32 v24, 56, v24
	v_lshlrev_b64 v[28:29], 13, v[28:29]
	v_ashrrev_i32_e32 v25, 31, v24
	v_lshl_add_u64 v[34:35], v[26:27], 0, v[28:29]
	v_lshlrev_b64 v[24:25], 13, v[24:25]
	v_lshl_add_u64 v[40:41], v[26:27], 0, v[24:25]
	global_load_dwordx4 v[24:27], v[34:35], off
	global_load_dwordx4 v[28:31], v[40:41], off
	v_add_u32_e32 v41, s78, v36
	v_lshl_add_u64 v[34:35], s[6:7], 0, v[36:37]
	v_and_b32_e32 v36, 56, v33
	v_mul_u32_u24_e32 v40, 0x84, v36
	v_lshlrev_b32_e32 v36, 1, v36
	v_mul_u32_u24_e32 v42, 0x84, v39
	v_lshl_add_u64 v[36:37], s[18:19], 0, v[36:37]
	s_mov_b64 s[6:7], 0x1c00000
	v_lshlrev_b32_e32 v43, 2, v39
	s_lshl_b32 s9, s40, 5
	v_lshl_add_u64 v[36:37], v[36:37], 0, s[6:7]
	v_add3_u32 v40, s78, v40, v43
	s_lshl_b32 s8, s41, 5
	v_add_u32_e32 v41, v41, v42
	s_mov_b32 s10, s9
	v_mov_b32_e32 v42, v39
	s_mov_b32 s14, s41
	s_branch .LBB0_173

;     __host__ __device__ bool next(int i, Unit& u) const {
;         const long L = (long)i * G + c; if (L >= nwg) return false;
;         int wgid = (int)L; { const int q = nwg / NXCD, r = nwg % NXCD, xcd = wgid % NXCD, off = wgid / NXCD; wgid = (xcd < r ? xcd * (q + 1) : r * (q + 1) + (xcd - r) * q) + off; }
;         const int nig = wgm * nN, gid = wgid / nig, fm = gid * wgm, gsz = (nM - fm) < wgm ? (nM - fm) : wgm;
;         u.pm = fm + ((wgid % nig) % gsz); u.pn = (wgid % nig) / gsz; return true;
.LBB0_273:
	s_or_b64 exec, exec, s[6:7]
	s_waitcnt vmcnt(11) lgkmcnt(0)
	s_setprio 0
	v_mov_b32_e32 v0, v252
	s_barrier
	s_cmpk_lt_i32 s2, 0x400
	s_waitcnt vmcnt(9)
	v_add_u32_e32 v8, s81, v0
	s_cselect_b64 s[8:9], -1, 0
	s_cmpk_gt_i32 s2, 0x3ff
	v_readfirstlane_b32 s10, v8
	s_cbranch_scc1 .LBB0_279
	s_lshr_b32 s6, s3, 29
	s_add_i32 s11, s2, s6
	s_and_b32 s6, s11, -8
	s_sub_i32 s14, s2, s6
	s_cmp_gt_i32 s14, -1
	s_cbranch_scc0 .LBB0_276
	s_lshl_b32 s15, s14, 7
	s_cbranch_execz .LBB0_277
	s_branch .LBB0_278

; #define PG8_STAGE(bufoff, gbase, voff) do { _Pragma("unroll") for (int _i = 0; _i < 2; ++_i) \
;         __builtin_amdgcn_global_load_lds((const unsigned*)((const char*)(gbase) + (voff)[_i]), (PG8_LAS unsigned*)(lds + (bufoff) + ldsw + _i * 8192), 16, 0, 0); } while (0)
; #define PG8_WAIT_V(n) asm volatile("s_waitcnt vmcnt(" #n ")" ::: "memory")
; #define PG8_BAR __builtin_amdgcn_s_barrier()
; template <class Epi, class Sched, bool ALIGN_EPI = false, bool SP2 = false>
; __device__ __forceinline__ void gemm_phase(PG8_LAS unsigned char* lds, const Gemm g, const Sched& S, const Epi& E, int tid_in) {
;     int tid_ = tid_in; asm volatile("" : "+v"(tid_)); const int tid = tid_, wid = __builtin_amdgcn_readfirstlane(tid >> 6), lane = tid & 63, wr = wid >> 2, wc = wid & 3, fr = lane & 15, fq = lane >> 4;
;     const int K = g.K, nt = K / BK;
;     unsigned voffA[2], voffB[2];
; #pragma unroll
;     for (int i = 0; i < 2; ++i) { int R, C; stage_rc(tid * 16 + i * 8192, R, C); const int Rb = 2 * (R & ~31) + (Epi::PERM ? perm32(R & 31) : (R & 31));
;         voffA[i] = (unsigned)(R * g.lda + C) * 2u; voffB[i] = (unsigned)(Rb * K + C) * 2u; }
;     const size_t kstep = (size_t)(BK * 2);
;     const size_t hstep = (size_t)HALF * g.lda * 2;
;     const size_t hstepB = (size_t)32 * K * 2;
;     const size_t tstep = 2 * hstep, tstepB = (size_t)BM * K * 2;
;     const unsigned ldsw = (unsigned)wid * 1024u;
;     const int aoff = lds_byte(wr * 64 + fr, fq * 8), boff = lds_byte(wc * 32 + fr, fq * 8);
;     ...
;     Unit cur, nxt; int ui = 0;
;     if (!S.next(0, cur)) return;
;     f32x4 acc[2][2][4][2];
; #pragma unroll
;     for (int a = 0; a < 2; ++a)
; #pragma unroll
;         for (int b = 0; b < 2; ++b)
; #pragma unroll
;             for (int m = 0; m < 4; ++m)
; #pragma unroll
;                 for (int n = 0; n < 2; ++n) acc[a][b][m][n] = (f32x4){0.f, 0.f, 0.f, 0.f};
;     bf16x8 At[4][2], B0[2][2], B1[2][2];
;     const char* cA = (const char*)g.A + (size_t)cur.pm * tstep; const char* cB = (const char*)g.Bt + (size_t)cur.pn * tstepB;
;     S.a_ready(cur);
;     if constexpr (SP2) {
;         PG8_STAGE(PG8_SB(0, 0), cB, voffB); PG8_STAGE(PG8_SB(0, 1), cB + hstepB, voffB); PG8_STAGE(PG8_SA(0, 0), cA, voffA); PG8_STAGE(PG8_SA(0, 1), cA + hstep, voffA);
;         if (wr == 1) PG8_BAR;
;         PG8_WAIT_V(2); PG8_BAR;
.LBB0_279:
	s_add_u32 s14, s18, 0x40000
	s_addc_u32 s15, s19, 0
	s_add_u32 s38, s18, 0x10800000
	v_cndmask_b32_e64 v0, 0, 1, s[8:9]
	s_addc_u32 s39, s19, 0
	v_cmp_ne_u32_e64 s[6:7], 1, v0
	s_andn2_b64 vcc, exec, s[8:9]
	s_cbranch_vccnz .LBB0_315
	v_ashrrev_i32_e32 v1, 31, v8
	v_lshrrev_b32_e32 v1, 26, v1
	v_add_u32_e32 v1, v8, v1
	v_ashrrev_i32_e32 v9, 6, v1
	v_bfe_i32 v1, v8, 27, 1
	v_lshlrev_b32_e32 v0, 4, v8
	v_lshrrev_b32_e32 v1, 22, v1
	v_add_u32_e32 v1, v0, v1
	v_and_b32_e32 v1, 0xfffffc00, v1
	v_sub_u32_e32 v1, v0, v1
	v_lshrrev_b32_e32 v2, 4, v1
	v_bitop3_b32 v1, v2, v1, 32 bitop3:0x6c
	v_ashrrev_i32_e32 v3, 31, v1
	v_lshrrev_b32_e32 v3, 26, v3
	v_add_u32_e32 v3, v1, v3
	v_lshlrev_b32_e32 v2, 3, v9
	v_ashrrev_i32_e32 v10, 6, v3
	v_and_b32_e32 v3, 0xc0, v3
	v_and_b32_e32 v2, -16, v2
	v_sub_u32_e32 v1, v1, v3
	v_mov_b32_e32 v3, 1
	v_add_u32_e32 v2, v10, v2
	v_lshlrev_b32_e32 v4, 5, v9
	v_ashrrev_i16_sdwa v1, v3, sext(v1) dst_sel:DWORD dst_unused:UNUSED_PAD src0_sel:DWORD src1_sel:BYTE_0
	v_and_b32_e32 v4, 32, v4
	v_bfe_i32 v11, v1, 0, 16
	v_lshlrev_b32_e32 v1, 1, v2
	v_and_b32_e32 v5, 31, v2
	s_mov_b32 s9, 0xfffc0
	v_and_or_b32 v1, v1, s9, v5
	v_add_lshl_u32 v4, v4, v11, 1
	v_add_u32_e32 v0, 0x2000, v0
	v_lshl_add_u32 v130, v1, 12, v4
	v_ashrrev_i32_e32 v1, 31, v0
	v_lshrrev_b32_e32 v1, 22, v1
	v_add_u32_e32 v1, v0, v1
	s_waitcnt vmcnt(8)
	v_ashrrev_i32_e32 v12, 10, v1
	v_mul_i32_i24_e32 v1, 0x400, v12
	v_sub_u32_e32 v0, v0, v1
	v_lshrrev_b32_e32 v1, 4, v0
	v_bitop3_b32 v0, v1, v0, 32 bitop3:0x6c
	v_lshl_add_u32 v128, v2, 12, v4
	v_ashrrev_i32_e32 v2, 31, v0
	v_lshrrev_b32_e32 v2, 26, v2
	v_add_u32_e32 v2, v0, v2
	v_lshlrev_b32_e32 v1, 3, v12
	v_ashrrev_i32_e32 v13, 6, v2
	v_and_b32_e32 v2, 0xc0, v2
	v_and_b32_e32 v1, -16, v1
	v_sub_u32_e32 v0, v0, v2
	s_add_u32 s64, s18, 0x1c00000
	v_add_u32_e32 v1, v13, v1
	v_ashrrev_i16_sdwa v0, v3, sext(v0) dst_sel:DWORD dst_unused:UNUSED_PAD src0_sel:DWORD src1_sel:BYTE_0
	s_addc_u32 s65, s19, 0
	s_ashr_i32 s8, s10, 6
	v_bfe_i32 v14, v0, 0, 16
	v_lshlrev_b32_e32 v0, 1, v1
	v_and_b32_e32 v2, 31, v1
	s_ashr_i32 s55, s54, 31
	s_ashr_i32 s57, s56, 31
	v_and_or_b32 v0, v0, s9, v2
	s_ashr_i32 s9, s10, 8
	s_lshl_b32 s66, s8, 10
	s_lshl_b64 s[26:27], s[54:55], 20
	s_lshl_b64 s[40:41], s[56:57], 20
	s_add_u32 s60, s64, s40
	v_lshlrev_b32_e32 v4, 5, v12
	s_addc_u32 s61, s65, s41
	s_add_i32 s57, s66, 0
	v_and_b32_e32 v4, 32, v4
	s_add_i32 m0, s57, 0x10000
	v_add_lshl_u32 v2, v4, v14, 1
	global_load_lds_dwordx4 v130, s[60:61]
	s_add_i32 m0, s57, 0x12000
	v_lshl_add_u32 v134, v0, 12, v2
	s_add_u32 s40, s60, 0x20000
	global_load_lds_dwordx4 v134, s[60:61]
	s_addc_u32 s41, s61, 0
	s_add_i32 m0, s57, 0x14000
	v_lshl_add_u32 v132, v1, 12, v2
	global_load_lds_dwordx4 v130, s[40:41]
	s_add_i32 m0, s57, 0x16000
	s_add_u32 s58, s28, s26
	s_addc_u32 s59, s29, s27
	s_add_i32 s67, s57, 0x2000
	global_load_lds_dwordx4 v134, s[40:41]
	s_mov_b32 m0, s57
	s_add_u32 s26, s58, 0x80000
	global_load_lds_dwordx4 v128, s[58:59]
	s_mov_b32 m0, s67
	s_addc_u32 s27, s59, 0
	s_add_i32 s68, s57, 0x4000
	global_load_lds_dwordx4 v132, s[58:59]
	s_mov_b32 m0, s68
	s_add_i32 s69, s57, 0x6000
	global_load_lds_dwordx4 v128, s[26:27]
	s_mov_b32 m0, s69
	v_mov_b32_e32 v131, 0
	global_load_lds_dwordx4 v132, s[26:27]
	v_mov_b32_e32 v135, v131
	v_mov_b32_e32 v129, v131
	v_mov_b32_e32 v133, v131
	s_cmp_eq_u32 s9, 1
	s_mov_b32 s70, 0
	v_lshl_add_u64 v[6:7], s[60:61], 0, v[130:131]
	v_lshl_add_u64 v[4:5], s[60:61], 0, v[134:135]
	v_lshl_add_u64 v[0:1], s[58:59], 0, v[128:129]
	s_cselect_b64 s[40:41], -1, 0
	s_cmp_lg_u32 s9, 1
	v_lshl_add_u64 v[2:3], s[58:59], 0, v[132:133]
	s_cbranch_scc1 .LBB0_282
	s_barrier
	s_setprio 1

; #define PG8_STAGE(bufoff, gbase, voff) do { _Pragma("unroll") for (int _i = 0; _i < 2; ++_i) \
;         __builtin_amdgcn_global_load_lds((const unsigned*)((const char*)(gbase) + (voff)[_i]), (PG8_LAS unsigned*)(lds + (bufoff) + ldsw + _i * 8192), 16, 0, 0); } while (0)
; #define PG8_LDA(dst, b, h) do { _Pragma("unroll") for (int m = 0; m < 4; ++m) _Pragma("unroll") for (int k = 0; k < 2; ++k) dst[m][k] = *(const PG8_LAS bf16x8*)(lds + PG8_SA(b, h) + aoff + m * 2048 + k * 1024); } while (0)
; #define PG8_LDB(dst, b, h) do { _Pragma("unroll") for (int n = 0; n < 2; ++n) _Pragma("unroll") for (int k = 0; k < 2; ++k) dst[n][k] = *(const PG8_LAS bf16x8*)(lds + PG8_SB(b, h) + boff + n * 2048 + k * 1024); } while (0)
; #define PG8_MMA(ai, bj, At, Bt) do { __builtin_amdgcn_s_setprio(1); _Pragma("unroll") for (int m = 0; m < 4; ++m) _Pragma("unroll") for (int n = 0; n < 2; ++n) _Pragma("unroll") for (int k = 0; k < 2; ++k) \
;         acc[ai][bj][m][n] = __builtin_amdgcn_mfma_f32_16x16x32_bf16(Bt[n][k], At[m][k], acc[ai][bj][m][n], 0, 0, 0); __builtin_amdgcn_s_setprio(0); } while (0)
; #define PG8_WAIT_V(n) asm volatile("s_waitcnt vmcnt(" #n ")" ::: "memory")
; #define PG8_WAIT_L(n) asm volatile("s_waitcnt lgkmcnt(" #n ")" ::: "memory")
; #define PG8_BAR __builtin_amdgcn_s_barrier()
; #define PG8_SCHED __builtin_amdgcn_sched_barrier(0)
; template <class Epi, class Sched, bool ALIGN_EPI = false, bool SP2 = false>
; __device__ __forceinline__ void gemm_phase(PG8_LAS unsigned char* lds, const Gemm g, const Sched& S, const Epi& E, int tid_in) {
;     ...
;             PG8_LDB(B0, 0, 0); PG8_LDB(B1, 0, 1); PG8_SCHED; PG8_LDA(At, 0, 0); PG8_STAGE(PG8_SA(1, 1), a1 + hstep, voffA);
;             PG8_WAIT_V(8); PG8_WAIT_L(0); PG8_BAR; PG8_MMA(0, 0, At, B0); PG8_MMA(0, 1, At, B1); PG8_BAR; PG8_SCHED;
;             PG8_LDA(At, 0, 1); PG8_STAGE(PG8_SB(0, 0), b2, voffB); PG8_STAGE(PG8_SB(0, 1), b2 + hstepB, voffB); PG8_STAGE(PG8_SA(0, 0), a2, voffA);
;             PG8_WAIT_V(8); PG8_WAIT_L(0); PG8_BAR; PG8_MMA(1, 0, At, B0); PG8_MMA(1, 1, At, B1); PG8_BAR; PG8_SCHED;
.Lkb_skip_1:
.LBB0_292:
	ds_read_b128 v[146:149], v153
	ds_read_b128 v[158:161], v153 offset:1024
	ds_read_b128 v[162:165], v153 offset:2048
	ds_read_b128 v[166:169], v153 offset:3072
	ds_read_b128 v[170:173], v154
	ds_read_b128 v[174:177], v154 offset:1024
	ds_read_b128 v[178:181], v154 offset:2048
	ds_read_b128 v[182:185], v154 offset:3072
	s_add_u32 s26, s58, 0xfff80080
	s_addc_u32 s27, s59, -1
	s_cmp_eq_u32 s79, 28
	s_cselect_b32 s63, s49, s27
	s_cselect_b32 s62, s55, s26
	s_cselect_b32 s61, s47, s77
	s_cselect_b32 s60, s75, s76
	v_lshl_add_u64 v[220:221], s[58:59], 0, v[138:139]
	s_add_i32 m0, s57, 0xc000
	ds_read_b128 v[186:189], v155
	ds_read_b128 v[190:193], v155 offset:1024
	ds_read_b128 v[194:197], v155 offset:2048
	ds_read_b128 v[198:201], v155 offset:3072
	ds_read_b128 v[202:205], v155 offset:4096
	ds_read_b128 v[206:209], v155 offset:5120
	ds_read_b128 v[212:215], v155 offset:6144
	ds_read_b128 v[216:219], v155 offset:7168
	global_load_lds_dwordx4 v[220:221], off
	v_lshl_add_u64 v[220:221], s[58:59], 0, v[140:141]
	s_add_i32 m0, s57, 0xe000
	s_nop 0
	global_load_lds_dwordx4 v[220:221], off
	s_waitcnt vmcnt(8)
	s_waitcnt lgkmcnt(0)
	s_barrier
	s_waitcnt lgkmcnt(0)
	v_mfma_f32_16x16x32_bf16 v[124:127], v[146:149], v[186:189], v[124:127]
	v_mfma_f32_16x16x32_bf16 v[120:123], v[162:165], v[186:189], v[120:123]
	v_mfma_f32_16x16x32_bf16 v[108:111], v[146:149], v[194:197], v[108:111]
	v_mfma_f32_16x16x32_bf16 v[104:107], v[162:165], v[194:197], v[104:107]
	v_mfma_f32_16x16x32_bf16 v[92:95], v[146:149], v[202:205], v[92:95]
	v_mfma_f32_16x16x32_bf16 v[88:91], v[162:165], v[202:205], v[88:91]
	v_mfma_f32_16x16x32_bf16 v[76:79], v[146:149], v[212:215], v[76:79]
	v_mfma_f32_16x16x32_bf16 v[72:75], v[162:165], v[212:215], v[72:75]
	v_mfma_f32_16x16x32_bf16 v[124:127], v[158:161], v[190:193], v[124:127]
	v_mfma_f32_16x16x32_bf16 v[120:123], v[166:169], v[190:193], v[120:123]
	v_mfma_f32_16x16x32_bf16 v[108:111], v[158:161], v[198:201], v[108:111]
	v_mfma_f32_16x16x32_bf16 v[104:107], v[166:169], v[198:201], v[104:107]
	v_mfma_f32_16x16x32_bf16 v[92:95], v[158:161], v[206:209], v[92:95]
	v_mfma_f32_16x16x32_bf16 v[88:91], v[166:169], v[206:209], v[88:91]
	v_mfma_f32_16x16x32_bf16 v[76:79], v[158:161], v[216:219], v[76:79]
	v_mfma_f32_16x16x32_bf16 v[72:75], v[166:169], v[216:219], v[72:75]
	v_mfma_f32_16x16x32_bf16 v[116:119], v[170:173], v[186:189], v[116:119]
	v_mfma_f32_16x16x32_bf16 v[112:115], v[178:181], v[186:189], v[112:115]
	v_mfma_f32_16x16x32_bf16 v[100:103], v[170:173], v[194:197], v[100:103]
	v_mfma_f32_16x16x32_bf16 v[96:99], v[178:181], v[194:197], v[96:99]
	v_mfma_f32_16x16x32_bf16 v[84:87], v[170:173], v[202:205], v[84:87]
	v_mfma_f32_16x16x32_bf16 v[80:83], v[178:181], v[202:205], v[80:83]
	v_mfma_f32_16x16x32_bf16 v[68:71], v[170:173], v[212:215], v[68:71]
	v_mfma_f32_16x16x32_bf16 v[64:67], v[178:181], v[212:215], v[64:67]
	v_mfma_f32_16x16x32_bf16 v[116:119], v[174:177], v[190:193], v[116:119]
	v_mfma_f32_16x16x32_bf16 v[112:115], v[182:185], v[190:193], v[112:115]
	v_mfma_f32_16x16x32_bf16 v[100:103], v[174:177], v[198:201], v[100:103]
	v_mfma_f32_16x16x32_bf16 v[96:99], v[182:185], v[198:201], v[96:99]
	v_mfma_f32_16x16x32_bf16 v[84:87], v[174:177], v[206:209], v[84:87]
	v_mfma_f32_16x16x32_bf16 v[80:83], v[182:185], v[206:209], v[80:83]
	v_mfma_f32_16x16x32_bf16 v[68:71], v[174:177], v[216:219], v[68:71]
	v_mfma_f32_16x16x32_bf16 v[64:67], v[182:185], v[216:219], v[64:67]
	s_barrier
	s_add_i32 s26, s73, s66
	v_lshl_add_u64 v[220:221], s[60:61], 0, v[130:131]
	s_mov_b32 m0, s26
	ds_read_b128 v[186:189], v155 offset:16384
	ds_read_b128 v[190:193], v155 offset:17408
	ds_read_b128 v[194:197], v155 offset:18432
	ds_read_b128 v[198:201], v155 offset:19456
	ds_read_b128 v[202:205], v155 offset:20480
	ds_read_b128 v[206:209], v155 offset:21504
	ds_read_b128 v[212:215], v155 offset:22528
	ds_read_b128 v[216:219], v155 offset:23552
	global_load_lds_dwordx4 v[220:221], off
	s_add_i32 m0, s26, 0x2000
	s_add_u32 s26, s60, 0x20000
	v_lshl_add_u64 v[222:223], s[60:61], 0, v[134:135]
	s_addc_u32 s27, s61, 0
	s_add_i32 s33, s74, s66
	global_load_lds_dwordx4 v[222:223], off
	v_lshl_add_u64 v[224:225], s[26:27], 0, v[130:131]
	s_mov_b32 m0, s33
	v_lshl_add_u64 v[226:227], s[62:63], 0, v[132:133]
	global_load_lds_dwordx4 v[224:225], off
	v_lshl_add_u64 v[224:225], s[26:27], 0, v[134:135]
	s_add_i32 m0, s33, 0x2000
	s_nop 0
	global_load_lds_dwordx4 v[224:225], off
	v_lshl_add_u64 v[224:225], s[62:63], 0, v[128:129]
	s_mov_b32 m0, s57
	s_nop 0
	global_load_lds_dwordx4 v[224:225], off
	s_mov_b32 m0, s67
	s_nop 0
	global_load_lds_dwordx4 v[226:227], off
	s_waitcnt vmcnt(8)
	s_waitcnt lgkmcnt(0)
	s_barrier
; #define PG8_STAGE(bufoff, gbase, voff) do { _Pragma("unroll") for (int _i = 0; _i < 2; ++_i) \
;         __builtin_amdgcn_global_load_lds((const unsigned*)((const char*)(gbase) + (voff)[_i]), (PG8_LAS unsigned*)(lds + (bufoff) + ldsw + _i * 8192), 16, 0, 0); } while (0)
; #define PG8_LDA(dst, b, h) do { _Pragma("unroll") for (int m = 0; m < 4; ++m) _Pragma("unroll") for (int k = 0; k < 2; ++k) dst[m][k] = *(const PG8_LAS bf16x8*)(lds + PG8_SA(b, h) + aoff + m * 2048 + k * 1024); } while (0)
; #define PG8_LDB(dst, b, h) do { _Pragma("unroll") for (int n = 0; n < 2; ++n) _Pragma("unroll") for (int k = 0; k < 2; ++k) dst[n][k] = *(const PG8_LAS bf16x8*)(lds + PG8_SB(b, h) + boff + n * 2048 + k * 1024); } while (0)
; #define PG8_MMA(ai, bj, At, Bt) do { __builtin_amdgcn_s_setprio(1); _Pragma("unroll") for (int m = 0; m < 4; ++m) _Pragma("unroll") for (int n = 0; n < 2; ++n) _Pragma("unroll") for (int k = 0; k < 2; ++k) \
;         acc[ai][bj][m][n] = __builtin_amdgcn_mfma_f32_16x16x32_bf16(Bt[n][k], At[m][k], acc[ai][bj][m][n], 0, 0, 0); __builtin_amdgcn_s_setprio(0); } while (0)
; #define PG8_WAIT_V(n) asm volatile("s_waitcnt vmcnt(" #n ")" ::: "memory")
; #define PG8_WAIT_L(n) asm volatile("s_waitcnt lgkmcnt(" #n ")" ::: "memory")
; #define PG8_BAR __builtin_amdgcn_s_barrier()
; #define PG8_SCHED __builtin_amdgcn_sched_barrier(0)
; template <class Epi, class Sched, bool ALIGN_EPI = false, bool SP2 = false>
; __device__ __forceinline__ void gemm_phase(PG8_LAS unsigned char* lds, const Gemm g, const Sched& S, const Epi& E, int tid_in) {
;     ...
;             PG8_WAIT_V(8); PG8_WAIT_L(0); PG8_BAR; PG8_MMA(1, 0, At, B0); PG8_MMA(1, 1, At, B1); PG8_BAR; PG8_SCHED;
;             PG8_LDB(B0, 1, 0); PG8_LDB(B1, 1, 1); PG8_SCHED; PG8_LDA(At, 1, 0); PG8_STAGE(PG8_SA(0, 1), a2 + hstep, voffA);
;             PG8_WAIT_V(8); PG8_WAIT_L(0); PG8_BAR; PG8_MMA(0, 0, At, B0); PG8_MMA(0, 1, At, B1); PG8_BAR; PG8_SCHED;
	s_waitcnt lgkmcnt(0)
	v_mfma_f32_16x16x32_bf16 v[60:63], v[146:149], v[186:189], v[60:63]
	v_mfma_f32_16x16x32_bf16 v[56:59], v[162:165], v[186:189], v[56:59]
	v_mfma_f32_16x16x32_bf16 v[44:47], v[146:149], v[194:197], v[44:47]
	v_mfma_f32_16x16x32_bf16 v[40:43], v[162:165], v[194:197], v[40:43]
	v_mfma_f32_16x16x32_bf16 v[28:31], v[146:149], v[202:205], v[28:31]
	v_mfma_f32_16x16x32_bf16 v[24:27], v[162:165], v[202:205], v[24:27]
	v_mfma_f32_16x16x32_bf16 v[12:15], v[146:149], v[212:215], v[12:15]
	v_mfma_f32_16x16x32_bf16 v[8:11], v[162:165], v[212:215], v[8:11]
	v_mfma_f32_16x16x32_bf16 v[60:63], v[158:161], v[190:193], v[60:63]
	v_mfma_f32_16x16x32_bf16 v[56:59], v[166:169], v[190:193], v[56:59]
	v_mfma_f32_16x16x32_bf16 v[44:47], v[158:161], v[198:201], v[44:47]
	v_mfma_f32_16x16x32_bf16 v[40:43], v[166:169], v[198:201], v[40:43]
	v_mfma_f32_16x16x32_bf16 v[28:31], v[158:161], v[206:209], v[28:31]
	v_mfma_f32_16x16x32_bf16 v[24:27], v[166:169], v[206:209], v[24:27]
	v_mfma_f32_16x16x32_bf16 v[12:15], v[158:161], v[216:219], v[12:15]
	v_mfma_f32_16x16x32_bf16 v[8:11], v[166:169], v[216:219], v[8:11]
	v_mfma_f32_16x16x32_bf16 v[52:55], v[170:173], v[186:189], v[52:55]
	v_mfma_f32_16x16x32_bf16 v[48:51], v[178:181], v[186:189], v[48:51]
	v_mfma_f32_16x16x32_bf16 v[36:39], v[170:173], v[194:197], v[36:39]
	v_mfma_f32_16x16x32_bf16 v[32:35], v[178:181], v[194:197], v[32:35]
	v_mfma_f32_16x16x32_bf16 v[20:23], v[170:173], v[202:205], v[20:23]
	v_mfma_f32_16x16x32_bf16 v[16:19], v[178:181], v[202:205], v[16:19]
	v_mfma_f32_16x16x32_bf16 v[4:7], v[170:173], v[212:215], v[4:7]
	v_mfma_f32_16x16x32_bf16 v[0:3], v[178:181], v[212:215], v[0:3]
	v_mfma_f32_16x16x32_bf16 v[52:55], v[174:177], v[190:193], v[52:55]
	v_mfma_f32_16x16x32_bf16 v[48:51], v[182:185], v[190:193], v[48:51]
	v_mfma_f32_16x16x32_bf16 v[36:39], v[174:177], v[198:201], v[36:39]
	v_mfma_f32_16x16x32_bf16 v[32:35], v[182:185], v[198:201], v[32:35]
	v_mfma_f32_16x16x32_bf16 v[20:23], v[174:177], v[206:209], v[20:23]
	v_mfma_f32_16x16x32_bf16 v[16:19], v[182:185], v[206:209], v[16:19]
	v_mfma_f32_16x16x32_bf16 v[4:7], v[174:177], v[216:219], v[4:7]
	v_mfma_f32_16x16x32_bf16 v[0:3], v[182:185], v[216:219], v[0:3]
	s_barrier
	s_add_i32 s33, 0, 0x18000
	s_add_i32 s84, 0, 0x1c000
	v_add_u32_e32 v166, s33, v137
	v_add_u32_e32 v182, s84, v137
	ds_read_b128 v[146:149], v166
	ds_read_b128 v[158:161], v166 offset:1024
	ds_read_b128 v[162:165], v166 offset:2048
	ds_read_b128 v[166:169], v166 offset:3072
	ds_read_b128 v[170:173], v182
	ds_read_b128 v[174:177], v182 offset:1024
	ds_read_b128 v[178:181], v182 offset:2048
	ds_read_b128 v[182:185], v182 offset:3072
	s_add_u32 s26, s62, 0x80000
	s_addc_u32 s27, s63, 0
	s_mov_b32 m0, s68
	v_lshl_add_u64 v[228:229], s[26:27], 0, v[128:129]
	ds_read_b128 v[186:189], v155 offset:32768
	ds_read_b128 v[190:193], v155 offset:33792
	ds_read_b128 v[194:197], v155 offset:34816
	ds_read_b128 v[198:201], v155 offset:35840
	ds_read_b128 v[202:205], v155 offset:36864
	ds_read_b128 v[206:209], v155 offset:37888
	ds_read_b128 v[212:215], v155 offset:38912
	ds_read_b128 v[216:219], v155 offset:39936
	global_load_lds_dwordx4 v[228:229], off
	v_lshl_add_u64 v[228:229], s[26:27], 0, v[132:133]
	s_mov_b32 m0, s69
	s_nop 0
	global_load_lds_dwordx4 v[228:229], off
	s_waitcnt vmcnt(8)
	s_waitcnt lgkmcnt(0)
	s_barrier
	s_waitcnt lgkmcnt(0)
	v_mfma_f32_16x16x32_bf16 v[124:127], v[146:149], v[186:189], v[124:127]
	v_mfma_f32_16x16x32_bf16 v[120:123], v[162:165], v[186:189], v[120:123]
	v_mfma_f32_16x16x32_bf16 v[108:111], v[146:149], v[194:197], v[108:111]
	v_mfma_f32_16x16x32_bf16 v[104:107], v[162:165], v[194:197], v[104:107]
	v_mfma_f32_16x16x32_bf16 v[92:95], v[146:149], v[202:205], v[92:95]
	v_mfma_f32_16x16x32_bf16 v[88:91], v[162:165], v[202:205], v[88:91]
	v_mfma_f32_16x16x32_bf16 v[76:79], v[146:149], v[212:215], v[76:79]
	v_mfma_f32_16x16x32_bf16 v[72:75], v[162:165], v[212:215], v[72:75]
	v_mfma_f32_16x16x32_bf16 v[124:127], v[158:161], v[190:193], v[124:127]
	v_mfma_f32_16x16x32_bf16 v[120:123], v[166:169], v[190:193], v[120:123]
	v_mfma_f32_16x16x32_bf16 v[108:111], v[158:161], v[198:201], v[108:111]
	v_mfma_f32_16x16x32_bf16 v[104:107], v[166:169], v[198:201], v[104:107]
	v_mfma_f32_16x16x32_bf16 v[92:95], v[158:161], v[206:209], v[92:95]
	v_mfma_f32_16x16x32_bf16 v[88:91], v[166:169], v[206:209], v[88:91]
	v_mfma_f32_16x16x32_bf16 v[76:79], v[158:161], v[216:219], v[76:79]
	v_mfma_f32_16x16x32_bf16 v[72:75], v[166:169], v[216:219], v[72:75]
	v_mfma_f32_16x16x32_bf16 v[116:119], v[170:173], v[186:189], v[116:119]
	v_mfma_f32_16x16x32_bf16 v[112:115], v[178:181], v[186:189], v[112:115]
	v_mfma_f32_16x16x32_bf16 v[100:103], v[170:173], v[194:197], v[100:103]
	v_mfma_f32_16x16x32_bf16 v[96:99], v[178:181], v[194:197], v[96:99]
	v_mfma_f32_16x16x32_bf16 v[84:87], v[170:173], v[202:205], v[84:87]
	v_mfma_f32_16x16x32_bf16 v[80:83], v[178:181], v[202:205], v[80:83]
	v_mfma_f32_16x16x32_bf16 v[68:71], v[170:173], v[212:215], v[68:71]
	v_mfma_f32_16x16x32_bf16 v[64:67], v[178:181], v[212:215], v[64:67]
	v_mfma_f32_16x16x32_bf16 v[116:119], v[174:177], v[190:193], v[116:119]
	v_mfma_f32_16x16x32_bf16 v[112:115], v[182:185], v[190:193], v[112:115]
	v_mfma_f32_16x16x32_bf16 v[100:103], v[174:177], v[198:201], v[100:103]
	v_mfma_f32_16x16x32_bf16 v[96:99], v[182:185], v[198:201], v[96:99]
	v_mfma_f32_16x16x32_bf16 v[84:87], v[174:177], v[206:209], v[84:87]
	v_mfma_f32_16x16x32_bf16 v[80:83], v[182:185], v[206:209], v[80:83]
	v_mfma_f32_16x16x32_bf16 v[68:71], v[174:177], v[216:219], v[68:71]
	v_mfma_f32_16x16x32_bf16 v[64:67], v[182:185], v[216:219], v[64:67]
	s_barrier
; #define PG8_STAGE(bufoff, gbase, voff) do { _Pragma("unroll") for (int _i = 0; _i < 2; ++_i) \
;         __builtin_amdgcn_global_load_lds((const unsigned*)((const char*)(gbase) + (voff)[_i]), (PG8_LAS unsigned*)(lds + (bufoff) + ldsw + _i * 8192), 16, 0, 0); } while (0)
; #define PG8_LDA(dst, b, h) do { _Pragma("unroll") for (int m = 0; m < 4; ++m) _Pragma("unroll") for (int k = 0; k < 2; ++k) dst[m][k] = *(const PG8_LAS bf16x8*)(lds + PG8_SA(b, h) + aoff + m * 2048 + k * 1024); } while (0)
; #define PG8_MMA(ai, bj, At, Bt) do { __builtin_amdgcn_s_setprio(1); _Pragma("unroll") for (int m = 0; m < 4; ++m) _Pragma("unroll") for (int n = 0; n < 2; ++n) _Pragma("unroll") for (int k = 0; k < 2; ++k) \
;         acc[ai][bj][m][n] = __builtin_amdgcn_mfma_f32_16x16x32_bf16(Bt[n][k], At[m][k], acc[ai][bj][m][n], 0, 0, 0); __builtin_amdgcn_s_setprio(0); } while (0)
; #define PG8_WAIT_V(n) asm volatile("s_waitcnt vmcnt(" #n ")" ::: "memory")
; #define PG8_WAIT_L(n) asm volatile("s_waitcnt lgkmcnt(" #n ")" ::: "memory")
; #define PG8_BAR __builtin_amdgcn_s_barrier()
; #define PG8_SCHED __builtin_amdgcn_sched_barrier(0)
; template <class Epi, class Sched, bool ALIGN_EPI = false, bool SP2 = false>
; __device__ __forceinline__ void gemm_phase(PG8_LAS unsigned char* lds, const Gemm g, const Sched& S, const Epi& E, int tid_in) {
;     ...
;             PG8_LDA(At, 1, 1); PG8_STAGE(PG8_SB(1, 0), b3, voffB); PG8_STAGE(PG8_SB(1, 1), b3 + hstepB, voffB); PG8_STAGE(PG8_SA(1, 0), a3, voffA);
;             PG8_WAIT_V(8); PG8_WAIT_L(0); PG8_BAR; PG8_MMA(1, 0, At, B0); PG8_MMA(1, 1, At, B1); PG8_BAR; PG8_SCHED;
;     __device__ __forceinline__ void operator()(const f32x4 (&acc)[2][2][4][2], const Unit& u, int wr, int wc, int fr, int fq) const {
;     ...
;                     const size_t off = (size_t)row * 2048 + u.pn * BM + wc * 64 + bj * 32 + 8 * p;
;                     f32x4 b0, b1;
;                     if (BASE_F32) { b0 = *(const f32x4*)((const float*)base + off); b1 = *(const f32x4*)((const float*)base + off + 4); }
	s_add_i32 s26, s33, s66
	v_lshl_add_u64 v[220:221], v[220:221], 0, s[42:43]
	s_mov_b32 m0, s26
	ds_read_b128 v[186:189], v155 offset:49152
	ds_read_b128 v[190:193], v155 offset:50176
	ds_read_b128 v[194:197], v155 offset:51200
	ds_read_b128 v[198:201], v155 offset:52224
	ds_read_b128 v[202:205], v155 offset:53248
	ds_read_b128 v[206:209], v155 offset:54272
	ds_read_b128 v[212:215], v155 offset:55296
	ds_read_b128 v[216:219], v155 offset:56320
	global_load_lds_dwordx4 v[220:221], off
	s_add_i32 m0, s26, 0x2000
	s_add_u32 s26, s60, 0x20080
	v_lshl_add_u64 v[220:221], v[222:223], 0, s[42:43]
	s_addc_u32 s27, s61, 0
	s_add_i32 s33, s84, s66
	global_load_lds_dwordx4 v[220:221], off
	v_lshl_add_u64 v[220:221], s[26:27], 0, v[130:131]
	s_mov_b32 m0, s33
	s_nop 0
	global_load_lds_dwordx4 v[220:221], off
	v_lshl_add_u64 v[220:221], s[26:27], 0, v[134:135]
	s_add_i32 m0, s33, 0x2000
	s_nop 0
	global_load_lds_dwordx4 v[220:221], off
	v_lshl_add_u64 v[220:221], v[224:225], 0, s[42:43]
	s_mov_b32 m0, s71
	s_nop 0
	global_load_lds_dwordx4 v[220:221], off
	v_lshl_add_u64 v[220:221], v[226:227], 0, s[42:43]
	s_mov_b32 m0, s72
	s_nop 0
	global_load_lds_dwordx4 v[220:221], off
	s_waitcnt vmcnt(8)
	s_waitcnt lgkmcnt(0)
	s_barrier
	s_waitcnt lgkmcnt(0)
	v_mfma_f32_16x16x32_bf16 v[60:63], v[146:149], v[186:189], v[60:63]
	v_mfma_f32_16x16x32_bf16 v[56:59], v[162:165], v[186:189], v[56:59]
	v_mfma_f32_16x16x32_bf16 v[44:47], v[146:149], v[194:197], v[44:47]
	v_mfma_f32_16x16x32_bf16 v[40:43], v[162:165], v[194:197], v[40:43]
	v_mfma_f32_16x16x32_bf16 v[28:31], v[146:149], v[202:205], v[28:31]
	v_mfma_f32_16x16x32_bf16 v[24:27], v[162:165], v[202:205], v[24:27]
	v_mfma_f32_16x16x32_bf16 v[12:15], v[146:149], v[212:215], v[12:15]
	v_mfma_f32_16x16x32_bf16 v[8:11], v[162:165], v[212:215], v[8:11]
	v_mfma_f32_16x16x32_bf16 v[60:63], v[158:161], v[190:193], v[60:63]
	v_mfma_f32_16x16x32_bf16 v[56:59], v[166:169], v[190:193], v[56:59]
	v_mfma_f32_16x16x32_bf16 v[44:47], v[158:161], v[198:201], v[44:47]
	v_mfma_f32_16x16x32_bf16 v[40:43], v[166:169], v[198:201], v[40:43]
	v_mfma_f32_16x16x32_bf16 v[28:31], v[158:161], v[206:209], v[28:31]
	v_mfma_f32_16x16x32_bf16 v[24:27], v[166:169], v[206:209], v[24:27]
	v_mfma_f32_16x16x32_bf16 v[12:15], v[158:161], v[216:219], v[12:15]
	v_mfma_f32_16x16x32_bf16 v[8:11], v[166:169], v[216:219], v[8:11]
	v_mfma_f32_16x16x32_bf16 v[52:55], v[170:173], v[186:189], v[52:55]
	v_mfma_f32_16x16x32_bf16 v[48:51], v[178:181], v[186:189], v[48:51]
	v_mfma_f32_16x16x32_bf16 v[36:39], v[170:173], v[194:197], v[36:39]
	v_mfma_f32_16x16x32_bf16 v[32:35], v[178:181], v[194:197], v[32:35]
	v_mfma_f32_16x16x32_bf16 v[20:23], v[170:173], v[202:205], v[20:23]
	v_mfma_f32_16x16x32_bf16 v[16:19], v[178:181], v[202:205], v[16:19]
	v_mfma_f32_16x16x32_bf16 v[4:7], v[170:173], v[212:215], v[4:7]
	v_mfma_f32_16x16x32_bf16 v[0:3], v[178:181], v[212:215], v[0:3]
	v_mfma_f32_16x16x32_bf16 v[52:55], v[174:177], v[190:193], v[52:55]
	v_mfma_f32_16x16x32_bf16 v[48:51], v[182:185], v[190:193], v[48:51]
	v_mfma_f32_16x16x32_bf16 v[36:39], v[174:177], v[198:201], v[36:39]
	v_mfma_f32_16x16x32_bf16 v[32:35], v[182:185], v[198:201], v[32:35]
	v_mfma_f32_16x16x32_bf16 v[20:23], v[174:177], v[206:209], v[20:23]
	v_mfma_f32_16x16x32_bf16 v[16:19], v[182:185], v[206:209], v[16:19]
	v_mfma_f32_16x16x32_bf16 v[4:7], v[174:177], v[216:219], v[4:7]
	v_mfma_f32_16x16x32_bf16 v[0:3], v[182:185], v[216:219], v[0:3]
	s_barrier
	s_add_i32 s79, s79, 2
	s_add_u32 s58, s58, 0x100
	s_addc_u32 s59, s59, 0
	s_add_u32 s76, s76, 0x100
	s_addc_u32 s77, s77, 0
	s_cmp_gt_u32 s79, 29
	s_cbranch_scc0 .LBB0_292
	v_lshl_add_u32 v148, s54, 8, v150
	v_lshl_or_b32 v146, s56, 8, v136
	v_lshl_add_u32 v147, v148, 11, v146
	v_lshlrev_b32_e32 v159, 1, v147
	v_lshlrev_b32_e32 v158, 2, v147
	v_lshlrev_b32_e32 v208, 3, v148
	global_load_dwordx4 v[160:163], v158, s[12:13]
	global_load_dwordx4 v[164:167], v158, s[12:13] offset:16
	global_load_dwordx4 v[168:171], v158, s[12:13] offset:128
	global_load_dwordx4 v[172:175], v158, s[12:13] offset:144
	v_add_u32_e32 v149, 0x20000, v158
	global_load_dwordx4 v[176:179], v149, s[12:13]
	global_load_dwordx4 v[180:183], v149, s[12:13] offset:16
	global_load_dwordx4 v[184:187], v149, s[12:13] offset:128
	global_load_dwordx4 v[188:191], v149, s[12:13] offset:144
	v_add_u32_e32 v209, 0x40000, v158
	global_load_dwordx4 v[192:195], v209, s[12:13]
	global_load_dwordx4 v[196:199], v209, s[12:13] offset:16
	global_load_dwordx4 v[200:203], v209, s[12:13] offset:128
	global_load_dwordx4 v[204:207], v209, s[12:13] offset:144
	v_add_u32_e32 v149, 0x60000, v158
	global_load_dwordx4 v[212:215], v149, s[12:13]
	global_load_dwordx4 v[216:219], v149, s[12:13] offset:16
	global_load_dwordx4 v[220:223], v149, s[12:13] offset:128
	global_load_dwordx4 v[224:227], v149, s[12:13] offset:144
	v_add_u32_e32 v209, 0x100000, v158
	global_load_dwordx4 v[228:231], v209, s[12:13]
	global_load_dwordx4 v[232:235], v209, s[12:13] offset:16
	global_load_dwordx4 v[236:239], v209, s[12:13] offset:128
	global_load_dwordx4 v[240:243], v209, s[12:13] offset:144
	s_and_b64 vcc, exec, s[44:45]
	s_cbranch_vccz .LBB0_295
	s_barrier

; __device__ __forceinline__ float rstd_of(const u64* ss, int row) { return __builtin_amdgcn_rsqf((float)ss[row] * (1.0f / (2048.0f * SS_SCALE)) + RMS_EPS); }
; #define LAS __attribute__((address_space(3)))
; __device__ __forceinline__ void fill_rstd(LAS unsigned char* L, const pg8::StaticOrder& S, const pg8::u64* ssx, int tid) {
;     LAS float* tabl = (LAS float*)(L + pg8::RSTD_OFF); pg8::Unit u; int last = -1;
;     for (int i = 0; S.next(i, u); ++i) { if (u.pm != last) { last = u.pm; if (tid < 256) tabl[((u.pm >> 3) & 3) * 256 + tid] = pg8::rstd_of(ssx, u.pm * 256 + tid); } }
;     __syncthreads();
.LBB0_367:
	s_or_b64 exec, exec, s[8:9]
	s_waitcnt lgkmcnt(0)
	s_setprio 0
	v_mov_b32_e32 v0, v252
	s_barrier
	s_movk_i32 s8, 0xff
	v_add_u32_e32 v2, s81, v0
	v_cmp_lt_i32_e32 vcc, s8, v2
	v_lshl_add_u32 v3, v2, 2, s82
	s_mov_b32 s26, -1
	v_mov_b64_e32 v[0:1], 0xfff
	s_xor_b64 s[8:9], vcc, -1
	v_mov_b32_e32 v4, 0x358637bd
	s_mov_b64 s[10:11], s[2:3]
	s_branch .LBB0_370

;     __host__ __device__ bool next(int i, Unit& u) const {
;         const long L = (long)i * G + c; if (L >= nwg) return false;
;         int wgid = (int)L; { const int q = nwg / NXCD, r = nwg % NXCD, xcd = wgid % NXCD, off = wgid / NXCD; wgid = (xcd < r ? xcd * (q + 1) : r * (q + 1) + (xcd - r) * q) + off; }
;         const int nig = wgm * nN, gid = wgid / nig, fm = gid * wgm, gsz = (nM - fm) < wgm ? (nM - fm) : wgm;
;         u.pm = fm + ((wgid % nig) % gsz); u.pn = (wgid % nig) / gsz; return true;
; __device__ __forceinline__ void fill_rstd(LAS unsigned char* L, const pg8::StaticOrder& S, const pg8::u64* ssx, int tid) {
;     ...
;     __syncthreads();
.LBB0_377:
	s_setprio 0
	v_mov_b32_e32 v0, v252
	s_waitcnt lgkmcnt(0)
	s_barrier
	s_cmpk_lt_i32 s2, 0x1000
	v_add_u32_e32 v8, s81, v0
	s_cselect_b64 s[40:41], -1, 0
	s_cmpk_gt_i32 s2, 0xfff
	v_readfirstlane_b32 s14, v8
	s_cbranch_scc1 .LBB0_401
	s_lshr_b32 s8, s3, 29
	s_add_i32 s11, s2, s8
	s_and_b32 s8, s11, -8
	s_sub_i32 s12, s2, s8
	s_cmp_gt_i32 s12, -1
	s_cbranch_scc0 .LBB0_380
	s_lshl_b32 s10, s12, 9
	s_cbranch_execz .LBB0_381
	s_branch .LBB0_382

; #define PG8_STAGE(bufoff, gbase, voff) do { _Pragma("unroll") for (int _i = 0; _i < 2; ++_i) \
;         __builtin_amdgcn_global_load_lds((const unsigned*)((const char*)(gbase) + (voff)[_i]), (PG8_LAS unsigned*)(lds + (bufoff) + ldsw + _i * 8192), 16, 0, 0); } while (0)
; #define PG8_WAIT_V(n) asm volatile("s_waitcnt vmcnt(" #n ")" ::: "memory")
; #define PG8_BAR __builtin_amdgcn_s_barrier()
; template <class Epi, class Sched, bool ALIGN_EPI = false, bool SP2 = false>
; __device__ __forceinline__ void gemm_phase(PG8_LAS unsigned char* lds, const Gemm g, const Sched& S, const Epi& E, int tid_in) {
;     int tid_ = tid_in; asm volatile("" : "+v"(tid_)); const int tid = tid_, wid = __builtin_amdgcn_readfirstlane(tid >> 6), lane = tid & 63, wr = wid >> 2, wc = wid & 3, fr = lane & 15, fq = lane >> 4;
;     const int K = g.K, nt = K / BK;
;     unsigned voffA[2], voffB[2];
; #pragma unroll
;     for (int i = 0; i < 2; ++i) { int R, C; stage_rc(tid * 16 + i * 8192, R, C); const int Rb = 2 * (R & ~31) + (Epi::PERM ? perm32(R & 31) : (R & 31));
;         voffA[i] = (unsigned)(R * g.lda + C) * 2u; voffB[i] = (unsigned)(Rb * K + C) * 2u; }
;     const size_t kstep = (size_t)(BK * 2);
;     const size_t hstep = (size_t)HALF * g.lda * 2;
;     const size_t hstepB = (size_t)32 * K * 2;
;     const size_t tstep = 2 * hstep, tstepB = (size_t)BM * K * 2;
;     const unsigned ldsw = (unsigned)wid * 1024u;
;     const int aoff = lds_byte(wr * 64 + fr, fq * 8), boff = lds_byte(wc * 32 + fr, fq * 8);
;     ...
;     Unit cur, nxt; int ui = 0;
;     if (!S.next(0, cur)) return;
;     f32x4 acc[2][2][4][2];
; #pragma unroll
;     for (int a = 0; a < 2; ++a)
; #pragma unroll
;         for (int b = 0; b < 2; ++b)
; #pragma unroll
;             for (int m = 0; m < 4; ++m)
; #pragma unroll
;                 for (int n = 0; n < 2; ++n) acc[a][b][m][n] = (f32x4){0.f, 0.f, 0.f, 0.f};
;     bf16x8 At[4][2], B0[2][2], B1[2][2];
;     const char* cA = (const char*)g.A + (size_t)cur.pm * tstep; const char* cB = (const char*)g.Bt + (size_t)cur.pn * tstepB;
;     S.a_ready(cur);
;     if constexpr (SP2) {
;         PG8_STAGE(PG8_SB(0, 0), cB, voffB); PG8_STAGE(PG8_SB(0, 1), cB + hstepB, voffB); PG8_STAGE(PG8_SA(0, 0), cA, voffA); PG8_STAGE(PG8_SA(0, 1), cA + hstep, voffA);
;         if (wr == 1) PG8_BAR;
;         PG8_WAIT_V(2); PG8_BAR;
.LBB0_382:
	v_ashrrev_i32_e32 v0, 31, v8
	v_lshrrev_b32_e32 v0, 26, v0
	v_add_u32_e32 v0, v8, v0
	v_ashrrev_i32_e32 v9, 6, v0
	v_bfe_i32 v0, v8, 27, 1
	s_waitcnt vmcnt(8)
	v_lshlrev_b32_e32 v12, 4, v8
	v_lshrrev_b32_e32 v0, 22, v0
	v_add_u32_e32 v0, v12, v0
	v_and_b32_e32 v0, 0xfffffc00, v0
	v_sub_u32_e32 v0, v12, v0
	v_lshrrev_b32_e32 v1, 4, v0
	v_bitop3_b32 v0, v1, v0, 32 bitop3:0x6c
	v_ashrrev_i32_e32 v2, 31, v0
	v_lshrrev_b32_e32 v2, 26, v2
	v_add_u32_e32 v2, v0, v2
	v_lshlrev_b32_e32 v1, 3, v9
	v_ashrrev_i32_e32 v10, 6, v2
	v_and_b32_e32 v2, 0xc0, v2
	v_and_b32_e32 v1, -16, v1
	v_sub_u32_e32 v0, v0, v2
	v_mov_b32_e32 v2, 1
	v_add_u32_e32 v1, v10, v1
	v_ashrrev_i16_sdwa v0, v2, sext(v0) dst_sel:DWORD dst_unused:UNUSED_PAD src0_sel:DWORD src1_sel:BYTE_0
	s_ashr_i32 s8, s11, 3
	v_lshlrev_b32_e32 v3, 5, v9
	v_bfe_i32 v11, v0, 0, 16
	v_lshlrev_b32_e32 v0, 1, v1
	v_lshrrev_b32_e32 v4, 2, v1
	s_add_u32 s58, s18, 0x2400000
	v_and_b32_e32 v3, 32, v3
	v_and_b32_e32 v4, 4, v4
	v_and_b32_e32 v5, 3, v10
	v_and_b32_e32 v0, 0xfffd8, v0
	s_addc_u32 s59, s19, 0
	v_or3_b32 v0, v5, v4, v0
	v_add_lshl_u32 v3, v3, v11, 1
	s_add_i32 s8, s10, s8
	v_lshl_add_u32 v130, v0, 12, v3
	v_add_u32_e32 v0, 0x2000, v12
	s_ashr_i32 s10, s8, 31
	v_lshl_add_u32 v128, v1, 12, v3
	v_ashrrev_i32_e32 v1, 31, v0
	s_lshr_b32 s10, s10, 24
	v_lshrrev_b32_e32 v1, 22, v1
	s_add_i32 s10, s8, s10
	v_add_u32_e32 v1, v0, v1
	s_ashr_i32 s11, s10, 8
	s_and_b32 s10, s10, 0xffffff00
	v_ashrrev_i32_e32 v13, 10, v1
	s_sub_i32 s10, s8, s10
	v_mul_i32_i24_e32 v1, 0x400, v13
	s_sext_i32_i16 s8, s10
	v_sub_u32_e32 v0, v0, v1
	s_bfe_u32 s8, s8, 0x3001c
	v_lshrrev_b32_e32 v1, 4, v0
	s_add_i32 s12, s10, s8
	v_bitop3_b32 v0, v1, v0, 32 bitop3:0x6c
	s_sext_i32_i16 s8, s12
	s_and_b32 s12, s12, 0xfff8
	v_ashrrev_i32_e32 v3, 31, v0
	s_sub_i32 s10, s10, s12
	v_lshrrev_b32_e32 v3, 26, v3
	s_lshl_b32 s11, s11, 3
	s_sext_i32_i16 s10, s10
	s_ashr_i32 s9, s14, 6
	v_add_u32_e32 v3, v0, v3
	s_lshr_b32 s8, s8, 3
	s_add_i32 s50, s11, s10
	v_lshlrev_b32_e32 v1, 3, v13
	v_ashrrev_i32_e32 v14, 6, v3
	v_and_b32_e32 v3, 0xc0, v3
	s_ashr_i32 s51, s50, 31
	s_bfe_i64 s[12:13], s[8:9], 0x100000
	v_and_b32_e32 v1, -16, v1
	v_sub_u32_e32 v0, v0, v3
	s_ashr_i32 s33, s14, 8
	s_lshl_b32 s60, s9, 10
	s_lshl_b64 s[10:11], s[50:51], 20
	s_lshl_b64 s[12:13], s[12:13], 20
	v_add_u32_e32 v1, v14, v1
	v_ashrrev_i16_sdwa v0, v2, sext(v0) dst_sel:DWORD dst_unused:UNUSED_PAD src0_sel:DWORD src1_sel:BYTE_0
	s_add_u32 s54, s58, s12
	v_lshlrev_b32_e32 v4, 5, v13
	v_bfe_i32 v15, v0, 0, 16
	v_lshlrev_b32_e32 v0, 1, v1
	v_lshrrev_b32_e32 v2, 2, v1
	s_addc_u32 s55, s59, s13
	s_add_i32 s51, s60, 0
	v_and_b32_e32 v4, 32, v4
	v_and_b32_e32 v2, 4, v2
	v_and_b32_e32 v3, 3, v14
	v_and_b32_e32 v0, 0xfffd8, v0
	s_add_i32 m0, s51, 0x10000
	v_or3_b32 v0, v3, v2, v0
	v_add_lshl_u32 v2, v4, v15, 1
	global_load_lds_dwordx4 v130, s[54:55]
	s_add_i32 m0, s51, 0x12000
	v_lshl_add_u32 v134, v0, 12, v2
	s_add_u32 s12, s54, 0x20000
	global_load_lds_dwordx4 v134, s[54:55]
	s_addc_u32 s13, s55, 0
	s_add_i32 m0, s51, 0x14000
	v_lshl_add_u32 v132, v1, 12, v2
	global_load_lds_dwordx4 v130, s[12:13]
	s_add_i32 m0, s51, 0x16000
	s_add_u32 s52, s38, s10
	s_addc_u32 s53, s39, s11
	s_add_i32 s61, s51, 0x2000
	global_load_lds_dwordx4 v134, s[12:13]
	s_mov_b32 m0, s51
	s_add_u32 s10, s52, 0x80000
	global_load_lds_dwordx4 v128, s[52:53]
	s_mov_b32 m0, s61
	s_addc_u32 s11, s53, 0
	s_add_i32 s62, s51, 0x4000
	global_load_lds_dwordx4 v132, s[52:53]
	s_mov_b32 m0, s62
	s_add_i32 s63, s51, 0x6000
	global_load_lds_dwordx4 v128, s[10:11]
	s_mov_b32 m0, s63
	v_mov_b32_e32 v131, 0
	global_load_lds_dwordx4 v132, s[10:11]
	v_mov_b32_e32 v135, v131
	v_mov_b32_e32 v129, v131
	v_mov_b32_e32 v133, v131
	s_cmp_eq_u32 s33, 1
	s_mov_b32 s64, 0
	v_lshl_add_u64 v[6:7], s[54:55], 0, v[130:131]
	v_lshl_add_u64 v[4:5], s[54:55], 0, v[134:135]
	v_lshl_add_u64 v[0:1], s[52:53], 0, v[128:129]
	s_cselect_b64 s[10:11], -1, 0
	s_cmp_lg_u32 s33, 1
	v_lshl_add_u64 v[2:3], s[52:53], 0, v[132:133]
	s_cbranch_scc1 .LBB0_384
	s_barrier
	s_setprio 1

; #define PG8_STAGE(bufoff, gbase, voff) do { _Pragma("unroll") for (int _i = 0; _i < 2; ++_i) \
;         __builtin_amdgcn_global_load_lds((const unsigned*)((const char*)(gbase) + (voff)[_i]), (PG8_LAS unsigned*)(lds + (bufoff) + ldsw + _i * 8192), 16, 0, 0); } while (0)
; #define PG8_LDA(dst, b, h) do { _Pragma("unroll") for (int m = 0; m < 4; ++m) _Pragma("unroll") for (int k = 0; k < 2; ++k) dst[m][k] = *(const PG8_LAS bf16x8*)(lds + PG8_SA(b, h) + aoff + m * 2048 + k * 1024); } while (0)
; #define PG8_LDB(dst, b, h) do { _Pragma("unroll") for (int n = 0; n < 2; ++n) _Pragma("unroll") for (int k = 0; k < 2; ++k) dst[n][k] = *(const PG8_LAS bf16x8*)(lds + PG8_SB(b, h) + boff + n * 2048 + k * 1024); } while (0)
; #define PG8_MMA(ai, bj, At, Bt) do { __builtin_amdgcn_s_setprio(1); _Pragma("unroll") for (int m = 0; m < 4; ++m) _Pragma("unroll") for (int n = 0; n < 2; ++n) _Pragma("unroll") for (int k = 0; k < 2; ++k) \
;         acc[ai][bj][m][n] = __builtin_amdgcn_mfma_f32_16x16x32_bf16(Bt[n][k], At[m][k], acc[ai][bj][m][n], 0, 0, 0); __builtin_amdgcn_s_setprio(0); } while (0)
; #define PG8_WAIT_V(n) asm volatile("s_waitcnt vmcnt(" #n ")" ::: "memory")
; #define PG8_WAIT_L(n) asm volatile("s_waitcnt lgkmcnt(" #n ")" ::: "memory")
; #define PG8_BAR __builtin_amdgcn_s_barrier()
; #define PG8_SCHED __builtin_amdgcn_sched_barrier(0)
; template <class Epi, class Sched, bool ALIGN_EPI = false, bool SP2 = false>
; __device__ __forceinline__ void gemm_phase(PG8_LAS unsigned char* lds, const Gemm g, const Sched& S, const Epi& E, int tid_in) {
;     ...
;             PG8_LDB(B0, 0, 0); PG8_LDB(B1, 0, 1); PG8_SCHED; PG8_LDA(At, 0, 0); PG8_STAGE(PG8_SA(1, 1), a1 + hstep, voffA);
;             PG8_WAIT_V(8); PG8_WAIT_L(0); PG8_BAR; PG8_MMA(0, 0, At, B0); PG8_MMA(0, 1, At, B1); PG8_BAR; PG8_SCHED;
;             PG8_LDA(At, 0, 1); PG8_STAGE(PG8_SB(0, 0), b2, voffB); PG8_STAGE(PG8_SB(0, 1), b2 + hstepB, voffB); PG8_STAGE(PG8_SA(0, 0), a2, voffA);
;             PG8_WAIT_V(8); PG8_WAIT_L(0); PG8_BAR; PG8_MMA(1, 0, At, B0); PG8_MMA(1, 1, At, B1); PG8_BAR; PG8_SCHED;
.Lkb_skip_2:
.LBB0_394:
	ds_read_b128 v[156:159], v150
	ds_read_b128 v[160:163], v150 offset:1024
	ds_read_b128 v[164:167], v150 offset:2048
	ds_read_b128 v[168:171], v150 offset:3072
	ds_read_b128 v[172:175], v151
	ds_read_b128 v[176:179], v151 offset:1024
	ds_read_b128 v[180:183], v151 offset:2048
	ds_read_b128 v[184:187], v151 offset:3072
	s_add_u32 s26, s52, 0xfff80080
	s_addc_u32 s27, s53, -1
	s_cmp_eq_u32 s76, 28
	s_cselect_b32 s57, s45, s27
	s_cselect_b32 s56, s72, s26
	s_cselect_b32 s55, s43, s75
	s_cselect_b32 s54, s73, s74
	v_lshl_add_u64 v[208:209], s[52:53], 0, v[138:139]
	s_add_i32 m0, s51, 0xc000
	ds_read_b128 v[188:191], v152
	ds_read_b128 v[192:195], v152 offset:1024
	ds_read_b128 v[196:199], v152 offset:2048
	ds_read_b128 v[200:203], v152 offset:3072
	ds_read_b128 v[204:207], v152 offset:4096
	ds_read_b128 v[212:215], v152 offset:5120
	ds_read_b128 v[216:219], v152 offset:6144
	ds_read_b128 v[220:223], v152 offset:7168
	global_load_lds_dwordx4 v[208:209], off
	v_lshl_add_u64 v[208:209], s[52:53], 0, v[140:141]
	s_add_i32 m0, s51, 0xe000
	s_nop 0
	global_load_lds_dwordx4 v[208:209], off
	s_waitcnt vmcnt(8)
	s_waitcnt lgkmcnt(0)
	s_barrier
	s_waitcnt lgkmcnt(0)
	v_mfma_f32_16x16x32_bf16 v[124:127], v[156:159], v[188:191], v[124:127]
	v_mfma_f32_16x16x32_bf16 v[120:123], v[164:167], v[188:191], v[120:123]
	v_mfma_f32_16x16x32_bf16 v[108:111], v[156:159], v[196:199], v[108:111]
	v_mfma_f32_16x16x32_bf16 v[104:107], v[164:167], v[196:199], v[104:107]
	v_mfma_f32_16x16x32_bf16 v[92:95], v[156:159], v[204:207], v[92:95]
	v_mfma_f32_16x16x32_bf16 v[88:91], v[164:167], v[204:207], v[88:91]
	v_mfma_f32_16x16x32_bf16 v[76:79], v[156:159], v[216:219], v[76:79]
	v_mfma_f32_16x16x32_bf16 v[72:75], v[164:167], v[216:219], v[72:75]
	v_mfma_f32_16x16x32_bf16 v[124:127], v[160:163], v[192:195], v[124:127]
	v_mfma_f32_16x16x32_bf16 v[120:123], v[168:171], v[192:195], v[120:123]
	v_mfma_f32_16x16x32_bf16 v[108:111], v[160:163], v[200:203], v[108:111]
	v_mfma_f32_16x16x32_bf16 v[104:107], v[168:171], v[200:203], v[104:107]
	v_mfma_f32_16x16x32_bf16 v[92:95], v[160:163], v[212:215], v[92:95]
	v_mfma_f32_16x16x32_bf16 v[88:91], v[168:171], v[212:215], v[88:91]
	v_mfma_f32_16x16x32_bf16 v[76:79], v[160:163], v[220:223], v[76:79]
	v_mfma_f32_16x16x32_bf16 v[72:75], v[168:171], v[220:223], v[72:75]
	v_mfma_f32_16x16x32_bf16 v[116:119], v[172:175], v[188:191], v[116:119]
	v_mfma_f32_16x16x32_bf16 v[112:115], v[180:183], v[188:191], v[112:115]
	v_mfma_f32_16x16x32_bf16 v[100:103], v[172:175], v[196:199], v[100:103]
	v_mfma_f32_16x16x32_bf16 v[96:99], v[180:183], v[196:199], v[96:99]
	v_mfma_f32_16x16x32_bf16 v[84:87], v[172:175], v[204:207], v[84:87]
	v_mfma_f32_16x16x32_bf16 v[80:83], v[180:183], v[204:207], v[80:83]
	v_mfma_f32_16x16x32_bf16 v[68:71], v[172:175], v[216:219], v[68:71]
	v_mfma_f32_16x16x32_bf16 v[64:67], v[180:183], v[216:219], v[64:67]
	v_mfma_f32_16x16x32_bf16 v[116:119], v[176:179], v[192:195], v[116:119]
	v_mfma_f32_16x16x32_bf16 v[112:115], v[184:187], v[192:195], v[112:115]
	v_mfma_f32_16x16x32_bf16 v[100:103], v[176:179], v[200:203], v[100:103]
	v_mfma_f32_16x16x32_bf16 v[96:99], v[184:187], v[200:203], v[96:99]
	v_mfma_f32_16x16x32_bf16 v[84:87], v[176:179], v[212:215], v[84:87]
	v_mfma_f32_16x16x32_bf16 v[80:83], v[184:187], v[212:215], v[80:83]
	v_mfma_f32_16x16x32_bf16 v[68:71], v[176:179], v[220:223], v[68:71]
	v_mfma_f32_16x16x32_bf16 v[64:67], v[184:187], v[220:223], v[64:67]
	s_barrier
	s_add_i32 s26, s68, s60
	v_lshl_add_u64 v[208:209], s[54:55], 0, v[130:131]
	s_mov_b32 m0, s26
	ds_read_b128 v[188:191], v152 offset:16384
	ds_read_b128 v[192:195], v152 offset:17408
	ds_read_b128 v[196:199], v152 offset:18432
	ds_read_b128 v[200:203], v152 offset:19456
	ds_read_b128 v[204:207], v152 offset:20480
	ds_read_b128 v[212:215], v152 offset:21504
	ds_read_b128 v[216:219], v152 offset:22528
	ds_read_b128 v[220:223], v152 offset:23552
	global_load_lds_dwordx4 v[208:209], off
	s_add_i32 m0, s26, 0x2000
	s_add_u32 s26, s54, 0x20000
	v_lshl_add_u64 v[224:225], s[54:55], 0, v[134:135]
	s_addc_u32 s27, s55, 0
	s_add_i32 s33, s69, s60
	global_load_lds_dwordx4 v[224:225], off
	v_lshl_add_u64 v[226:227], s[26:27], 0, v[130:131]
	s_mov_b32 m0, s33
	v_lshl_add_u64 v[228:229], s[56:57], 0, v[132:133]
	global_load_lds_dwordx4 v[226:227], off
	v_lshl_add_u64 v[226:227], s[26:27], 0, v[134:135]
	s_add_i32 m0, s33, 0x2000
	s_nop 0
	global_load_lds_dwordx4 v[226:227], off
	v_lshl_add_u64 v[226:227], s[56:57], 0, v[128:129]
	s_mov_b32 m0, s51
	s_nop 0
	global_load_lds_dwordx4 v[226:227], off
	s_mov_b32 m0, s61
	s_nop 0
	global_load_lds_dwordx4 v[228:229], off
	s_waitcnt vmcnt(8)
	s_waitcnt lgkmcnt(0)
	s_barrier
; #define PG8_STAGE(bufoff, gbase, voff) do { _Pragma("unroll") for (int _i = 0; _i < 2; ++_i) \
;         __builtin_amdgcn_global_load_lds((const unsigned*)((const char*)(gbase) + (voff)[_i]), (PG8_LAS unsigned*)(lds + (bufoff) + ldsw + _i * 8192), 16, 0, 0); } while (0)
; #define PG8_LDA(dst, b, h) do { _Pragma("unroll") for (int m = 0; m < 4; ++m) _Pragma("unroll") for (int k = 0; k < 2; ++k) dst[m][k] = *(const PG8_LAS bf16x8*)(lds + PG8_SA(b, h) + aoff + m * 2048 + k * 1024); } while (0)
; #define PG8_LDB(dst, b, h) do { _Pragma("unroll") for (int n = 0; n < 2; ++n) _Pragma("unroll") for (int k = 0; k < 2; ++k) dst[n][k] = *(const PG8_LAS bf16x8*)(lds + PG8_SB(b, h) + boff + n * 2048 + k * 1024); } while (0)
; #define PG8_MMA(ai, bj, At, Bt) do { __builtin_amdgcn_s_setprio(1); _Pragma("unroll") for (int m = 0; m < 4; ++m) _Pragma("unroll") for (int n = 0; n < 2; ++n) _Pragma("unroll") for (int k = 0; k < 2; ++k) \
;         acc[ai][bj][m][n] = __builtin_amdgcn_mfma_f32_16x16x32_bf16(Bt[n][k], At[m][k], acc[ai][bj][m][n], 0, 0, 0); __builtin_amdgcn_s_setprio(0); } while (0)
; #define PG8_WAIT_V(n) asm volatile("s_waitcnt vmcnt(" #n ")" ::: "memory")
; #define PG8_WAIT_L(n) asm volatile("s_waitcnt lgkmcnt(" #n ")" ::: "memory")
; #define PG8_BAR __builtin_amdgcn_s_barrier()
; #define PG8_SCHED __builtin_amdgcn_sched_barrier(0)
; template <class Epi, class Sched, bool ALIGN_EPI = false, bool SP2 = false>
; __device__ __forceinline__ void gemm_phase(PG8_LAS unsigned char* lds, const Gemm g, const Sched& S, const Epi& E, int tid_in) {
;     ...
;             PG8_WAIT_V(8); PG8_WAIT_L(0); PG8_BAR; PG8_MMA(1, 0, At, B0); PG8_MMA(1, 1, At, B1); PG8_BAR; PG8_SCHED;
;             PG8_LDB(B0, 1, 0); PG8_LDB(B1, 1, 1); PG8_SCHED; PG8_LDA(At, 1, 0); PG8_STAGE(PG8_SA(0, 1), a2 + hstep, voffA);
;             PG8_WAIT_V(8); PG8_WAIT_L(0); PG8_BAR; PG8_MMA(0, 0, At, B0); PG8_MMA(0, 1, At, B1); PG8_BAR; PG8_SCHED;
	s_waitcnt lgkmcnt(0)
	v_mfma_f32_16x16x32_bf16 v[60:63], v[156:159], v[188:191], v[60:63]
	v_mfma_f32_16x16x32_bf16 v[56:59], v[164:167], v[188:191], v[56:59]
	v_mfma_f32_16x16x32_bf16 v[44:47], v[156:159], v[196:199], v[44:47]
	v_mfma_f32_16x16x32_bf16 v[40:43], v[164:167], v[196:199], v[40:43]
	v_mfma_f32_16x16x32_bf16 v[28:31], v[156:159], v[204:207], v[28:31]
	v_mfma_f32_16x16x32_bf16 v[24:27], v[164:167], v[204:207], v[24:27]
	v_mfma_f32_16x16x32_bf16 v[12:15], v[156:159], v[216:219], v[12:15]
	v_mfma_f32_16x16x32_bf16 v[8:11], v[164:167], v[216:219], v[8:11]
	v_mfma_f32_16x16x32_bf16 v[60:63], v[160:163], v[192:195], v[60:63]
	v_mfma_f32_16x16x32_bf16 v[56:59], v[168:171], v[192:195], v[56:59]
	v_mfma_f32_16x16x32_bf16 v[44:47], v[160:163], v[200:203], v[44:47]
	v_mfma_f32_16x16x32_bf16 v[40:43], v[168:171], v[200:203], v[40:43]
	v_mfma_f32_16x16x32_bf16 v[28:31], v[160:163], v[212:215], v[28:31]
	v_mfma_f32_16x16x32_bf16 v[24:27], v[168:171], v[212:215], v[24:27]
	v_mfma_f32_16x16x32_bf16 v[12:15], v[160:163], v[220:223], v[12:15]
	v_mfma_f32_16x16x32_bf16 v[8:11], v[168:171], v[220:223], v[8:11]
	v_mfma_f32_16x16x32_bf16 v[52:55], v[172:175], v[188:191], v[52:55]
	v_mfma_f32_16x16x32_bf16 v[48:51], v[180:183], v[188:191], v[48:51]
	v_mfma_f32_16x16x32_bf16 v[36:39], v[172:175], v[196:199], v[36:39]
	v_mfma_f32_16x16x32_bf16 v[32:35], v[180:183], v[196:199], v[32:35]
	v_mfma_f32_16x16x32_bf16 v[20:23], v[172:175], v[204:207], v[20:23]
	v_mfma_f32_16x16x32_bf16 v[16:19], v[180:183], v[204:207], v[16:19]
	v_mfma_f32_16x16x32_bf16 v[4:7], v[172:175], v[216:219], v[4:7]
	v_mfma_f32_16x16x32_bf16 v[0:3], v[180:183], v[216:219], v[0:3]
	v_mfma_f32_16x16x32_bf16 v[52:55], v[176:179], v[192:195], v[52:55]
	v_mfma_f32_16x16x32_bf16 v[48:51], v[184:187], v[192:195], v[48:51]
	v_mfma_f32_16x16x32_bf16 v[36:39], v[176:179], v[200:203], v[36:39]
	v_mfma_f32_16x16x32_bf16 v[32:35], v[184:187], v[200:203], v[32:35]
	v_mfma_f32_16x16x32_bf16 v[20:23], v[176:179], v[212:215], v[20:23]
	v_mfma_f32_16x16x32_bf16 v[16:19], v[184:187], v[212:215], v[16:19]
	v_mfma_f32_16x16x32_bf16 v[4:7], v[176:179], v[220:223], v[4:7]
	v_mfma_f32_16x16x32_bf16 v[0:3], v[184:187], v[220:223], v[0:3]
	s_barrier
	s_add_i32 s33, 0, 0x18000
	v_add_u32_e32 v155, s33, v146
	s_add_i32 s77, 0, 0x1c000
	ds_read_b128 v[156:159], v155
	ds_read_b128 v[160:163], v155 offset:1024
	ds_read_b128 v[164:167], v155 offset:2048
	ds_read_b128 v[168:171], v155 offset:3072
	v_add_u32_e32 v155, s77, v146
	ds_read_b128 v[172:175], v155
	ds_read_b128 v[176:179], v155 offset:1024
	ds_read_b128 v[180:183], v155 offset:2048
	ds_read_b128 v[184:187], v155 offset:3072
	s_add_u32 s26, s56, 0x80000
	s_addc_u32 s27, s57, 0
	s_mov_b32 m0, s62
	v_lshl_add_u64 v[230:231], s[26:27], 0, v[128:129]
	ds_read_b128 v[188:191], v152 offset:32768
	ds_read_b128 v[192:195], v152 offset:33792
	ds_read_b128 v[196:199], v152 offset:34816
	ds_read_b128 v[200:203], v152 offset:35840
	ds_read_b128 v[204:207], v152 offset:36864
	ds_read_b128 v[212:215], v152 offset:37888
	ds_read_b128 v[216:219], v152 offset:38912
	ds_read_b128 v[220:223], v152 offset:39936
	global_load_lds_dwordx4 v[230:231], off
	v_lshl_add_u64 v[230:231], s[26:27], 0, v[132:133]
	s_mov_b32 m0, s63
	s_nop 0
	global_load_lds_dwordx4 v[230:231], off
	s_waitcnt vmcnt(8)
	s_waitcnt lgkmcnt(0)
	s_barrier
	s_waitcnt lgkmcnt(0)
	v_mfma_f32_16x16x32_bf16 v[124:127], v[156:159], v[188:191], v[124:127]
	v_mfma_f32_16x16x32_bf16 v[120:123], v[164:167], v[188:191], v[120:123]
	v_mfma_f32_16x16x32_bf16 v[108:111], v[156:159], v[196:199], v[108:111]
	v_mfma_f32_16x16x32_bf16 v[104:107], v[164:167], v[196:199], v[104:107]
	v_mfma_f32_16x16x32_bf16 v[92:95], v[156:159], v[204:207], v[92:95]
	v_mfma_f32_16x16x32_bf16 v[88:91], v[164:167], v[204:207], v[88:91]
	v_mfma_f32_16x16x32_bf16 v[76:79], v[156:159], v[216:219], v[76:79]
	v_mfma_f32_16x16x32_bf16 v[72:75], v[164:167], v[216:219], v[72:75]
	v_mfma_f32_16x16x32_bf16 v[124:127], v[160:163], v[192:195], v[124:127]
	v_mfma_f32_16x16x32_bf16 v[120:123], v[168:171], v[192:195], v[120:123]
	v_mfma_f32_16x16x32_bf16 v[108:111], v[160:163], v[200:203], v[108:111]
	v_mfma_f32_16x16x32_bf16 v[104:107], v[168:171], v[200:203], v[104:107]
	v_mfma_f32_16x16x32_bf16 v[92:95], v[160:163], v[212:215], v[92:95]
	v_mfma_f32_16x16x32_bf16 v[88:91], v[168:171], v[212:215], v[88:91]
	v_mfma_f32_16x16x32_bf16 v[76:79], v[160:163], v[220:223], v[76:79]
	v_mfma_f32_16x16x32_bf16 v[72:75], v[168:171], v[220:223], v[72:75]
	v_mfma_f32_16x16x32_bf16 v[116:119], v[172:175], v[188:191], v[116:119]
	v_mfma_f32_16x16x32_bf16 v[112:115], v[180:183], v[188:191], v[112:115]
	v_mfma_f32_16x16x32_bf16 v[100:103], v[172:175], v[196:199], v[100:103]
	v_mfma_f32_16x16x32_bf16 v[96:99], v[180:183], v[196:199], v[96:99]
	v_mfma_f32_16x16x32_bf16 v[84:87], v[172:175], v[204:207], v[84:87]
	v_mfma_f32_16x16x32_bf16 v[80:83], v[180:183], v[204:207], v[80:83]
	v_mfma_f32_16x16x32_bf16 v[68:71], v[172:175], v[216:219], v[68:71]
	v_mfma_f32_16x16x32_bf16 v[64:67], v[180:183], v[216:219], v[64:67]
	v_mfma_f32_16x16x32_bf16 v[116:119], v[176:179], v[192:195], v[116:119]
	v_mfma_f32_16x16x32_bf16 v[112:115], v[184:187], v[192:195], v[112:115]
	v_mfma_f32_16x16x32_bf16 v[100:103], v[176:179], v[200:203], v[100:103]
	v_mfma_f32_16x16x32_bf16 v[96:99], v[184:187], v[200:203], v[96:99]
	v_mfma_f32_16x16x32_bf16 v[84:87], v[176:179], v[212:215], v[84:87]
	v_mfma_f32_16x16x32_bf16 v[80:83], v[184:187], v[212:215], v[80:83]
	v_mfma_f32_16x16x32_bf16 v[68:71], v[176:179], v[220:223], v[68:71]
	v_mfma_f32_16x16x32_bf16 v[64:67], v[184:187], v[220:223], v[64:67]
	s_barrier
; #define PG8_STAGE(bufoff, gbase, voff) do { _Pragma("unroll") for (int _i = 0; _i < 2; ++_i) \
;         __builtin_amdgcn_global_load_lds((const unsigned*)((const char*)(gbase) + (voff)[_i]), (PG8_LAS unsigned*)(lds + (bufoff) + ldsw + _i * 8192), 16, 0, 0); } while (0)
; #define PG8_LDA(dst, b, h) do { _Pragma("unroll") for (int m = 0; m < 4; ++m) _Pragma("unroll") for (int k = 0; k < 2; ++k) dst[m][k] = *(const PG8_LAS bf16x8*)(lds + PG8_SA(b, h) + aoff + m * 2048 + k * 1024); } while (0)
; #define PG8_MMA(ai, bj, At, Bt) do { __builtin_amdgcn_s_setprio(1); _Pragma("unroll") for (int m = 0; m < 4; ++m) _Pragma("unroll") for (int n = 0; n < 2; ++n) _Pragma("unroll") for (int k = 0; k < 2; ++k) \
;         acc[ai][bj][m][n] = __builtin_amdgcn_mfma_f32_16x16x32_bf16(Bt[n][k], At[m][k], acc[ai][bj][m][n], 0, 0, 0); __builtin_amdgcn_s_setprio(0); } while (0)
; #define PG8_WAIT_V(n) asm volatile("s_waitcnt vmcnt(" #n ")" ::: "memory")
; #define PG8_WAIT_L(n) asm volatile("s_waitcnt lgkmcnt(" #n ")" ::: "memory")
; #define PG8_BAR __builtin_amdgcn_s_barrier()
; #define PG8_SCHED __builtin_amdgcn_sched_barrier(0)
; template <class Epi, class Sched, bool ALIGN_EPI = false, bool SP2 = false>
; __device__ __forceinline__ void gemm_phase(PG8_LAS unsigned char* lds, const Gemm g, const Sched& S, const Epi& E, int tid_in) {
;     ...
;             PG8_LDA(At, 1, 1); PG8_STAGE(PG8_SB(1, 0), b3, voffB); PG8_STAGE(PG8_SB(1, 1), b3 + hstepB, voffB); PG8_STAGE(PG8_SA(1, 0), a3, voffA);
;             PG8_WAIT_V(8); PG8_WAIT_L(0); PG8_BAR; PG8_MMA(1, 0, At, B0); PG8_MMA(1, 1, At, B1); PG8_BAR; PG8_SCHED;
	s_add_i32 s26, s33, s60
	v_lshl_add_u64 v[208:209], v[208:209], 0, s[12:13]
	s_mov_b32 m0, s26
	ds_read_b128 v[188:191], v152 offset:49152
	ds_read_b128 v[192:195], v152 offset:50176
	ds_read_b128 v[196:199], v152 offset:51200
	ds_read_b128 v[200:203], v152 offset:52224
	ds_read_b128 v[204:207], v152 offset:53248
	ds_read_b128 v[212:215], v152 offset:54272
	ds_read_b128 v[216:219], v152 offset:55296
	ds_read_b128 v[220:223], v152 offset:56320
	global_load_lds_dwordx4 v[208:209], off
	s_add_i32 m0, s26, 0x2000
	s_add_u32 s26, s54, 0x20080
	v_lshl_add_u64 v[208:209], v[224:225], 0, s[12:13]
	s_addc_u32 s27, s55, 0
	s_add_i32 s33, s77, s60
	global_load_lds_dwordx4 v[208:209], off
	v_lshl_add_u64 v[208:209], s[26:27], 0, v[130:131]
	s_mov_b32 m0, s33
	s_nop 0
	global_load_lds_dwordx4 v[208:209], off
	v_lshl_add_u64 v[208:209], s[26:27], 0, v[134:135]
	s_add_i32 m0, s33, 0x2000
	s_nop 0
	global_load_lds_dwordx4 v[208:209], off
	v_lshl_add_u64 v[208:209], v[226:227], 0, s[12:13]
	s_mov_b32 m0, s66
	s_nop 0
	global_load_lds_dwordx4 v[208:209], off
	v_lshl_add_u64 v[208:209], v[228:229], 0, s[12:13]
	s_mov_b32 m0, s67
	s_nop 0
	global_load_lds_dwordx4 v[208:209], off
	s_waitcnt vmcnt(8)
	s_waitcnt lgkmcnt(0)
	s_barrier
	s_waitcnt lgkmcnt(0)
	v_mfma_f32_16x16x32_bf16 v[60:63], v[156:159], v[188:191], v[60:63]
	v_mfma_f32_16x16x32_bf16 v[56:59], v[164:167], v[188:191], v[56:59]
	v_mfma_f32_16x16x32_bf16 v[44:47], v[156:159], v[196:199], v[44:47]
	v_mfma_f32_16x16x32_bf16 v[40:43], v[164:167], v[196:199], v[40:43]
	v_mfma_f32_16x16x32_bf16 v[28:31], v[156:159], v[204:207], v[28:31]
	v_mfma_f32_16x16x32_bf16 v[24:27], v[164:167], v[204:207], v[24:27]
	v_mfma_f32_16x16x32_bf16 v[12:15], v[156:159], v[216:219], v[12:15]
	v_mfma_f32_16x16x32_bf16 v[8:11], v[164:167], v[216:219], v[8:11]
	v_mfma_f32_16x16x32_bf16 v[60:63], v[160:163], v[192:195], v[60:63]
	v_mfma_f32_16x16x32_bf16 v[56:59], v[168:171], v[192:195], v[56:59]
	v_mfma_f32_16x16x32_bf16 v[44:47], v[160:163], v[200:203], v[44:47]
	v_mfma_f32_16x16x32_bf16 v[40:43], v[168:171], v[200:203], v[40:43]
	v_mfma_f32_16x16x32_bf16 v[28:31], v[160:163], v[212:215], v[28:31]
	v_mfma_f32_16x16x32_bf16 v[24:27], v[168:171], v[212:215], v[24:27]
	v_mfma_f32_16x16x32_bf16 v[12:15], v[160:163], v[220:223], v[12:15]
	v_mfma_f32_16x16x32_bf16 v[8:11], v[168:171], v[220:223], v[8:11]
	v_mfma_f32_16x16x32_bf16 v[52:55], v[172:175], v[188:191], v[52:55]
	v_mfma_f32_16x16x32_bf16 v[48:51], v[180:183], v[188:191], v[48:51]
	v_mfma_f32_16x16x32_bf16 v[36:39], v[172:175], v[196:199], v[36:39]
	v_mfma_f32_16x16x32_bf16 v[32:35], v[180:183], v[196:199], v[32:35]
	v_mfma_f32_16x16x32_bf16 v[20:23], v[172:175], v[204:207], v[20:23]
	v_mfma_f32_16x16x32_bf16 v[16:19], v[180:183], v[204:207], v[16:19]
	v_mfma_f32_16x16x32_bf16 v[4:7], v[172:175], v[216:219], v[4:7]
	v_mfma_f32_16x16x32_bf16 v[0:3], v[180:183], v[216:219], v[0:3]
	v_mfma_f32_16x16x32_bf16 v[52:55], v[176:179], v[192:195], v[52:55]
	v_mfma_f32_16x16x32_bf16 v[48:51], v[184:187], v[192:195], v[48:51]
	v_mfma_f32_16x16x32_bf16 v[36:39], v[176:179], v[200:203], v[36:39]
	v_mfma_f32_16x16x32_bf16 v[32:35], v[184:187], v[200:203], v[32:35]
	v_mfma_f32_16x16x32_bf16 v[20:23], v[176:179], v[212:215], v[20:23]
	v_mfma_f32_16x16x32_bf16 v[16:19], v[184:187], v[212:215], v[16:19]
	v_mfma_f32_16x16x32_bf16 v[4:7], v[176:179], v[220:223], v[4:7]
	v_mfma_f32_16x16x32_bf16 v[0:3], v[184:187], v[220:223], v[0:3]
	s_barrier
	s_add_i32 s76, s76, 2
	s_add_u32 s52, s52, 0x100
	s_addc_u32 s53, s53, 0
	s_add_u32 s74, s74, 0x100
	s_addc_u32 s75, s75, 0
	s_cmp_gt_u32 s76, 29
	s_cbranch_scc0 .LBB0_394
	s_and_b64 vcc, exec, s[14:15]
	s_cbranch_vccz .LBB0_397
	s_barrier

;     __host__ __device__ bool next(int i, Unit& u) const {
;         const long L = (long)i * G + c; if (L >= nwg) return false;
;         int wgid = (int)L; { const int q = nwg / NXCD, r = nwg % NXCD, xcd = wgid % NXCD, off = wgid / NXCD; wgid = (xcd < r ? xcd * (q + 1) : r * (q + 1) + (xcd - r) * q) + off; }
;         const int nig = wgm * nN, gid = wgid / nig, fm = gid * wgm, gsz = (nM - fm) < wgm ? (nM - fm) : wgm;
;         u.pm = fm + ((wgid % nig) % gsz); u.pn = (wgid % nig) / gsz; return true;
.LBB0_453:
	s_or_b64 exec, exec, s[8:9]
	s_waitcnt lgkmcnt(0)
	s_setprio 0
	v_mov_b32_e32 v0, v252
	s_barrier
	s_and_b64 vcc, exec, s[6:7]
	v_add_u32_e32 v8, s81, v0
	s_nop 0
	v_readfirstlane_b32 s10, v8
	s_cbranch_vccnz .LBB0_459
	s_lshr_b32 s8, s3, 29
	s_add_i32 s11, s2, s8
	s_and_b32 s8, s11, -8
	s_sub_i32 s12, s2, s8
	s_cmp_gt_i32 s12, -1
	s_cbranch_scc0 .LBB0_456
	s_lshl_b32 s13, s12, 7
	s_cbranch_execz .LBB0_457
	s_branch .LBB0_458

; #define PG8_STAGE(bufoff, gbase, voff) do { _Pragma("unroll") for (int _i = 0; _i < 2; ++_i) \
;         __builtin_amdgcn_global_load_lds((const unsigned*)((const char*)(gbase) + (voff)[_i]), (PG8_LAS unsigned*)(lds + (bufoff) + ldsw + _i * 8192), 16, 0, 0); } while (0)
; #define PG8_WAIT_V(n) asm volatile("s_waitcnt vmcnt(" #n ")" ::: "memory")
; #define PG8_BAR __builtin_amdgcn_s_barrier()
; template <class Epi, class Sched, bool ALIGN_EPI = false, bool SP2 = false>
; __device__ __forceinline__ void gemm_phase(PG8_LAS unsigned char* lds, const Gemm g, const Sched& S, const Epi& E, int tid_in) {
;     int tid_ = tid_in; asm volatile("" : "+v"(tid_)); const int tid = tid_, wid = __builtin_amdgcn_readfirstlane(tid >> 6), lane = tid & 63, wr = wid >> 2, wc = wid & 3, fr = lane & 15, fq = lane >> 4;
;     const int K = g.K, nt = K / BK;
;     unsigned voffA[2], voffB[2];
; #pragma unroll
;     for (int i = 0; i < 2; ++i) { int R, C; stage_rc(tid * 16 + i * 8192, R, C); const int Rb = 2 * (R & ~31) + (Epi::PERM ? perm32(R & 31) : (R & 31));
;         voffA[i] = (unsigned)(R * g.lda + C) * 2u; voffB[i] = (unsigned)(Rb * K + C) * 2u; }
;     const size_t kstep = (size_t)(BK * 2);
;     const size_t hstep = (size_t)HALF * g.lda * 2;
;     const size_t hstepB = (size_t)32 * K * 2;
;     const size_t tstep = 2 * hstep, tstepB = (size_t)BM * K * 2;
;     const unsigned ldsw = (unsigned)wid * 1024u;
;     const int aoff = lds_byte(wr * 64 + fr, fq * 8), boff = lds_byte(wc * 32 + fr, fq * 8);
;     ...
;     Unit cur, nxt; int ui = 0;
;     if (!S.next(0, cur)) return;
;     f32x4 acc[2][2][4][2];
; #pragma unroll
;     for (int a = 0; a < 2; ++a)
; #pragma unroll
;         for (int b = 0; b < 2; ++b)
; #pragma unroll
;             for (int m = 0; m < 4; ++m)
; #pragma unroll
;                 for (int n = 0; n < 2; ++n) acc[a][b][m][n] = (f32x4){0.f, 0.f, 0.f, 0.f};
;     bf16x8 At[4][2], B0[2][2], B1[2][2];
;     const char* cA = (const char*)g.A + (size_t)cur.pm * tstep; const char* cB = (const char*)g.Bt + (size_t)cur.pn * tstepB;
;     S.a_ready(cur);
;     if constexpr (SP2) {
;         PG8_STAGE(PG8_SB(0, 0), cB, voffB); PG8_STAGE(PG8_SB(0, 1), cB + hstepB, voffB); PG8_STAGE(PG8_SA(0, 0), cA, voffA); PG8_STAGE(PG8_SA(0, 1), cA + hstep, voffA);
;         if (wr == 1) PG8_BAR;
;         PG8_WAIT_V(2); PG8_BAR;
.LBB0_459:
	s_add_u32 s44, s18, 0x80000
	s_addc_u32 s45, s19, 0
	s_and_b64 vcc, exec, s[6:7]
	s_cbranch_vccnz .LBB0_497
	v_ashrrev_i32_e32 v1, 31, v8
	v_lshrrev_b32_e32 v1, 26, v1
	v_add_u32_e32 v1, v8, v1
	v_ashrrev_i32_e32 v9, 6, v1
	v_bfe_i32 v1, v8, 27, 1
	v_lshlrev_b32_e32 v0, 4, v8
	v_lshrrev_b32_e32 v1, 22, v1
	v_add_u32_e32 v1, v0, v1
	v_and_b32_e32 v1, 0xfffffc00, v1
	v_sub_u32_e32 v1, v0, v1
	v_lshrrev_b32_e32 v2, 4, v1
	v_bitop3_b32 v1, v2, v1, 32 bitop3:0x6c
	v_ashrrev_i32_e32 v3, 31, v1
	v_lshrrev_b32_e32 v3, 26, v3
	v_add_u32_e32 v3, v1, v3
	v_ashrrev_i32_e32 v11, 6, v3
	v_and_b32_e32 v3, 0xc0, v3
	v_lshlrev_b32_e32 v2, 3, v9
	v_sub_u32_e32 v1, v1, v3
	v_mov_b32_e32 v3, 1
	v_and_b32_e32 v2, -16, v2
	v_lshlrev_b32_e32 v4, 5, v9
	v_ashrrev_i16_sdwa v1, v3, sext(v1) dst_sel:DWORD dst_unused:UNUSED_PAD src0_sel:DWORD src1_sel:BYTE_0
	v_add_u32_e32 v2, v11, v2
	v_and_b32_e32 v10, 32, v4
	v_bfe_i32 v12, v1, 0, 16
	s_movk_i32 s11, 0x2040
	v_add_u32_e32 v1, v10, v12
	v_lshlrev_b32_e32 v4, 1, v2
	v_and_b32_e32 v5, 31, v2
	s_mov_b32 s9, 0x3ffc0
	v_mul_lo_u32 v2, v2, s11
	v_and_or_b32 v4, v4, s9, v5
	v_add_lshl_u32 v128, v1, v2, 1
	v_lshlrev_b32_e32 v1, 1, v1
	v_add_u32_e32 v0, 0x2000, v0
	v_lshl_add_u32 v130, v4, 14, v1
	v_ashrrev_i32_e32 v1, 31, v0
	v_lshrrev_b32_e32 v1, 22, v1
	v_add_u32_e32 v1, v0, v1
	v_ashrrev_i32_e32 v13, 10, v1
	v_mul_i32_i24_e32 v1, 0x400, v13
	v_sub_u32_e32 v0, v0, v1
	v_lshrrev_b32_e32 v1, 4, v0
	v_bitop3_b32 v0, v1, v0, 32 bitop3:0x6c
	v_ashrrev_i32_e32 v2, 31, v0
	v_lshrrev_b32_e32 v2, 26, v2
	v_lshlrev_b32_e32 v1, 3, v13
	v_add_u32_e32 v2, v0, v2
	v_and_b32_e32 v1, -16, v1
	v_ashrrev_i32_e32 v14, 6, v2
	v_and_b32_e32 v2, 0xc0, v2
	s_add_u32 s62, s18, 0x4400000
	v_add_u32_e32 v1, v14, v1
	v_sub_u32_e32 v0, v0, v2
	s_addc_u32 s63, s19, 0
	s_ashr_i32 s8, s10, 6
	v_ashrrev_i16_sdwa v0, v3, sext(v0) dst_sel:DWORD dst_unused:UNUSED_PAD src0_sel:DWORD src1_sel:BYTE_0
	v_lshlrev_b32_e32 v2, 1, v1
	v_and_b32_e32 v3, 31, v1
	s_ashr_i32 s55, s54, 31
	v_and_or_b32 v2, v2, s9, v3
	s_ashr_i32 s9, s10, 8
	s_lshl_b32 s64, s8, 10
	s_lshl_b64 s[12:13], s[54:55], 22
	v_lshlrev_b32_e32 v4, 5, v13
	s_add_u32 s58, s62, s12
	v_and_b32_e32 v15, 32, v4
	v_bfe_i32 v16, v0, 0, 16
	s_addc_u32 s59, s63, s13
	s_add_i32 s55, s64, 0
	v_add_u32_e32 v0, v15, v16
	v_mul_lo_u32 v1, v1, s11
	s_add_i32 m0, s55, 0x10000
	v_add_lshl_u32 v132, v0, v1, 1
	v_lshlrev_b32_e32 v0, 1, v0
	global_load_lds_dwordx4 v130, s[58:59]
	s_add_i32 m0, s55, 0x12000
	v_lshl_add_u32 v134, v2, 14, v0
	s_add_u32 s12, s58, 0x80000
	global_load_lds_dwordx4 v134, s[58:59]
	s_addc_u32 s13, s59, 0
	s_add_i32 m0, s55, 0x14000
	s_mul_i32 s15, s74, 0x408000
	global_load_lds_dwordx4 v130, s[12:13]
	s_add_i32 m0, s55, 0x16000
	s_mul_hi_i32 s14, s74, 0x408000
	s_add_u32 s56, s34, s15
	s_addc_u32 s57, s35, s14
	s_add_i32 s65, s55, 0x2000
	global_load_lds_dwordx4 v134, s[12:13]
	s_mov_b32 m0, s55
	s_add_u32 s12, s56, 0x204000
	global_load_lds_dwordx4 v128, s[56:57]
	s_mov_b32 m0, s65
	s_addc_u32 s13, s57, 0
	s_add_i32 s66, s55, 0x4000
	global_load_lds_dwordx4 v132, s[56:57]
	s_mov_b32 m0, s66
	s_add_i32 s67, s55, 0x6000
	global_load_lds_dwordx4 v128, s[12:13]
	s_mov_b32 m0, s67
	v_mov_b32_e32 v131, 0
	global_load_lds_dwordx4 v132, s[12:13]
	v_mov_b32_e32 v135, v131
	v_mov_b32_e32 v129, v131
	v_mov_b32_e32 v133, v131
	s_cmp_eq_u32 s9, 1
	s_mov_b32 s68, 0
	v_lshl_add_u64 v[6:7], s[58:59], 0, v[130:131]
	v_lshl_add_u64 v[4:5], s[58:59], 0, v[134:135]
	v_lshl_add_u64 v[0:1], s[56:57], 0, v[128:129]
	s_cselect_b64 s[14:15], -1, 0
	s_cmp_lg_u32 s9, 1
	v_lshl_add_u64 v[2:3], s[56:57], 0, v[132:133]
	s_cbranch_scc1 .LBB0_462
	s_barrier
	s_setprio 1

; #define PG8_STAGE(bufoff, gbase, voff) do { _Pragma("unroll") for (int _i = 0; _i < 2; ++_i) \
;         __builtin_amdgcn_global_load_lds((const unsigned*)((const char*)(gbase) + (voff)[_i]), (PG8_LAS unsigned*)(lds + (bufoff) + ldsw + _i * 8192), 16, 0, 0); } while (0)
; #define PG8_LDA(dst, b, h) do { _Pragma("unroll") for (int m = 0; m < 4; ++m) _Pragma("unroll") for (int k = 0; k < 2; ++k) dst[m][k] = *(const PG8_LAS bf16x8*)(lds + PG8_SA(b, h) + aoff + m * 2048 + k * 1024); } while (0)
; #define PG8_LDB(dst, b, h) do { _Pragma("unroll") for (int n = 0; n < 2; ++n) _Pragma("unroll") for (int k = 0; k < 2; ++k) dst[n][k] = *(const PG8_LAS bf16x8*)(lds + PG8_SB(b, h) + boff + n * 2048 + k * 1024); } while (0)
; #define PG8_MMA(ai, bj, At, Bt) do { __builtin_amdgcn_s_setprio(1); _Pragma("unroll") for (int m = 0; m < 4; ++m) _Pragma("unroll") for (int n = 0; n < 2; ++n) _Pragma("unroll") for (int k = 0; k < 2; ++k) \
;         acc[ai][bj][m][n] = __builtin_amdgcn_mfma_f32_16x16x32_bf16(Bt[n][k], At[m][k], acc[ai][bj][m][n], 0, 0, 0); __builtin_amdgcn_s_setprio(0); } while (0)
; #define PG8_WAIT_V(n) asm volatile("s_waitcnt vmcnt(" #n ")" ::: "memory")
; #define PG8_WAIT_L(n) asm volatile("s_waitcnt lgkmcnt(" #n ")" ::: "memory")
; #define PG8_BAR __builtin_amdgcn_s_barrier()
; #define PG8_SCHED __builtin_amdgcn_sched_barrier(0)
; template <class Epi, class Sched, bool ALIGN_EPI = false, bool SP2 = false>
; __device__ __forceinline__ void gemm_phase(PG8_LAS unsigned char* lds, const Gemm g, const Sched& S, const Epi& E, int tid_in) {
;     ...
;             PG8_LDB(B0, 0, 0); PG8_LDB(B1, 0, 1); PG8_SCHED; PG8_LDA(At, 0, 0); PG8_STAGE(PG8_SA(1, 1), a1 + hstep, voffA);
;             PG8_WAIT_V(8); PG8_WAIT_L(0); PG8_BAR; PG8_MMA(0, 0, At, B0); PG8_MMA(0, 1, At, B1); PG8_BAR; PG8_SCHED;
;             PG8_LDA(At, 0, 1); PG8_STAGE(PG8_SB(0, 0), b2, voffB); PG8_STAGE(PG8_SB(0, 1), b2 + hstepB, voffB); PG8_STAGE(PG8_SA(0, 0), a2, voffA);
;             PG8_WAIT_V(8); PG8_WAIT_L(0); PG8_BAR; PG8_MMA(1, 0, At, B0); PG8_MMA(1, 1, At, B1); PG8_BAR; PG8_SCHED;
.Lkb_skip_3:
.LBB0_474:
	ds_read_b128 v[146:149], v153
	ds_read_b128 v[158:161], v153 offset:1024
	ds_read_b128 v[162:165], v153 offset:2048
	ds_read_b128 v[166:169], v153 offset:3072
	ds_read_b128 v[170:173], v154
	ds_read_b128 v[174:177], v154 offset:1024
	ds_read_b128 v[178:181], v154 offset:2048
	ds_read_b128 v[182:185], v154 offset:3072
	s_add_u32 s12, s56, 0x100
	s_addc_u32 s13, s57, 0
	s_cmpk_eq_i32 s79, 0x7c
	s_cselect_b32 s61, s51, s13
	s_cselect_b32 s60, s50, s12
	s_cselect_b32 s59, s49, s77
	s_cselect_b32 s58, s75, s76
	v_lshl_add_u64 v[220:221], s[56:57], 0, v[138:139]
	s_add_i32 m0, s55, 0xc000
	ds_read_b128 v[186:189], v155
	ds_read_b128 v[190:193], v155 offset:1024
	ds_read_b128 v[194:197], v155 offset:2048
	ds_read_b128 v[198:201], v155 offset:3072
	ds_read_b128 v[202:205], v155 offset:4096
	ds_read_b128 v[206:209], v155 offset:5120
	ds_read_b128 v[212:215], v155 offset:6144
	ds_read_b128 v[216:219], v155 offset:7168
	global_load_lds_dwordx4 v[220:221], off
	v_lshl_add_u64 v[220:221], s[56:57], 0, v[140:141]
	s_add_i32 m0, s55, 0xe000
	s_nop 0
	global_load_lds_dwordx4 v[220:221], off
	s_waitcnt vmcnt(8)
	s_waitcnt lgkmcnt(0)
	s_barrier
	s_waitcnt lgkmcnt(0)
	v_mfma_f32_16x16x32_bf16 v[124:127], v[146:149], v[186:189], v[124:127]
	v_mfma_f32_16x16x32_bf16 v[120:123], v[162:165], v[186:189], v[120:123]
	v_mfma_f32_16x16x32_bf16 v[108:111], v[146:149], v[194:197], v[108:111]
	v_mfma_f32_16x16x32_bf16 v[104:107], v[162:165], v[194:197], v[104:107]
	v_mfma_f32_16x16x32_bf16 v[92:95], v[146:149], v[202:205], v[92:95]
	v_mfma_f32_16x16x32_bf16 v[88:91], v[162:165], v[202:205], v[88:91]
	v_mfma_f32_16x16x32_bf16 v[76:79], v[146:149], v[212:215], v[76:79]
	v_mfma_f32_16x16x32_bf16 v[72:75], v[162:165], v[212:215], v[72:75]
	v_mfma_f32_16x16x32_bf16 v[124:127], v[158:161], v[190:193], v[124:127]
	v_mfma_f32_16x16x32_bf16 v[120:123], v[166:169], v[190:193], v[120:123]
	v_mfma_f32_16x16x32_bf16 v[108:111], v[158:161], v[198:201], v[108:111]
	v_mfma_f32_16x16x32_bf16 v[104:107], v[166:169], v[198:201], v[104:107]
	v_mfma_f32_16x16x32_bf16 v[92:95], v[158:161], v[206:209], v[92:95]
	v_mfma_f32_16x16x32_bf16 v[88:91], v[166:169], v[206:209], v[88:91]
	v_mfma_f32_16x16x32_bf16 v[76:79], v[158:161], v[216:219], v[76:79]
	v_mfma_f32_16x16x32_bf16 v[72:75], v[166:169], v[216:219], v[72:75]
	v_mfma_f32_16x16x32_bf16 v[116:119], v[170:173], v[186:189], v[116:119]
	v_mfma_f32_16x16x32_bf16 v[112:115], v[178:181], v[186:189], v[112:115]
	v_mfma_f32_16x16x32_bf16 v[100:103], v[170:173], v[194:197], v[100:103]
	v_mfma_f32_16x16x32_bf16 v[96:99], v[178:181], v[194:197], v[96:99]
	v_mfma_f32_16x16x32_bf16 v[84:87], v[170:173], v[202:205], v[84:87]
	v_mfma_f32_16x16x32_bf16 v[80:83], v[178:181], v[202:205], v[80:83]
	v_mfma_f32_16x16x32_bf16 v[68:71], v[170:173], v[212:215], v[68:71]
	v_mfma_f32_16x16x32_bf16 v[64:67], v[178:181], v[212:215], v[64:67]
	v_mfma_f32_16x16x32_bf16 v[116:119], v[174:177], v[190:193], v[116:119]
	v_mfma_f32_16x16x32_bf16 v[112:115], v[182:185], v[190:193], v[112:115]
	v_mfma_f32_16x16x32_bf16 v[100:103], v[174:177], v[198:201], v[100:103]
	v_mfma_f32_16x16x32_bf16 v[96:99], v[182:185], v[198:201], v[96:99]
	v_mfma_f32_16x16x32_bf16 v[84:87], v[174:177], v[206:209], v[84:87]
	v_mfma_f32_16x16x32_bf16 v[80:83], v[182:185], v[206:209], v[80:83]
	v_mfma_f32_16x16x32_bf16 v[68:71], v[174:177], v[216:219], v[68:71]
	v_mfma_f32_16x16x32_bf16 v[64:67], v[182:185], v[216:219], v[64:67]
	s_barrier
	s_add_i32 s26, s71, s64
	v_lshl_add_u64 v[220:221], s[58:59], 0, v[130:131]
	s_mov_b32 m0, s26
	ds_read_b128 v[186:189], v155 offset:16384
	ds_read_b128 v[190:193], v155 offset:17408
	ds_read_b128 v[194:197], v155 offset:18432
	ds_read_b128 v[198:201], v155 offset:19456
	ds_read_b128 v[202:205], v155 offset:20480
	ds_read_b128 v[206:209], v155 offset:21504
	ds_read_b128 v[212:215], v155 offset:22528
	ds_read_b128 v[216:219], v155 offset:23552
	global_load_lds_dwordx4 v[220:221], off
	s_add_i32 m0, s26, 0x2000
	s_add_u32 s26, s58, 0x80000
	v_lshl_add_u64 v[222:223], s[58:59], 0, v[134:135]
	s_addc_u32 s27, s59, 0
	s_add_i32 s33, s72, s64
	global_load_lds_dwordx4 v[222:223], off
	v_lshl_add_u64 v[224:225], s[26:27], 0, v[130:131]
	s_mov_b32 m0, s33
	v_lshl_add_u64 v[226:227], s[60:61], 0, v[132:133]
	global_load_lds_dwordx4 v[224:225], off
	v_lshl_add_u64 v[224:225], s[26:27], 0, v[134:135]
	s_add_i32 m0, s33, 0x2000
	s_nop 0
	global_load_lds_dwordx4 v[224:225], off
	v_lshl_add_u64 v[224:225], s[60:61], 0, v[128:129]
	s_mov_b32 m0, s55
	s_nop 0
	global_load_lds_dwordx4 v[224:225], off
	s_mov_b32 m0, s65
	s_nop 0
	global_load_lds_dwordx4 v[226:227], off
	s_waitcnt vmcnt(8)
	s_waitcnt lgkmcnt(0)
	s_barrier
; #define PG8_STAGE(bufoff, gbase, voff) do { _Pragma("unroll") for (int _i = 0; _i < 2; ++_i) \
;         __builtin_amdgcn_global_load_lds((const unsigned*)((const char*)(gbase) + (voff)[_i]), (PG8_LAS unsigned*)(lds + (bufoff) + ldsw + _i * 8192), 16, 0, 0); } while (0)
; #define PG8_LDA(dst, b, h) do { _Pragma("unroll") for (int m = 0; m < 4; ++m) _Pragma("unroll") for (int k = 0; k < 2; ++k) dst[m][k] = *(const PG8_LAS bf16x8*)(lds + PG8_SA(b, h) + aoff + m * 2048 + k * 1024); } while (0)
; #define PG8_LDB(dst, b, h) do { _Pragma("unroll") for (int n = 0; n < 2; ++n) _Pragma("unroll") for (int k = 0; k < 2; ++k) dst[n][k] = *(const PG8_LAS bf16x8*)(lds + PG8_SB(b, h) + boff + n * 2048 + k * 1024); } while (0)
; #define PG8_MMA(ai, bj, At, Bt) do { __builtin_amdgcn_s_setprio(1); _Pragma("unroll") for (int m = 0; m < 4; ++m) _Pragma("unroll") for (int n = 0; n < 2; ++n) _Pragma("unroll") for (int k = 0; k < 2; ++k) \
;         acc[ai][bj][m][n] = __builtin_amdgcn_mfma_f32_16x16x32_bf16(Bt[n][k], At[m][k], acc[ai][bj][m][n], 0, 0, 0); __builtin_amdgcn_s_setprio(0); } while (0)
; #define PG8_WAIT_V(n) asm volatile("s_waitcnt vmcnt(" #n ")" ::: "memory")
; #define PG8_WAIT_L(n) asm volatile("s_waitcnt lgkmcnt(" #n ")" ::: "memory")
; #define PG8_BAR __builtin_amdgcn_s_barrier()
; #define PG8_SCHED __builtin_amdgcn_sched_barrier(0)
; template <class Epi, class Sched, bool ALIGN_EPI = false, bool SP2 = false>
; __device__ __forceinline__ void gemm_phase(PG8_LAS unsigned char* lds, const Gemm g, const Sched& S, const Epi& E, int tid_in) {
;     ...
;             PG8_WAIT_V(8); PG8_WAIT_L(0); PG8_BAR; PG8_MMA(1, 0, At, B0); PG8_MMA(1, 1, At, B1); PG8_BAR; PG8_SCHED;
;             PG8_LDB(B0, 1, 0); PG8_LDB(B1, 1, 1); PG8_SCHED; PG8_LDA(At, 1, 0); PG8_STAGE(PG8_SA(0, 1), a2 + hstep, voffA);
;             PG8_WAIT_V(8); PG8_WAIT_L(0); PG8_BAR; PG8_MMA(0, 0, At, B0); PG8_MMA(0, 1, At, B1); PG8_BAR; PG8_SCHED;
	s_waitcnt lgkmcnt(0)
	v_mfma_f32_16x16x32_bf16 v[60:63], v[146:149], v[186:189], v[60:63]
	v_mfma_f32_16x16x32_bf16 v[56:59], v[162:165], v[186:189], v[56:59]
	v_mfma_f32_16x16x32_bf16 v[44:47], v[146:149], v[194:197], v[44:47]
	v_mfma_f32_16x16x32_bf16 v[40:43], v[162:165], v[194:197], v[40:43]
	v_mfma_f32_16x16x32_bf16 v[28:31], v[146:149], v[202:205], v[28:31]
	v_mfma_f32_16x16x32_bf16 v[24:27], v[162:165], v[202:205], v[24:27]
	v_mfma_f32_16x16x32_bf16 v[12:15], v[146:149], v[212:215], v[12:15]
	v_mfma_f32_16x16x32_bf16 v[8:11], v[162:165], v[212:215], v[8:11]
	v_mfma_f32_16x16x32_bf16 v[60:63], v[158:161], v[190:193], v[60:63]
	v_mfma_f32_16x16x32_bf16 v[56:59], v[166:169], v[190:193], v[56:59]
	v_mfma_f32_16x16x32_bf16 v[44:47], v[158:161], v[198:201], v[44:47]
	v_mfma_f32_16x16x32_bf16 v[40:43], v[166:169], v[198:201], v[40:43]
	v_mfma_f32_16x16x32_bf16 v[28:31], v[158:161], v[206:209], v[28:31]
	v_mfma_f32_16x16x32_bf16 v[24:27], v[166:169], v[206:209], v[24:27]
	v_mfma_f32_16x16x32_bf16 v[12:15], v[158:161], v[216:219], v[12:15]
	v_mfma_f32_16x16x32_bf16 v[8:11], v[166:169], v[216:219], v[8:11]
	v_mfma_f32_16x16x32_bf16 v[52:55], v[170:173], v[186:189], v[52:55]
	v_mfma_f32_16x16x32_bf16 v[48:51], v[178:181], v[186:189], v[48:51]
	v_mfma_f32_16x16x32_bf16 v[36:39], v[170:173], v[194:197], v[36:39]
	v_mfma_f32_16x16x32_bf16 v[32:35], v[178:181], v[194:197], v[32:35]
	v_mfma_f32_16x16x32_bf16 v[20:23], v[170:173], v[202:205], v[20:23]
	v_mfma_f32_16x16x32_bf16 v[16:19], v[178:181], v[202:205], v[16:19]
	v_mfma_f32_16x16x32_bf16 v[4:7], v[170:173], v[212:215], v[4:7]
	v_mfma_f32_16x16x32_bf16 v[0:3], v[178:181], v[212:215], v[0:3]
	v_mfma_f32_16x16x32_bf16 v[52:55], v[174:177], v[190:193], v[52:55]
	v_mfma_f32_16x16x32_bf16 v[48:51], v[182:185], v[190:193], v[48:51]
	v_mfma_f32_16x16x32_bf16 v[36:39], v[174:177], v[198:201], v[36:39]
	v_mfma_f32_16x16x32_bf16 v[32:35], v[182:185], v[198:201], v[32:35]
	v_mfma_f32_16x16x32_bf16 v[20:23], v[174:177], v[206:209], v[20:23]
	v_mfma_f32_16x16x32_bf16 v[16:19], v[182:185], v[206:209], v[16:19]
	v_mfma_f32_16x16x32_bf16 v[4:7], v[174:177], v[216:219], v[4:7]
	v_mfma_f32_16x16x32_bf16 v[0:3], v[182:185], v[216:219], v[0:3]
	s_barrier
	s_add_i32 s33, 0, 0x18000
	s_add_i32 s56, 0, 0x1c000
	v_add_u32_e32 v166, s33, v137
	v_add_u32_e32 v182, s56, v137
	ds_read_b128 v[146:149], v166
	ds_read_b128 v[158:161], v166 offset:1024
	ds_read_b128 v[162:165], v166 offset:2048
	ds_read_b128 v[166:169], v166 offset:3072
	ds_read_b128 v[170:173], v182
	ds_read_b128 v[174:177], v182 offset:1024
	ds_read_b128 v[178:181], v182 offset:2048
	ds_read_b128 v[182:185], v182 offset:3072
	s_add_u32 s26, s60, 0x204000
	s_addc_u32 s27, s61, 0
	s_mov_b32 m0, s66
	v_lshl_add_u64 v[228:229], s[26:27], 0, v[128:129]
	ds_read_b128 v[186:189], v155 offset:32768
	ds_read_b128 v[190:193], v155 offset:33792
	ds_read_b128 v[194:197], v155 offset:34816
	ds_read_b128 v[198:201], v155 offset:35840
	ds_read_b128 v[202:205], v155 offset:36864
	ds_read_b128 v[206:209], v155 offset:37888
	ds_read_b128 v[212:215], v155 offset:38912
	ds_read_b128 v[216:219], v155 offset:39936
	global_load_lds_dwordx4 v[228:229], off
	v_lshl_add_u64 v[228:229], s[26:27], 0, v[132:133]
	s_mov_b32 m0, s67
	s_nop 0
	global_load_lds_dwordx4 v[228:229], off
	s_waitcnt vmcnt(8)
	s_waitcnt lgkmcnt(0)
	s_barrier
	s_waitcnt lgkmcnt(0)
	v_mfma_f32_16x16x32_bf16 v[124:127], v[146:149], v[186:189], v[124:127]
	v_mfma_f32_16x16x32_bf16 v[120:123], v[162:165], v[186:189], v[120:123]
	v_mfma_f32_16x16x32_bf16 v[108:111], v[146:149], v[194:197], v[108:111]
	v_mfma_f32_16x16x32_bf16 v[104:107], v[162:165], v[194:197], v[104:107]
	v_mfma_f32_16x16x32_bf16 v[92:95], v[146:149], v[202:205], v[92:95]
	v_mfma_f32_16x16x32_bf16 v[88:91], v[162:165], v[202:205], v[88:91]
	v_mfma_f32_16x16x32_bf16 v[76:79], v[146:149], v[212:215], v[76:79]
	v_mfma_f32_16x16x32_bf16 v[72:75], v[162:165], v[212:215], v[72:75]
	v_mfma_f32_16x16x32_bf16 v[124:127], v[158:161], v[190:193], v[124:127]
	v_mfma_f32_16x16x32_bf16 v[120:123], v[166:169], v[190:193], v[120:123]
	v_mfma_f32_16x16x32_bf16 v[108:111], v[158:161], v[198:201], v[108:111]
	v_mfma_f32_16x16x32_bf16 v[104:107], v[166:169], v[198:201], v[104:107]
	v_mfma_f32_16x16x32_bf16 v[92:95], v[158:161], v[206:209], v[92:95]
	v_mfma_f32_16x16x32_bf16 v[88:91], v[166:169], v[206:209], v[88:91]
	v_mfma_f32_16x16x32_bf16 v[76:79], v[158:161], v[216:219], v[76:79]
	v_mfma_f32_16x16x32_bf16 v[72:75], v[166:169], v[216:219], v[72:75]
	v_mfma_f32_16x16x32_bf16 v[116:119], v[170:173], v[186:189], v[116:119]
	v_mfma_f32_16x16x32_bf16 v[112:115], v[178:181], v[186:189], v[112:115]
	v_mfma_f32_16x16x32_bf16 v[100:103], v[170:173], v[194:197], v[100:103]
	v_mfma_f32_16x16x32_bf16 v[96:99], v[178:181], v[194:197], v[96:99]
	v_mfma_f32_16x16x32_bf16 v[84:87], v[170:173], v[202:205], v[84:87]
	v_mfma_f32_16x16x32_bf16 v[80:83], v[178:181], v[202:205], v[80:83]
	v_mfma_f32_16x16x32_bf16 v[68:71], v[170:173], v[212:215], v[68:71]
	v_mfma_f32_16x16x32_bf16 v[64:67], v[178:181], v[212:215], v[64:67]
	v_mfma_f32_16x16x32_bf16 v[116:119], v[174:177], v[190:193], v[116:119]
	v_mfma_f32_16x16x32_bf16 v[112:115], v[182:185], v[190:193], v[112:115]
	v_mfma_f32_16x16x32_bf16 v[100:103], v[174:177], v[198:201], v[100:103]
	v_mfma_f32_16x16x32_bf16 v[96:99], v[182:185], v[198:201], v[96:99]
	v_mfma_f32_16x16x32_bf16 v[84:87], v[174:177], v[206:209], v[84:87]
	v_mfma_f32_16x16x32_bf16 v[80:83], v[182:185], v[206:209], v[80:83]
	v_mfma_f32_16x16x32_bf16 v[68:71], v[174:177], v[216:219], v[68:71]
	v_mfma_f32_16x16x32_bf16 v[64:67], v[182:185], v[216:219], v[64:67]
	s_barrier
; #define PG8_STAGE(bufoff, gbase, voff) do { _Pragma("unroll") for (int _i = 0; _i < 2; ++_i) \
;         __builtin_amdgcn_global_load_lds((const unsigned*)((const char*)(gbase) + (voff)[_i]), (PG8_LAS unsigned*)(lds + (bufoff) + ldsw + _i * 8192), 16, 0, 0); } while (0)
; #define PG8_LDA(dst, b, h) do { _Pragma("unroll") for (int m = 0; m < 4; ++m) _Pragma("unroll") for (int k = 0; k < 2; ++k) dst[m][k] = *(const PG8_LAS bf16x8*)(lds + PG8_SA(b, h) + aoff + m * 2048 + k * 1024); } while (0)
; #define PG8_MMA(ai, bj, At, Bt) do { __builtin_amdgcn_s_setprio(1); _Pragma("unroll") for (int m = 0; m < 4; ++m) _Pragma("unroll") for (int n = 0; n < 2; ++n) _Pragma("unroll") for (int k = 0; k < 2; ++k) \
;         acc[ai][bj][m][n] = __builtin_amdgcn_mfma_f32_16x16x32_bf16(Bt[n][k], At[m][k], acc[ai][bj][m][n], 0, 0, 0); __builtin_amdgcn_s_setprio(0); } while (0)
; #define PG8_WAIT_V(n) asm volatile("s_waitcnt vmcnt(" #n ")" ::: "memory")
; #define PG8_WAIT_L(n) asm volatile("s_waitcnt lgkmcnt(" #n ")" ::: "memory")
; #define PG8_BAR __builtin_amdgcn_s_barrier()
; template <class Epi, class Sched, bool ALIGN_EPI = false, bool SP2 = false>
; __device__ __forceinline__ void gemm_phase(PG8_LAS unsigned char* lds, const Gemm g, const Sched& S, const Epi& E, int tid_in) {
;     ...
;             PG8_LDA(At, 1, 1); PG8_STAGE(PG8_SB(1, 0), b3, voffB); PG8_STAGE(PG8_SB(1, 1), b3 + hstepB, voffB); PG8_STAGE(PG8_SA(1, 0), a3, voffA);
;             PG8_WAIT_V(8); PG8_WAIT_L(0); PG8_BAR; PG8_MMA(1, 0, At, B0); PG8_MMA(1, 1, At, B1); PG8_BAR; PG8_SCHED;
;     __device__ __forceinline__ void operator()(const f32x4 (&acc)[2][2][4][2], const Unit& u, int wr, int wc, int fr, int fq) const {
;     ...
;                     const size_t off = (size_t)row * 2048 + u.pn * BM + wc * 64 + bj * 32 + 8 * p;
;                     f32x4 b0, b1;
;                     if (BASE_F32) { b0 = *(const f32x4*)((const float*)base + off); b1 = *(const f32x4*)((const float*)base + off + 4); }
;                     else { const u32x4 bb = *(const u32x4*)((const bf16_t*)base + off);
;                         b0 = (f32x4){__uint_as_float(bb.x << 16), __uint_as_float(bb.x & 0xffff0000u), __uint_as_float(bb.y << 16), __uint_as_float(bb.y & 0xffff0000u)};
;                         b1 = (f32x4){__uint_as_float(bb.z << 16), __uint_as_float(bb.z & 0xffff0000u), __uint_as_float(bb.w << 16), __uint_as_float(bb.w & 0xffff0000u)}; }
	s_add_i32 s26, s33, s64
	v_lshl_add_u64 v[220:221], v[220:221], 0, s[42:43]
	s_mov_b32 m0, s26
	ds_read_b128 v[186:189], v155 offset:49152
	ds_read_b128 v[190:193], v155 offset:50176
	ds_read_b128 v[194:197], v155 offset:51200
	ds_read_b128 v[198:201], v155 offset:52224
	ds_read_b128 v[202:205], v155 offset:53248
	ds_read_b128 v[206:209], v155 offset:54272
	ds_read_b128 v[212:215], v155 offset:55296
	ds_read_b128 v[216:219], v155 offset:56320
	global_load_lds_dwordx4 v[220:221], off
	s_add_i32 m0, s26, 0x2000
	s_add_u32 s26, s58, 0x80080
	v_lshl_add_u64 v[220:221], v[222:223], 0, s[42:43]
	s_addc_u32 s27, s59, 0
	s_add_i32 s33, s56, s64
	global_load_lds_dwordx4 v[220:221], off
	v_lshl_add_u64 v[220:221], s[26:27], 0, v[130:131]
	s_mov_b32 m0, s33
	s_nop 0
	global_load_lds_dwordx4 v[220:221], off
	v_lshl_add_u64 v[220:221], s[26:27], 0, v[134:135]
	s_add_i32 m0, s33, 0x2000
	s_nop 0
	global_load_lds_dwordx4 v[220:221], off
	v_lshl_add_u64 v[220:221], v[224:225], 0, s[42:43]
	s_mov_b32 m0, s69
	s_nop 0
	global_load_lds_dwordx4 v[220:221], off
	v_lshl_add_u64 v[220:221], v[226:227], 0, s[42:43]
	s_mov_b32 m0, s70
	s_nop 0
	global_load_lds_dwordx4 v[220:221], off
	s_waitcnt vmcnt(8)
	s_waitcnt lgkmcnt(0)
	s_barrier
	s_waitcnt lgkmcnt(0)
	v_mfma_f32_16x16x32_bf16 v[60:63], v[146:149], v[186:189], v[60:63]
	v_mfma_f32_16x16x32_bf16 v[56:59], v[162:165], v[186:189], v[56:59]
	v_mfma_f32_16x16x32_bf16 v[44:47], v[146:149], v[194:197], v[44:47]
	v_mfma_f32_16x16x32_bf16 v[40:43], v[162:165], v[194:197], v[40:43]
	v_mfma_f32_16x16x32_bf16 v[28:31], v[146:149], v[202:205], v[28:31]
	v_mfma_f32_16x16x32_bf16 v[24:27], v[162:165], v[202:205], v[24:27]
	v_mfma_f32_16x16x32_bf16 v[12:15], v[146:149], v[212:215], v[12:15]
	v_mfma_f32_16x16x32_bf16 v[8:11], v[162:165], v[212:215], v[8:11]
	v_mfma_f32_16x16x32_bf16 v[60:63], v[158:161], v[190:193], v[60:63]
	v_mfma_f32_16x16x32_bf16 v[56:59], v[166:169], v[190:193], v[56:59]
	v_mfma_f32_16x16x32_bf16 v[44:47], v[158:161], v[198:201], v[44:47]
	v_mfma_f32_16x16x32_bf16 v[40:43], v[166:169], v[198:201], v[40:43]
	v_mfma_f32_16x16x32_bf16 v[28:31], v[158:161], v[206:209], v[28:31]
	v_mfma_f32_16x16x32_bf16 v[24:27], v[166:169], v[206:209], v[24:27]
	v_mfma_f32_16x16x32_bf16 v[12:15], v[158:161], v[216:219], v[12:15]
	v_mfma_f32_16x16x32_bf16 v[8:11], v[166:169], v[216:219], v[8:11]
	v_mfma_f32_16x16x32_bf16 v[52:55], v[170:173], v[186:189], v[52:55]
	v_mfma_f32_16x16x32_bf16 v[48:51], v[178:181], v[186:189], v[48:51]
	v_mfma_f32_16x16x32_bf16 v[36:39], v[170:173], v[194:197], v[36:39]
	v_mfma_f32_16x16x32_bf16 v[32:35], v[178:181], v[194:197], v[32:35]
	v_mfma_f32_16x16x32_bf16 v[20:23], v[170:173], v[202:205], v[20:23]
	v_mfma_f32_16x16x32_bf16 v[16:19], v[178:181], v[202:205], v[16:19]
	v_mfma_f32_16x16x32_bf16 v[4:7], v[170:173], v[212:215], v[4:7]
	v_mfma_f32_16x16x32_bf16 v[0:3], v[178:181], v[212:215], v[0:3]
	v_mfma_f32_16x16x32_bf16 v[52:55], v[174:177], v[190:193], v[52:55]
	v_mfma_f32_16x16x32_bf16 v[48:51], v[182:185], v[190:193], v[48:51]
	v_mfma_f32_16x16x32_bf16 v[36:39], v[174:177], v[198:201], v[36:39]
	v_mfma_f32_16x16x32_bf16 v[32:35], v[182:185], v[198:201], v[32:35]
	v_mfma_f32_16x16x32_bf16 v[20:23], v[174:177], v[206:209], v[20:23]
	v_mfma_f32_16x16x32_bf16 v[16:19], v[182:185], v[206:209], v[16:19]
	v_mfma_f32_16x16x32_bf16 v[4:7], v[174:177], v[216:219], v[4:7]
	v_mfma_f32_16x16x32_bf16 v[0:3], v[182:185], v[216:219], v[0:3]
	s_barrier
	s_add_i32 s79, s79, 2
	s_add_u32 s76, s76, 0x100
	s_addc_u32 s77, s77, 0
	s_cmpk_gt_u32 s79, 0x7d
	s_mov_b64 s[56:57], s[12:13]
	s_cbranch_scc0 .LBB0_474
	v_lshl_add_u32 v148, s74, 8, v150
	v_lshl_or_b32 v146, s54, 8, v136
	v_lshl_add_u32 v147, v148, 11, v146
	v_lshlrev_b32_e32 v159, 1, v147
	v_lshlrev_b32_e32 v208, 3, v148
	global_load_dwordx4 v[160:163], v159, s[38:39]
	global_load_dwordx4 v[164:167], v159, s[38:39] offset:64
	v_add_u32_e32 v149, 0x10000, v159
	global_load_dwordx4 v[168:171], v149, s[38:39]
	global_load_dwordx4 v[172:175], v149, s[38:39] offset:64
	v_add_u32_e32 v209, 0x20000, v159
	global_load_dwordx4 v[176:179], v209, s[38:39]
	global_load_dwordx4 v[180:183], v209, s[38:39] offset:64
	v_add_u32_e32 v149, 0x30000, v159
	global_load_dwordx4 v[184:187], v149, s[38:39]
	global_load_dwordx4 v[188:191], v149, s[38:39] offset:64
	v_add_u32_e32 v209, 0x80000, v159
	global_load_dwordx4 v[192:195], v209, s[38:39]
	global_load_dwordx4 v[196:199], v209, s[38:39] offset:64
	v_add_u32_e32 v149, 0x90000, v159
	global_load_dwordx4 v[200:203], v149, s[38:39]
	global_load_dwordx4 v[204:207], v149, s[38:39] offset:64
	v_add_u32_e32 v209, 0xa0000, v159
	global_load_dwordx4 v[212:215], v209, s[38:39]
	global_load_dwordx4 v[216:219], v209, s[38:39] offset:64
	v_add_u32_e32 v149, 0xb0000, v159
	global_load_dwordx4 v[220:223], v149, s[38:39]
	global_load_dwordx4 v[224:227], v149, s[38:39] offset:64
	s_and_b64 vcc, exec, s[46:47]
	s_cbranch_vccz .LBB0_477
	s_barrier

; #define TID() fresh_tid(wave)
; __device__ __forceinline__ void tr_load(const float* W, int N, int nblk, int item, int lane, f32x4 (&wv)[8]) {
;     const int kb = item / nblk, nb = item % nblk, k0 = 64 * kb, n0 = 32 * nb;
; #pragma unroll
;     for (int i = 0; i < 8; ++i) wv[i] = *(const f32x4*)(W + (size_t)(k0 + 8 * i + (lane >> 3)) * N + n0 + 4 * (lane & 7));
; }
; __global__ void __launch_bounds__(NWAVES * 64, 2) mk_fwd(Args args) {
;     ...
;     {
;         const int lane = TID() & 63;
;         convert_matrix(args.in[10], 1024, DM, (bf16*)(ws + WS_WO1), nullptr, 0, 1.f, scr, gw, NGW, lane);
.LBB0_549:
	s_or_b64 exec, exec, s[8:9]
	s_waitcnt lgkmcnt(0)
	s_setprio 0
	v_mov_b32_e32 v0, v252
	s_barrier
	s_cmpk_gt_i32 s20, 0x3ff
	v_and_b32_e32 v36, 63, v0
	v_lshrrev_b32_e32 v39, 3, v36
	v_lshlrev_b32_e32 v41, 4, v36
	v_lshlrev_b32_e32 v40, 3, v36
	s_cbranch_scc1 .LBB0_554
	s_ashr_i32 s10, s20, 31
	s_lshr_b32 s10, s10, 26
	s_add_i32 s10, s20, s10
	s_load_dwordx2 s[8:9], s[0:1], 0x50
	s_and_b32 s11, s10, 0xffffffc0
	s_sub_i32 s10, s20, s11
	s_lshl_b32 s10, s10, 5
	v_lshrrev_b32_e32 v37, 3, v36
	v_or_b32_e32 v24, s11, v37
	s_ashr_i32 s11, s10, 31
	s_lshl_b64 s[10:11], s[10:11], 2
	s_waitcnt lgkmcnt(0)
	s_add_u32 s10, s8, s10
	s_addc_u32 s11, s9, s11
	v_and_b32_e32 v34, 0x70, v41
	v_mov_b32_e32 v35, 0
	v_ashrrev_i32_e32 v25, 31, v24
	v_lshl_add_u64 v[26:27], s[10:11], 0, v[34:35]
	v_lshlrev_b64 v[0:1], 13, v[24:25]
	v_lshl_add_u64 v[8:9], v[26:27], 0, v[0:1]
	v_or_b32_e32 v0, 8, v24
	v_ashrrev_i32_e32 v1, 31, v0
	v_lshlrev_b64 v[0:1], 13, v[0:1]
	v_lshl_add_u64 v[10:11], v[26:27], 0, v[0:1]
	global_load_dwordx4 v[0:3], v[8:9], off
	global_load_dwordx4 v[4:7], v[10:11], off
	v_or_b32_e32 v8, 16, v24
	v_ashrrev_i32_e32 v9, 31, v8
	v_lshlrev_b64 v[8:9], 13, v[8:9]
	v_lshl_add_u64 v[16:17], v[26:27], 0, v[8:9]
	v_or_b32_e32 v8, 24, v24
	v_ashrrev_i32_e32 v9, 31, v8
	v_lshlrev_b64 v[8:9], 13, v[8:9]
	v_lshl_add_u64 v[18:19], v[26:27], 0, v[8:9]
	global_load_dwordx4 v[8:11], v[16:17], off
	global_load_dwordx4 v[12:15], v[18:19], off
	v_or_b32_e32 v16, 32, v24
	v_ashrrev_i32_e32 v17, 31, v16
	v_lshlrev_b64 v[16:17], 13, v[16:17]
	v_lshl_add_u64 v[28:29], v[26:27], 0, v[16:17]
	v_or_b32_e32 v16, 40, v24
	v_ashrrev_i32_e32 v17, 31, v16
	v_lshlrev_b64 v[16:17], 13, v[16:17]
	v_lshl_add_u64 v[30:31], v[26:27], 0, v[16:17]
	global_load_dwordx4 v[16:19], v[28:29], off
	global_load_dwordx4 v[20:23], v[30:31], off
	v_or_b32_e32 v28, 48, v24
	v_ashrrev_i32_e32 v29, 31, v28
	v_or_b32_e32 v24, 56, v24
	v_lshlrev_b64 v[28:29], 13, v[28:29]
	v_ashrrev_i32_e32 v25, 31, v24
	v_lshl_add_u64 v[32:33], v[26:27], 0, v[28:29]
	v_lshlrev_b64 v[24:25], 13, v[24:25]
	v_lshl_add_u64 v[42:43], v[26:27], 0, v[24:25]
	global_load_dwordx4 v[24:27], v[32:33], off
	global_load_dwordx4 v[28:31], v[42:43], off
	v_add_u32_e32 v42, s78, v34
	v_lshl_add_u64 v[32:33], s[8:9], 0, v[34:35]
	v_and_b32_e32 v34, 56, v40
	v_mul_u32_u24_e32 v43, 0x84, v37
	v_mul_u32_u24_e32 v38, 0x84, v34
	v_lshlrev_b32_e32 v34, 1, v34
	v_lshlrev_b32_e32 v44, 2, v37
	s_lshl_b32 s11, s22, 5
	v_lshl_add_u64 v[34:35], s[36:37], 0, v[34:35]
	v_add3_u32 v38, s78, v38, v44
	s_lshl_b32 s10, s20, 5
	v_add_u32_e32 v42, v42, v43
	s_mov_b32 s12, s11
	v_mov_b32_e32 v43, v37
	s_mov_b32 s14, s20
	s_branch .LBB0_552

; __device__ __forceinline__ float rstd_of(const u64* ss, int row) { return __builtin_amdgcn_rsqf((float)ss[row] * (1.0f / (2048.0f * SS_SCALE)) + RMS_EPS); }
; #define LAS __attribute__((address_space(3)))
; __device__ __forceinline__ void fill_rstd(LAS unsigned char* L, const pg8::StaticOrder& S, const pg8::u64* ssx, int tid) {
;     LAS float* tabl = (LAS float*)(L + pg8::RSTD_OFF); pg8::Unit u; int last = -1;
;     for (int i = 0; S.next(i, u); ++i) { if (u.pm != last) { last = u.pm; if (tid < 256) tabl[((u.pm >> 3) & 3) * 256 + tid] = pg8::rstd_of(ssx, u.pm * 256 + tid); } }
;     __syncthreads();
.LBB0_580:
	s_waitcnt vmcnt(11)
	s_setprio 0
	v_mov_b32_e32 v0, v252
	s_barrier
	s_movk_i32 s8, 0xff
	v_add_u32_e32 v2, s81, v0
	v_cmp_lt_i32_e32 vcc, s8, v2
	v_lshl_add_u32 v3, v2, 2, s82
	s_mov_b32 s27, -1
	v_mov_b64_e32 v[0:1], 0x11ff
	s_movk_i32 s26, 0x241
	s_xor_b64 s[8:9], vcc, -1
	s_waitcnt vmcnt(10)
	v_mov_b32_e32 v4, 0x358637bd
	s_mov_b64 s[10:11], s[2:3]
	s_branch .LBB0_583

;     __host__ __device__ bool next(int i, Unit& u) const {
;         const long L = (long)i * G + c; if (L >= nwg) return false;
;         int wgid = (int)L; { const int q = nwg / NXCD, r = nwg % NXCD, xcd = wgid % NXCD, off = wgid / NXCD; wgid = (xcd < r ? xcd * (q + 1) : r * (q + 1) + (xcd - r) * q) + off; }
;         const int nig = wgm * nN, gid = wgid / nig, fm = gid * wgm, gsz = (nM - fm) < wgm ? (nM - fm) : wgm;
;         u.pm = fm + ((wgid % nig) % gsz); u.pn = (wgid % nig) / gsz; return true;
; template <class Epi, class Sched, bool ALIGN_EPI = false, bool SP2 = false>
; __device__ __forceinline__ void gemm_phase(PG8_LAS unsigned char* lds, const Gemm g, const Sched& S, const Epi& E, int tid_in) {
;     int tid_ = tid_in; asm volatile("" : "+v"(tid_)); const int tid = tid_, wid = __builtin_amdgcn_readfirstlane(tid >> 6), lane = tid & 63, wr = wid >> 2, wc = wid & 3, fr = lane & 15, fq = lane >> 4;
;     const int K = g.K, nt = K / BK;
;     unsigned voffA[2], voffB[2];
; #pragma unroll
;     for (int i = 0; i < 2; ++i) { int R, C; stage_rc(tid * 16 + i * 8192, R, C); const int Rb = 2 * (R & ~31) + (Epi::PERM ? perm32(R & 31) : (R & 31));
;         voffA[i] = (unsigned)(R * g.lda + C) * 2u; voffB[i] = (unsigned)(Rb * K + C) * 2u; }
;     const size_t kstep = (size_t)(BK * 2);
;     const size_t hstep = (size_t)HALF * g.lda * 2;
;     const size_t hstepB = (size_t)32 * K * 2;
;     const size_t tstep = 2 * hstep, tstepB = (size_t)BM * K * 2;
;     const unsigned ldsw = (unsigned)wid * 1024u;
;     const int aoff = lds_byte(wr * 64 + fr, fq * 8), boff = lds_byte(wc * 32 + fr, fq * 8);
;     ...
;     Unit cur, nxt; int ui = 0;
;     if (!S.next(0, cur)) return;
;     f32x4 acc[2][2][4][2];
; #pragma unroll
;     for (int a = 0; a < 2; ++a)
; #pragma unroll
;         for (int b = 0; b < 2; ++b)
; #pragma unroll
;             for (int m = 0; m < 4; ++m)
; #pragma unroll
;                 for (int n = 0; n < 2; ++n) acc[a][b][m][n] = (f32x4){0.f, 0.f, 0.f, 0.f};
;     bf16x8 At[4][2], B0[2][2], B1[2][2];
;     const char* cA = (const char*)g.A + (size_t)cur.pm * tstep; const char* cB = (const char*)g.Bt + (size_t)cur.pn * tstepB;
;     S.a_ready(cur);
;     if constexpr (SP2) {
;         PG8_STAGE(PG8_SB(0, 0), cB, voffB); PG8_STAGE(PG8_SB(0, 1), cB + hstepB, voffB); PG8_STAGE(PG8_SA(0, 0), cA, voffA); PG8_STAGE(PG8_SA(0, 1), cA + hstep, voffA);
.LBB0_586:
	s_setprio 0
	v_mov_b32_e32 v0, v252
	s_waitcnt lgkmcnt(0)
	s_barrier
	s_cmpk_lt_i32 s2, 0x1200
	s_waitcnt vmcnt(9)
	v_add_u32_e32 v8, s81, v0
	s_cselect_b64 s[8:9], -1, 0
	s_cmpk_gt_i32 s2, 0x11ff
	v_readfirstlane_b32 s48, v8
	s_cbranch_scc1 .LBB0_588
	s_lshr_b32 s10, s3, 29
	s_add_i32 s10, s2, s10
	s_ashr_i32 s11, s10, 3
	s_and_b32 s10, s10, -8
	s_sub_i32 s10, s2, s10
	s_cmp_lt_i32 s10, 0
	s_movk_i32 s12, 0x241
	s_cselect_b32 s12, s12, 0x240
	s_mul_i32 s10, s10, s12
	s_add_i32 s10, s10, s11
	s_mul_hi_i32 s11, s10, 0x38e38e39
	s_lshr_b32 s12, s11, 31
	s_ashr_i32 s11, s11, 6
	s_add_i32 s11, s11, s12
	s_lshl_b32 s12, s11, 3
	s_mulk_i32 s11, 0x120
	s_sub_i32 s10, s10, s11
	s_sext_i32_i16 s11, s10
	s_bfe_u32 s11, s11, 0x3001c
	s_add_i32 s11, s10, s11
	s_sext_i32_i16 s13, s11
	s_and_b32 s11, s11, 0xfff8
	s_sub_i32 s10, s10, s11
	s_sext_i32_i16 s10, s10
	s_add_i32 s10, s12, s10
	s_ashr_i32 s58, s13, 3
.LBB0_588:
	s_andn2_b64 vcc, exec, s[8:9]
	s_cbranch_vccnz .LBB0_622
	v_ashrrev_i32_e32 v0, 31, v8
	v_lshrrev_b32_e32 v0, 26, v0
	v_add_u32_e32 v0, v8, v0
	v_ashrrev_i32_e32 v9, 6, v0
	v_bfe_i32 v0, v8, 27, 1
	s_waitcnt vmcnt(8)
	v_lshlrev_b32_e32 v13, 4, v8
	v_lshrrev_b32_e32 v0, 22, v0
	v_add_u32_e32 v0, v13, v0
	v_and_b32_e32 v0, 0xfffffc00, v0
	v_sub_u32_e32 v0, v13, v0
	v_lshrrev_b32_e32 v1, 4, v0
	v_bitop3_b32 v0, v1, v0, 32 bitop3:0x6c
	v_ashrrev_i32_e32 v2, 31, v0
	v_lshrrev_b32_e32 v2, 26, v2
	v_add_u32_e32 v2, v0, v2
	v_lshlrev_b32_e32 v1, 3, v9
	v_ashrrev_i32_e32 v10, 6, v2
	v_and_b32_e32 v2, 0xc0, v2
	v_and_b32_e32 v1, -16, v1
	v_sub_u32_e32 v0, v0, v2
	v_mov_b32_e32 v2, 1
	v_add_u32_e32 v1, v10, v1
	v_lshlrev_b32_e32 v3, 5, v9
	v_ashrrev_i16_sdwa v0, v2, sext(v0) dst_sel:DWORD dst_unused:UNUSED_PAD src0_sel:DWORD src1_sel:BYTE_0
	v_and_b32_e32 v3, 32, v3
	v_bfe_i32 v11, v0, 0, 16
	v_lshlrev_b32_e32 v0, 1, v1
	v_and_b32_e32 v4, 31, v1
	s_mov_b32 s9, 0xfffc0
	v_and_or_b32 v0, v0, s9, v4
	v_add_lshl_u32 v3, v3, v11, 1
	v_lshl_add_u32 v144, v0, 12, v3
	v_add_u32_e32 v0, 0x2000, v13
	v_lshl_add_u32 v142, v1, 12, v3
	v_ashrrev_i32_e32 v1, 31, v0
	v_lshrrev_b32_e32 v1, 22, v1
	v_add_u32_e32 v1, v0, v1
	v_ashrrev_i32_e32 v12, 10, v1
	v_mul_i32_i24_e32 v1, 0x400, v12
	v_sub_u32_e32 v0, v0, v1
	v_lshrrev_b32_e32 v1, 4, v0
	v_bitop3_b32 v0, v1, v0, 32 bitop3:0x6c
	v_ashrrev_i32_e32 v3, 31, v0
	v_lshrrev_b32_e32 v3, 26, v3
	v_add_u32_e32 v3, v0, v3
	v_lshlrev_b32_e32 v1, 3, v12
	v_ashrrev_i32_e32 v14, 6, v3
	v_and_b32_e32 v3, 0xc0, v3
	v_and_b32_e32 v1, -16, v1
	v_sub_u32_e32 v0, v0, v3
	s_add_u32 s66, s18, 0x6400000
	v_add_u32_e32 v1, v14, v1
	v_ashrrev_i16_sdwa v0, v2, sext(v0) dst_sel:DWORD dst_unused:UNUSED_PAD src0_sel:DWORD src1_sel:BYTE_0
	s_addc_u32 s67, s19, 0
	s_ashr_i32 s8, s48, 6
	v_bfe_i32 v15, v0, 0, 16
	v_lshlrev_b32_e32 v0, 1, v1
	v_and_b32_e32 v2, 31, v1
	s_ashr_i32 s11, s10, 31
	s_ashr_i32 s59, s58, 31
	v_and_or_b32 v0, v0, s9, v2
	s_ashr_i32 s9, s48, 8
	s_lshl_b32 s68, s8, 10
	s_lshl_b64 s[12:13], s[10:11], 20
	s_lshl_b64 s[26:27], s[58:59], 20
	s_add_u32 s62, s66, s26
	v_lshlrev_b32_e32 v4, 5, v12
	s_addc_u32 s63, s67, s27
	s_add_i32 s59, s68, 0
	v_and_b32_e32 v4, 32, v4
	s_add_i32 m0, s59, 0x10000
	v_add_lshl_u32 v2, v4, v15, 1
	global_load_lds_dwordx4 v144, s[62:63]
	s_add_i32 m0, s59, 0x12000
	v_lshl_add_u32 v148, v0, 12, v2
	s_add_u32 s26, s62, 0x20000
	global_load_lds_dwordx4 v148, s[62:63]
	s_addc_u32 s27, s63, 0
	s_add_i32 m0, s59, 0x14000
	v_lshl_add_u32 v146, v1, 12, v2
	global_load_lds_dwordx4 v144, s[26:27]
	s_add_i32 m0, s59, 0x16000
	s_add_u32 s60, s28, s12
	s_addc_u32 s61, s29, s13
	s_add_i32 s69, s59, 0x2000
	global_load_lds_dwordx4 v148, s[26:27]
	s_mov_b32 m0, s59
	s_add_u32 s12, s60, 0x80000
	global_load_lds_dwordx4 v142, s[60:61]
	s_mov_b32 m0, s69
	s_addc_u32 s13, s61, 0
	s_add_i32 s70, s59, 0x4000
	global_load_lds_dwordx4 v146, s[60:61]
	s_mov_b32 m0, s70
	s_add_i32 s71, s59, 0x6000
	global_load_lds_dwordx4 v142, s[12:13]
	s_mov_b32 m0, s71
	v_mov_b32_e32 v151, 0
	global_load_lds_dwordx4 v146, s[12:13]
	v_mov_b32_e32 v145, v151
	v_mov_b32_e32 v149, v151
	v_mov_b32_e32 v143, v151
	v_mov_b32_e32 v147, v151
	s_cmp_eq_u32 s9, 1
	s_mov_b32 s72, 0
	v_lshl_add_u64 v[6:7], s[62:63], 0, v[144:145]
	v_lshl_add_u64 v[4:5], s[62:63], 0, v[148:149]
	v_lshl_add_u64 v[0:1], s[60:61], 0, v[142:143]
	s_cselect_b64 s[12:13], -1, 0
	s_cmp_lg_u32 s9, 1
	v_lshl_add_u64 v[2:3], s[60:61], 0, v[146:147]
	s_cbranch_scc1 .LBB0_591
	s_barrier
	s_setprio 1

; #define PG8_STAGE(bufoff, gbase, voff) do { _Pragma("unroll") for (int _i = 0; _i < 2; ++_i) \
;         __builtin_amdgcn_global_load_lds((const unsigned*)((const char*)(gbase) + (voff)[_i]), (PG8_LAS unsigned*)(lds + (bufoff) + ldsw + _i * 8192), 16, 0, 0); } while (0)
; #define PG8_LDA(dst, b, h) do { _Pragma("unroll") for (int m = 0; m < 4; ++m) _Pragma("unroll") for (int k = 0; k < 2; ++k) dst[m][k] = *(const PG8_LAS bf16x8*)(lds + PG8_SA(b, h) + aoff + m * 2048 + k * 1024); } while (0)
; #define PG8_LDB(dst, b, h) do { _Pragma("unroll") for (int n = 0; n < 2; ++n) _Pragma("unroll") for (int k = 0; k < 2; ++k) dst[n][k] = *(const PG8_LAS bf16x8*)(lds + PG8_SB(b, h) + boff + n * 2048 + k * 1024); } while (0)
; #define PG8_MMA(ai, bj, At, Bt) do { __builtin_amdgcn_s_setprio(1); _Pragma("unroll") for (int m = 0; m < 4; ++m) _Pragma("unroll") for (int n = 0; n < 2; ++n) _Pragma("unroll") for (int k = 0; k < 2; ++k) \
;         acc[ai][bj][m][n] = __builtin_amdgcn_mfma_f32_16x16x32_bf16(Bt[n][k], At[m][k], acc[ai][bj][m][n], 0, 0, 0); __builtin_amdgcn_s_setprio(0); } while (0)
; #define PG8_WAIT_V(n) asm volatile("s_waitcnt vmcnt(" #n ")" ::: "memory")
; #define PG8_WAIT_L(n) asm volatile("s_waitcnt lgkmcnt(" #n ")" ::: "memory")
; #define PG8_BAR __builtin_amdgcn_s_barrier()
; #define PG8_SCHED __builtin_amdgcn_sched_barrier(0)
; template <class Epi, class Sched, bool ALIGN_EPI = false, bool SP2 = false>
; __device__ __forceinline__ void gemm_phase(PG8_LAS unsigned char* lds, const Gemm g, const Sched& S, const Epi& E, int tid_in) {
;     ...
;             PG8_LDB(B0, 0, 0); PG8_LDB(B1, 0, 1); PG8_SCHED; PG8_LDA(At, 0, 0); PG8_STAGE(PG8_SA(1, 1), a1 + hstep, voffA);
;             PG8_WAIT_V(8); PG8_WAIT_L(0); PG8_BAR; PG8_MMA(0, 0, At, B0); PG8_MMA(0, 1, At, B1); PG8_BAR; PG8_SCHED;
;             PG8_LDA(At, 0, 1); PG8_STAGE(PG8_SB(0, 0), b2, voffB); PG8_STAGE(PG8_SB(0, 1), b2 + hstepB, voffB); PG8_STAGE(PG8_SA(0, 0), a2, voffA);
;             PG8_WAIT_V(8); PG8_WAIT_L(0); PG8_BAR; PG8_MMA(1, 0, At, B0); PG8_MMA(1, 1, At, B1); PG8_BAR; PG8_SCHED;
.Lkb_skip_4:
.LBB0_597:
	ds_read_b128 v[128:131], v171
	ds_read_b128 v[132:135], v171 offset:1024
	ds_read_b128 v[136:139], v171 offset:2048
	ds_read_b128 v[184:187], v171 offset:3072
	ds_read_b128 v[188:191], v172
	ds_read_b128 v[192:195], v172 offset:1024
	ds_read_b128 v[196:199], v172 offset:2048
	ds_read_b128 v[200:203], v172 offset:3072
	s_add_u32 s26, s60, 0xfff80080
	s_addc_u32 s27, s61, -1
	s_cmp_eq_u32 s88, 28
	s_cselect_b32 s65, s11, s27
	s_cselect_b32 s64, s53, s26
	s_cselect_b32 s63, s51, s87
	s_cselect_b32 s62, s85, s86
	v_lshl_add_u64 v[140:141], s[60:61], 0, v[158:159]
	s_add_i32 m0, s59, 0xc000
	ds_read_b128 v[204:207], v173
	ds_read_b128 v[212:215], v173 offset:1024
	ds_read_b128 v[216:219], v173 offset:2048
	ds_read_b128 v[220:223], v173 offset:3072
	ds_read_b128 v[224:227], v173 offset:4096
	ds_read_b128 v[228:231], v173 offset:5120
	ds_read_b128 v[232:235], v173 offset:6144
	ds_read_b128 v[236:239], v173 offset:7168
	global_load_lds_dwordx4 v[140:141], off
	v_lshl_add_u64 v[140:141], s[60:61], 0, v[160:161]
	s_add_i32 m0, s59, 0xe000
	s_nop 0
	global_load_lds_dwordx4 v[140:141], off
	s_waitcnt vmcnt(8)
	s_waitcnt lgkmcnt(0)
	s_barrier
	s_waitcnt lgkmcnt(0)
	v_mfma_f32_16x16x32_bf16 v[124:127], v[128:131], v[204:207], v[124:127]
	v_mfma_f32_16x16x32_bf16 v[120:123], v[136:139], v[204:207], v[120:123]
	v_mfma_f32_16x16x32_bf16 v[108:111], v[128:131], v[216:219], v[108:111]
	v_mfma_f32_16x16x32_bf16 v[104:107], v[136:139], v[216:219], v[104:107]
	v_mfma_f32_16x16x32_bf16 v[92:95], v[128:131], v[224:227], v[92:95]
	v_mfma_f32_16x16x32_bf16 v[88:91], v[136:139], v[224:227], v[88:91]
	v_mfma_f32_16x16x32_bf16 v[76:79], v[128:131], v[232:235], v[76:79]
	v_mfma_f32_16x16x32_bf16 v[72:75], v[136:139], v[232:235], v[72:75]
	v_mfma_f32_16x16x32_bf16 v[124:127], v[132:135], v[212:215], v[124:127]
	v_mfma_f32_16x16x32_bf16 v[120:123], v[184:187], v[212:215], v[120:123]
	v_mfma_f32_16x16x32_bf16 v[108:111], v[132:135], v[220:223], v[108:111]
	v_mfma_f32_16x16x32_bf16 v[104:107], v[184:187], v[220:223], v[104:107]
	v_mfma_f32_16x16x32_bf16 v[92:95], v[132:135], v[228:231], v[92:95]
	v_mfma_f32_16x16x32_bf16 v[88:91], v[184:187], v[228:231], v[88:91]
	v_mfma_f32_16x16x32_bf16 v[76:79], v[132:135], v[236:239], v[76:79]
	v_mfma_f32_16x16x32_bf16 v[72:75], v[184:187], v[236:239], v[72:75]
	v_mfma_f32_16x16x32_bf16 v[116:119], v[188:191], v[204:207], v[116:119]
	v_mfma_f32_16x16x32_bf16 v[112:115], v[196:199], v[204:207], v[112:115]
	v_mfma_f32_16x16x32_bf16 v[100:103], v[188:191], v[216:219], v[100:103]
	v_mfma_f32_16x16x32_bf16 v[96:99], v[196:199], v[216:219], v[96:99]
	v_mfma_f32_16x16x32_bf16 v[84:87], v[188:191], v[224:227], v[84:87]
	v_mfma_f32_16x16x32_bf16 v[80:83], v[196:199], v[224:227], v[80:83]
	v_mfma_f32_16x16x32_bf16 v[68:71], v[188:191], v[232:235], v[68:71]
	v_mfma_f32_16x16x32_bf16 v[64:67], v[196:199], v[232:235], v[64:67]
	v_mfma_f32_16x16x32_bf16 v[116:119], v[192:195], v[212:215], v[116:119]
	v_mfma_f32_16x16x32_bf16 v[112:115], v[200:203], v[212:215], v[112:115]
	v_mfma_f32_16x16x32_bf16 v[100:103], v[192:195], v[220:223], v[100:103]
	v_mfma_f32_16x16x32_bf16 v[96:99], v[200:203], v[220:223], v[96:99]
	v_mfma_f32_16x16x32_bf16 v[84:87], v[192:195], v[228:231], v[84:87]
	v_mfma_f32_16x16x32_bf16 v[80:83], v[200:203], v[228:231], v[80:83]
	v_mfma_f32_16x16x32_bf16 v[68:71], v[192:195], v[236:239], v[68:71]
	v_mfma_f32_16x16x32_bf16 v[64:67], v[200:203], v[236:239], v[64:67]
	s_barrier
	s_add_i32 s26, s78, s68
	v_lshl_add_u64 v[140:141], s[62:63], 0, v[144:145]
	s_mov_b32 m0, s26
	ds_read_b128 v[204:207], v173 offset:16384
	ds_read_b128 v[212:215], v173 offset:17408
	ds_read_b128 v[216:219], v173 offset:18432
	ds_read_b128 v[220:223], v173 offset:19456
	ds_read_b128 v[224:227], v173 offset:20480
	ds_read_b128 v[228:231], v173 offset:21504
	ds_read_b128 v[232:235], v173 offset:22528
	ds_read_b128 v[236:239], v173 offset:23552
	global_load_lds_dwordx4 v[140:141], off
	s_add_i32 m0, s26, 0x2000
	s_add_u32 s26, s62, 0x20000
	v_lshl_add_u64 v[208:209], s[62:63], 0, v[148:149]
	s_addc_u32 s27, s63, 0
	s_add_i32 s33, s79, s68
	global_load_lds_dwordx4 v[208:209], off
	v_lshl_add_u64 v[240:241], s[26:27], 0, v[144:145]
	s_mov_b32 m0, s33
	v_lshl_add_u64 v[242:243], s[64:65], 0, v[146:147]
	global_load_lds_dwordx4 v[240:241], off
	v_lshl_add_u64 v[240:241], s[26:27], 0, v[148:149]
	s_add_i32 m0, s33, 0x2000
	s_nop 0
	global_load_lds_dwordx4 v[240:241], off
	v_lshl_add_u64 v[240:241], s[64:65], 0, v[142:143]
	s_mov_b32 m0, s59
	s_nop 0
	global_load_lds_dwordx4 v[240:241], off
	s_mov_b32 m0, s69
	s_nop 0
	global_load_lds_dwordx4 v[242:243], off
	s_waitcnt vmcnt(8)
	s_waitcnt lgkmcnt(0)
	s_barrier
; #define PG8_STAGE(bufoff, gbase, voff) do { _Pragma("unroll") for (int _i = 0; _i < 2; ++_i) \
;         __builtin_amdgcn_global_load_lds((const unsigned*)((const char*)(gbase) + (voff)[_i]), (PG8_LAS unsigned*)(lds + (bufoff) + ldsw + _i * 8192), 16, 0, 0); } while (0)
; #define PG8_LDA(dst, b, h) do { _Pragma("unroll") for (int m = 0; m < 4; ++m) _Pragma("unroll") for (int k = 0; k < 2; ++k) dst[m][k] = *(const PG8_LAS bf16x8*)(lds + PG8_SA(b, h) + aoff + m * 2048 + k * 1024); } while (0)
; #define PG8_LDB(dst, b, h) do { _Pragma("unroll") for (int n = 0; n < 2; ++n) _Pragma("unroll") for (int k = 0; k < 2; ++k) dst[n][k] = *(const PG8_LAS bf16x8*)(lds + PG8_SB(b, h) + boff + n * 2048 + k * 1024); } while (0)
; #define PG8_MMA(ai, bj, At, Bt) do { __builtin_amdgcn_s_setprio(1); _Pragma("unroll") for (int m = 0; m < 4; ++m) _Pragma("unroll") for (int n = 0; n < 2; ++n) _Pragma("unroll") for (int k = 0; k < 2; ++k) \
;         acc[ai][bj][m][n] = __builtin_amdgcn_mfma_f32_16x16x32_bf16(Bt[n][k], At[m][k], acc[ai][bj][m][n], 0, 0, 0); __builtin_amdgcn_s_setprio(0); } while (0)
; #define PG8_WAIT_V(n) asm volatile("s_waitcnt vmcnt(" #n ")" ::: "memory")
; #define PG8_WAIT_L(n) asm volatile("s_waitcnt lgkmcnt(" #n ")" ::: "memory")
; #define PG8_BAR __builtin_amdgcn_s_barrier()
; #define PG8_SCHED __builtin_amdgcn_sched_barrier(0)
; template <class Epi, class Sched, bool ALIGN_EPI = false, bool SP2 = false>
; __device__ __forceinline__ void gemm_phase(PG8_LAS unsigned char* lds, const Gemm g, const Sched& S, const Epi& E, int tid_in) {
;     ...
;             PG8_WAIT_V(8); PG8_WAIT_L(0); PG8_BAR; PG8_MMA(1, 0, At, B0); PG8_MMA(1, 1, At, B1); PG8_BAR; PG8_SCHED;
;             PG8_LDB(B0, 1, 0); PG8_LDB(B1, 1, 1); PG8_SCHED; PG8_LDA(At, 1, 0); PG8_STAGE(PG8_SA(0, 1), a2 + hstep, voffA);
;             PG8_WAIT_V(8); PG8_WAIT_L(0); PG8_BAR; PG8_MMA(0, 0, At, B0); PG8_MMA(0, 1, At, B1); PG8_BAR; PG8_SCHED;
	s_waitcnt lgkmcnt(0)
	v_mfma_f32_16x16x32_bf16 v[60:63], v[128:131], v[204:207], v[60:63]
	v_mfma_f32_16x16x32_bf16 v[56:59], v[136:139], v[204:207], v[56:59]
	v_mfma_f32_16x16x32_bf16 v[44:47], v[128:131], v[216:219], v[44:47]
	v_mfma_f32_16x16x32_bf16 v[40:43], v[136:139], v[216:219], v[40:43]
	v_mfma_f32_16x16x32_bf16 v[28:31], v[128:131], v[224:227], v[28:31]
	v_mfma_f32_16x16x32_bf16 v[24:27], v[136:139], v[224:227], v[24:27]
	v_mfma_f32_16x16x32_bf16 v[12:15], v[128:131], v[232:235], v[12:15]
	v_mfma_f32_16x16x32_bf16 v[8:11], v[136:139], v[232:235], v[8:11]
	v_mfma_f32_16x16x32_bf16 v[60:63], v[132:135], v[212:215], v[60:63]
	v_mfma_f32_16x16x32_bf16 v[56:59], v[184:187], v[212:215], v[56:59]
	v_mfma_f32_16x16x32_bf16 v[44:47], v[132:135], v[220:223], v[44:47]
	v_mfma_f32_16x16x32_bf16 v[40:43], v[184:187], v[220:223], v[40:43]
	v_mfma_f32_16x16x32_bf16 v[28:31], v[132:135], v[228:231], v[28:31]
	v_mfma_f32_16x16x32_bf16 v[24:27], v[184:187], v[228:231], v[24:27]
	v_mfma_f32_16x16x32_bf16 v[12:15], v[132:135], v[236:239], v[12:15]
	v_mfma_f32_16x16x32_bf16 v[8:11], v[184:187], v[236:239], v[8:11]
	v_mfma_f32_16x16x32_bf16 v[52:55], v[188:191], v[204:207], v[52:55]
	v_mfma_f32_16x16x32_bf16 v[48:51], v[196:199], v[204:207], v[48:51]
	v_mfma_f32_16x16x32_bf16 v[36:39], v[188:191], v[216:219], v[36:39]
	v_mfma_f32_16x16x32_bf16 v[32:35], v[196:199], v[216:219], v[32:35]
	v_mfma_f32_16x16x32_bf16 v[20:23], v[188:191], v[224:227], v[20:23]
	v_mfma_f32_16x16x32_bf16 v[16:19], v[196:199], v[224:227], v[16:19]
	v_mfma_f32_16x16x32_bf16 v[4:7], v[188:191], v[232:235], v[4:7]
	v_mfma_f32_16x16x32_bf16 v[0:3], v[196:199], v[232:235], v[0:3]
	v_mfma_f32_16x16x32_bf16 v[52:55], v[192:195], v[212:215], v[52:55]
	v_mfma_f32_16x16x32_bf16 v[48:51], v[200:203], v[212:215], v[48:51]
	v_mfma_f32_16x16x32_bf16 v[36:39], v[192:195], v[220:223], v[36:39]
	v_mfma_f32_16x16x32_bf16 v[32:35], v[200:203], v[220:223], v[32:35]
	v_mfma_f32_16x16x32_bf16 v[20:23], v[192:195], v[228:231], v[20:23]
	v_mfma_f32_16x16x32_bf16 v[16:19], v[200:203], v[228:231], v[16:19]
	v_mfma_f32_16x16x32_bf16 v[4:7], v[192:195], v[236:239], v[4:7]
	v_mfma_f32_16x16x32_bf16 v[0:3], v[200:203], v[236:239], v[0:3]
	s_barrier
	s_add_i32 s33, 0, 0x18000
	v_add_u32_e32 v150, s33, v167
	s_add_i32 s89, 0, 0x1c000
	ds_read_b128 v[128:131], v150
	ds_read_b128 v[132:135], v150 offset:1024
	ds_read_b128 v[136:139], v150 offset:2048
	ds_read_b128 v[184:187], v150 offset:3072
	v_add_u32_e32 v150, s89, v167
	ds_read_b128 v[188:191], v150
	ds_read_b128 v[192:195], v150 offset:1024
	ds_read_b128 v[196:199], v150 offset:2048
	ds_read_b128 v[200:203], v150 offset:3072
	s_add_u32 s26, s64, 0x80000
	s_addc_u32 s27, s65, 0
	s_mov_b32 m0, s70
	v_lshl_add_u64 v[244:245], s[26:27], 0, v[142:143]
	ds_read_b128 v[204:207], v173 offset:32768
	ds_read_b128 v[212:215], v173 offset:33792
	ds_read_b128 v[216:219], v173 offset:34816
	ds_read_b128 v[220:223], v173 offset:35840
	ds_read_b128 v[224:227], v173 offset:36864
	ds_read_b128 v[228:231], v173 offset:37888
	ds_read_b128 v[232:235], v173 offset:38912
	ds_read_b128 v[236:239], v173 offset:39936
	global_load_lds_dwordx4 v[244:245], off
	v_lshl_add_u64 v[244:245], s[26:27], 0, v[146:147]
	s_mov_b32 m0, s71
	s_nop 0
	global_load_lds_dwordx4 v[244:245], off
	s_waitcnt vmcnt(8)
	s_waitcnt lgkmcnt(0)
	s_barrier
	s_waitcnt lgkmcnt(0)
	v_mfma_f32_16x16x32_bf16 v[124:127], v[128:131], v[204:207], v[124:127]
	v_mfma_f32_16x16x32_bf16 v[120:123], v[136:139], v[204:207], v[120:123]
	v_mfma_f32_16x16x32_bf16 v[108:111], v[128:131], v[216:219], v[108:111]
	v_mfma_f32_16x16x32_bf16 v[104:107], v[136:139], v[216:219], v[104:107]
	v_mfma_f32_16x16x32_bf16 v[92:95], v[128:131], v[224:227], v[92:95]
	v_mfma_f32_16x16x32_bf16 v[88:91], v[136:139], v[224:227], v[88:91]
	v_mfma_f32_16x16x32_bf16 v[76:79], v[128:131], v[232:235], v[76:79]
	v_mfma_f32_16x16x32_bf16 v[72:75], v[136:139], v[232:235], v[72:75]
	v_mfma_f32_16x16x32_bf16 v[124:127], v[132:135], v[212:215], v[124:127]
	v_mfma_f32_16x16x32_bf16 v[120:123], v[184:187], v[212:215], v[120:123]
	v_mfma_f32_16x16x32_bf16 v[108:111], v[132:135], v[220:223], v[108:111]
	v_mfma_f32_16x16x32_bf16 v[104:107], v[184:187], v[220:223], v[104:107]
	v_mfma_f32_16x16x32_bf16 v[92:95], v[132:135], v[228:231], v[92:95]
	v_mfma_f32_16x16x32_bf16 v[88:91], v[184:187], v[228:231], v[88:91]
	v_mfma_f32_16x16x32_bf16 v[76:79], v[132:135], v[236:239], v[76:79]
	v_mfma_f32_16x16x32_bf16 v[72:75], v[184:187], v[236:239], v[72:75]
	v_mfma_f32_16x16x32_bf16 v[116:119], v[188:191], v[204:207], v[116:119]
	v_mfma_f32_16x16x32_bf16 v[112:115], v[196:199], v[204:207], v[112:115]
	v_mfma_f32_16x16x32_bf16 v[100:103], v[188:191], v[216:219], v[100:103]
	v_mfma_f32_16x16x32_bf16 v[96:99], v[196:199], v[216:219], v[96:99]
	v_mfma_f32_16x16x32_bf16 v[84:87], v[188:191], v[224:227], v[84:87]
	v_mfma_f32_16x16x32_bf16 v[80:83], v[196:199], v[224:227], v[80:83]
	v_mfma_f32_16x16x32_bf16 v[68:71], v[188:191], v[232:235], v[68:71]
	v_mfma_f32_16x16x32_bf16 v[64:67], v[196:199], v[232:235], v[64:67]
	v_mfma_f32_16x16x32_bf16 v[116:119], v[192:195], v[212:215], v[116:119]
	v_mfma_f32_16x16x32_bf16 v[112:115], v[200:203], v[212:215], v[112:115]
	v_mfma_f32_16x16x32_bf16 v[100:103], v[192:195], v[220:223], v[100:103]
	v_mfma_f32_16x16x32_bf16 v[96:99], v[200:203], v[220:223], v[96:99]
	v_mfma_f32_16x16x32_bf16 v[84:87], v[192:195], v[228:231], v[84:87]
	v_mfma_f32_16x16x32_bf16 v[80:83], v[200:203], v[228:231], v[80:83]
	v_mfma_f32_16x16x32_bf16 v[68:71], v[192:195], v[236:239], v[68:71]
	v_mfma_f32_16x16x32_bf16 v[64:67], v[200:203], v[236:239], v[64:67]
	s_barrier
; #define PG8_STAGE(bufoff, gbase, voff) do { _Pragma("unroll") for (int _i = 0; _i < 2; ++_i) \
;         __builtin_amdgcn_global_load_lds((const unsigned*)((const char*)(gbase) + (voff)[_i]), (PG8_LAS unsigned*)(lds + (bufoff) + ldsw + _i * 8192), 16, 0, 0); } while (0)
; #define PG8_LDA(dst, b, h) do { _Pragma("unroll") for (int m = 0; m < 4; ++m) _Pragma("unroll") for (int k = 0; k < 2; ++k) dst[m][k] = *(const PG8_LAS bf16x8*)(lds + PG8_SA(b, h) + aoff + m * 2048 + k * 1024); } while (0)
; #define PG8_MMA(ai, bj, At, Bt) do { __builtin_amdgcn_s_setprio(1); _Pragma("unroll") for (int m = 0; m < 4; ++m) _Pragma("unroll") for (int n = 0; n < 2; ++n) _Pragma("unroll") for (int k = 0; k < 2; ++k) \
;         acc[ai][bj][m][n] = __builtin_amdgcn_mfma_f32_16x16x32_bf16(Bt[n][k], At[m][k], acc[ai][bj][m][n], 0, 0, 0); __builtin_amdgcn_s_setprio(0); } while (0)
; #define PG8_WAIT_V(n) asm volatile("s_waitcnt vmcnt(" #n ")" ::: "memory")
; #define PG8_WAIT_L(n) asm volatile("s_waitcnt lgkmcnt(" #n ")" ::: "memory")
; #define PG8_BAR __builtin_amdgcn_s_barrier()
; #define PG8_SCHED __builtin_amdgcn_sched_barrier(0)
; template <class Epi, class Sched, bool ALIGN_EPI = false, bool SP2 = false>
; __device__ __forceinline__ void gemm_phase(PG8_LAS unsigned char* lds, const Gemm g, const Sched& S, const Epi& E, int tid_in) {
;     ...
;             PG8_LDA(At, 1, 1); PG8_STAGE(PG8_SB(1, 0), b3, voffB); PG8_STAGE(PG8_SB(1, 1), b3 + hstepB, voffB); PG8_STAGE(PG8_SA(1, 0), a3, voffA);
;             PG8_WAIT_V(8); PG8_WAIT_L(0); PG8_BAR; PG8_MMA(1, 0, At, B0); PG8_MMA(1, 1, At, B1); PG8_BAR; PG8_SCHED;
	s_add_i32 s26, s33, s68
	v_lshl_add_u64 v[140:141], v[140:141], 0, s[44:45]
	s_mov_b32 m0, s26
	ds_read_b128 v[204:207], v173 offset:49152
	ds_read_b128 v[212:215], v173 offset:50176
	ds_read_b128 v[216:219], v173 offset:51200
	ds_read_b128 v[220:223], v173 offset:52224
	ds_read_b128 v[224:227], v173 offset:53248
	ds_read_b128 v[228:231], v173 offset:54272
	ds_read_b128 v[232:235], v173 offset:55296
	ds_read_b128 v[236:239], v173 offset:56320
	global_load_lds_dwordx4 v[140:141], off
	s_add_i32 m0, s26, 0x2000
	s_add_u32 s26, s62, 0x20080
	v_lshl_add_u64 v[140:141], v[208:209], 0, s[44:45]
	s_addc_u32 s27, s63, 0
	s_add_i32 s33, s89, s68
	global_load_lds_dwordx4 v[140:141], off
	v_lshl_add_u64 v[140:141], s[26:27], 0, v[144:145]
	s_mov_b32 m0, s33
	s_nop 0
	global_load_lds_dwordx4 v[140:141], off
	v_lshl_add_u64 v[140:141], s[26:27], 0, v[148:149]
	s_add_i32 m0, s33, 0x2000
	s_nop 0
	global_load_lds_dwordx4 v[140:141], off
	v_lshl_add_u64 v[140:141], v[240:241], 0, s[44:45]
	s_mov_b32 m0, s74
	s_nop 0
	global_load_lds_dwordx4 v[140:141], off
	v_lshl_add_u64 v[140:141], v[242:243], 0, s[44:45]
	s_mov_b32 m0, s75
	s_nop 0
	global_load_lds_dwordx4 v[140:141], off
	s_waitcnt vmcnt(8)
	s_waitcnt lgkmcnt(0)
	s_barrier
	s_waitcnt lgkmcnt(0)
	v_mfma_f32_16x16x32_bf16 v[60:63], v[128:131], v[204:207], v[60:63]
	v_mfma_f32_16x16x32_bf16 v[56:59], v[136:139], v[204:207], v[56:59]
	v_mfma_f32_16x16x32_bf16 v[44:47], v[128:131], v[216:219], v[44:47]
	v_mfma_f32_16x16x32_bf16 v[40:43], v[136:139], v[216:219], v[40:43]
	v_mfma_f32_16x16x32_bf16 v[28:31], v[128:131], v[224:227], v[28:31]
	v_mfma_f32_16x16x32_bf16 v[24:27], v[136:139], v[224:227], v[24:27]
	v_mfma_f32_16x16x32_bf16 v[12:15], v[128:131], v[232:235], v[12:15]
	v_mfma_f32_16x16x32_bf16 v[8:11], v[136:139], v[232:235], v[8:11]
	v_mfma_f32_16x16x32_bf16 v[60:63], v[132:135], v[212:215], v[60:63]
	v_mfma_f32_16x16x32_bf16 v[56:59], v[184:187], v[212:215], v[56:59]
	v_mfma_f32_16x16x32_bf16 v[44:47], v[132:135], v[220:223], v[44:47]
	v_mfma_f32_16x16x32_bf16 v[40:43], v[184:187], v[220:223], v[40:43]
	v_mfma_f32_16x16x32_bf16 v[28:31], v[132:135], v[228:231], v[28:31]
	v_mfma_f32_16x16x32_bf16 v[24:27], v[184:187], v[228:231], v[24:27]
	v_mfma_f32_16x16x32_bf16 v[12:15], v[132:135], v[236:239], v[12:15]
	v_mfma_f32_16x16x32_bf16 v[8:11], v[184:187], v[236:239], v[8:11]
	v_mfma_f32_16x16x32_bf16 v[52:55], v[188:191], v[204:207], v[52:55]
	v_mfma_f32_16x16x32_bf16 v[48:51], v[196:199], v[204:207], v[48:51]
	v_mfma_f32_16x16x32_bf16 v[36:39], v[188:191], v[216:219], v[36:39]
	v_mfma_f32_16x16x32_bf16 v[32:35], v[196:199], v[216:219], v[32:35]
	v_mfma_f32_16x16x32_bf16 v[20:23], v[188:191], v[224:227], v[20:23]
	v_mfma_f32_16x16x32_bf16 v[16:19], v[196:199], v[224:227], v[16:19]
	v_mfma_f32_16x16x32_bf16 v[4:7], v[188:191], v[232:235], v[4:7]
	v_mfma_f32_16x16x32_bf16 v[0:3], v[196:199], v[232:235], v[0:3]
	v_mfma_f32_16x16x32_bf16 v[52:55], v[192:195], v[212:215], v[52:55]
	v_mfma_f32_16x16x32_bf16 v[48:51], v[200:203], v[212:215], v[48:51]
	v_mfma_f32_16x16x32_bf16 v[36:39], v[192:195], v[220:223], v[36:39]
	v_mfma_f32_16x16x32_bf16 v[32:35], v[200:203], v[220:223], v[32:35]
	v_mfma_f32_16x16x32_bf16 v[20:23], v[192:195], v[228:231], v[20:23]
	v_mfma_f32_16x16x32_bf16 v[16:19], v[200:203], v[228:231], v[16:19]
	v_mfma_f32_16x16x32_bf16 v[4:7], v[192:195], v[236:239], v[4:7]
	v_mfma_f32_16x16x32_bf16 v[0:3], v[200:203], v[236:239], v[0:3]
	s_barrier
	s_add_i32 s88, s88, 2
	s_add_u32 s60, s60, 0x100
	s_addc_u32 s61, s61, 0
	s_add_u32 s86, s86, 0x100
	s_addc_u32 s87, s87, 0
	s_cmp_gt_u32 s88, 29
	s_cbranch_scc0 .LBB0_597
	s_and_b64 vcc, exec, s[46:47]
	s_cbranch_vccz .LBB0_600
	s_barrier

; #define ALDS __attribute__((address_space(3)))
; #define ATT_Q_DMA() do { unsigned qo_ = kD - klb; asm volatile("" : "+v"(qo_) :: "memory");     \
;         _Pragma("unroll") for (int c = 0; c < 8; ++c) \
;         __builtin_amdgcn_global_load_lds((const unsigned*)(qb + 1024 * c + (qo_ ^ (unsigned)((c & 3) << 6))), (ALDS unsigned*)(klb + 1024u * c), 16, 0, 0); } while (0)
; __device__ __forceinline__ void dil_phase(const bf16* qkv, bf16* scratch, bf16* merged, ldsp lds, int vcu, int G, int tid_in) {
;     int tid_ = tid_in; asm volatile("" : "+v"(tid_)); const int tid = tid_, lane = tid & 63, wave = __builtin_amdgcn_readfirstlane(tid >> 6), r32 = lane & 31, hh = lane >> 5;
;     ATT_BASES((unsigned)(unsigned long)lds); ALDS float* lse = (ALDS float*)(lds + 131072);
;     constexpr size_t PITCH = 128, PLANE = pg8::PLANE; constexpr int NUNITS = 512;
;     const int per = (NUNITS + G - 1) / G; const int u_lo = vcu * per, u_hi = (u_lo + per < NUNITS) ? u_lo + per : NUNITS;
;     for (int U = u_lo; U < u_hi; ++U) {
;         const int b = U >> 8, head = (U >> 5) & 7, T0 = 512 * (U & 31), tokb = b * 16384;
; #pragma unroll 1
;         for (int k = 0; k < 6; ++k) {
;             const int it = k * 8 + wave, g = it >> 4, sub = it & 15;
;             const int shift = 2 * g, L = 16384 >> shift;
;             const int r = (g == 0) ? 0 : (g == 1) ? (sub & 3) : sub;
;             const int m0 = (g == 0) ? (T0 + 32 * sub) : (g == 1) ? ((T0 >> 2) + 32 * (sub >> 2)) : (T0 >> 4);
;             const int mq = m0 + r32, tq = (mq << shift) + r;
;             const int rbase = tokb + (r << (14 - shift));
;             const char* qb = (const char*)(qkv + (size_t)((g * 3 + 0) * 8 + head) * PLANE + (size_t)(rbase + m0) * PITCH);
;             ATT_Q_DMA();
.LBB0_674:
	s_or_b64 exec, exec, s[8:9]
	s_abs_i32 s8, s24
	s_waitcnt lgkmcnt(0)
	v_cvt_f32_u32_e32 v0, s8
	s_sub_i32 s11, 0, s8
	s_add_i32 s9, s24, 0x1ff
	s_xor_b32 s10, s9, s24
	v_rcp_iflag_f32_e32 v0, v0
	s_abs_i32 s9, s9
	s_ashr_i32 s10, s10, 31
	s_setprio 0
	v_mov_b32_e32 v1, v252
	v_mul_f32_e32 v0, 0x4f7ffffe, v0
	v_cvt_u32_f32_e32 v0, v0
	s_barrier
	v_readfirstlane_b32 s12, v0
	s_mul_i32 s11, s11, s12
	s_mul_hi_u32 s11, s12, s11
	s_add_i32 s12, s12, s11
	s_mul_hi_u32 s11, s9, s12
	s_mul_i32 s12, s11, s8
	s_sub_i32 s9, s9, s12
	s_add_i32 s12, s11, 1
	s_sub_i32 s13, s9, s8
	s_cmp_ge_u32 s9, s8
	s_cselect_b32 s11, s12, s11
	s_cselect_b32 s9, s13, s9
	s_add_i32 s12, s11, 1
	s_cmp_ge_u32 s9, s8
	s_cselect_b32 s8, s12, s11
	s_xor_b32 s8, s8, s10
	s_sub_i32 s8, s8, s10
	s_mul_i32 s54, s8, s83
	s_add_i32 s8, s54, s8
	s_min_i32 s55, s8, 0x200
	v_add_u32_e32 v211, s81, v1
	s_cmp_ge_i32 s54, s55
	v_readfirstlane_b32 s8, v211
	s_cbranch_scc1 .LBB0_696
	s_mul_i32 s10, s2, 0x60000
	s_mul_hi_i32 s9, s2, 0x60000
	s_add_u32 s44, s16, s10
	s_addc_u32 s45, s17, s9
	s_ashr_i32 s56, s8, 6
	v_and_b32_e32 v212, 31, v211
	v_bfe_u32 v0, v211, 5, 1
	v_and_b32_e32 v1, 15, v211
	s_waitcnt vmcnt(8)
	v_and_b32_e32 v12, 12, v211
	s_lshl_b32 s57, s56, 14
	v_bfe_u32 v213, v211, 4, 2
	v_lshlrev_b32_e32 v4, 8, v212
	v_bitop3_b32 v2, v0, v211, 15 bitop3:0x78
	v_lshlrev_b32_e32 v1, 4, v1
	v_lshlrev_b32_e32 v215, 2, v0
	v_or_b32_e32 v15, v0, v12
	v_lshlrev_b32_e32 v0, 3, v0
	s_add_i32 s57, s57, 0
	v_lshlrev_b32_e32 v5, 4, v2
	v_lshlrev_b32_e32 v6, 8, v213
	v_bitop3_b32 v2, v213, v211, 15 bitop3:0x78
	v_lshlrev_b32_e32 v7, 6, v213
	v_or3_b32 v0, v1, v0, v4
	v_lshlrev_b32_e32 v2, 4, v2
	v_xor_b32_e32 v7, v7, v1
	v_lshrrev_b32_e32 v9, 3, v211
	v_add_u32_e32 v220, s57, v0
	v_or_b32_e32 v0, v6, v1
	v_mov_b32_e32 v1, 0
	v_bfe_u32 v8, v211, 2, 2
	v_and_b32_e32 v9, 2, v9
	v_bfe_u32 v10, v211, 1, 1
	v_lshl_add_u64 v[192:193], s[34:35], 0, v[0:1]
	v_xor_b32_e32 v0, 64, v2
	s_add_i32 s8, s57, 0x2000
	v_or_b32_e32 v11, v9, v10
	v_lshlrev_b32_e32 v13, 3, v211
	v_or_b32_e32 v14, v215, v8
	v_bitop3_b32 v9, v9, v15, v10 bitop3:0x36
	v_lshl_add_u64 v[196:197], s[44:45], 0, v[0:1]
	v_xor_b32_e32 v0, 0x80, v2
	v_and_or_b32 v13, v13, 8, s8
	v_lshlrev_b32_e32 v14, 8, v14
	v_lshlrev_b32_e32 v9, 4, v9
	v_lshl_add_u64 v[198:199], s[44:45], 0, v[0:1]
	v_xor_b32_e32 v0, 0xc0, v2
	v_add3_u32 v216, v14, v13, v9
	v_or_b32_e32 v9, 8, v215
	v_lshl_add_u64 v[200:201], s[44:45], 0, v[0:1]
	v_and_b32_e32 v0, 64, v252
	v_or_b32_e32 v8, v9, v8
	v_lshrrev_b32_e32 v9, 2, v9
	v_add_u32_e32 v0, 64, v0
	v_and_b32_e32 v3, 63, v211
	v_bitop3_b32 v9, v9, v11, v12 bitop3:0x36
	v_cmp_lt_i32_e32 vcc, v210, v0
	v_lshlrev_b32_e32 v8, 8, v8
	v_lshlrev_b32_e32 v9, 4, v9
	v_add3_u32 v218, s57, v4, v5
	v_add3_u32 v219, s8, v6, v7
	v_lshlrev_b32_e32 v4, 4, v3
	v_cmp_gt_u32_e64 s[8:9], 32, v3
	v_mov_b32_e32 v3, v1
	v_cndmask_b32_e32 v0, v252, v210, vcc
	v_or_b32_e32 v214, v2, v6
	v_add3_u32 v217, v8, v13, v9
	s_and_b32 s58, s56, 3
	v_xor_b32_e32 v221, 64, v220
	v_xor_b32_e32 v222, 0x50, v220
	v_xor_b32_e32 v223, 0x60, v220
	v_xor_b32_e32 v224, 0x70, v220
	v_xor_b32_e32 v225, 0x80, v220
	v_xor_b32_e32 v226, 0x90, v220
	v_xor_b32_e32 v227, 0xa0, v220
	v_xor_b32_e32 v228, 0xb0, v220
	v_xor_b32_e32 v229, 0xc0, v220
	v_xor_b32_e32 v230, 0xd0, v220
	v_xor_b32_e32 v231, 0xe0, v220
	v_xor_b32_e32 v232, 0xf0, v220
	v_lshl_add_u64 v[194:195], s[44:45], 0, v[2:3]
	v_lshlrev_b32_e32 v210, 2, v0
	v_sub_u32_e32 v233, v215, v212
	s_lshl_b32 s59, s54, 6
	s_lshl_b32 s60, s54, 9
	s_mov_b64 s[46:47], 0x1400
	s_mov_b64 s[48:49], 0x1800
	s_mov_b64 s[50:51], 0x1c00
	s_movk_i32 s61, 0x81
	v_add_u32_e32 v234, s57, v4
	s_mov_b32 s62, 0x20000
	s_mov_b32 s63, 0x40000
	s_mov_b32 s64, 0x22000
	s_mov_b32 s65, 0x42000
	s_mov_b32 s66, 0x24000
	s_mov_b32 s67, 0x44000
	s_movk_i32 s68, 0x6000
	s_mov_b32 s69, 0x26000
	s_mov_b32 s70, 0x46000
	v_mov_b32_e32 v235, 0xf149f2ca

; #define PG8_STAGE(bufoff, gbase, voff) do { _Pragma("unroll") for (int _i = 0; _i < 2; ++_i) \
;         __builtin_amdgcn_global_load_lds((const unsigned*)((const char*)(gbase) + (voff)[_i]), (PG8_LAS unsigned*)(lds + (bufoff) + ldsw + _i * 8192), 16, 0, 0); } while (0)
; #define PG8_WAIT_V(n) asm volatile("s_waitcnt vmcnt(" #n ")" ::: "memory")
; #define PG8_BAR __builtin_amdgcn_s_barrier()
; template <class Epi, class Sched, bool ALIGN_EPI = false, bool SP2 = false>
; __device__ __forceinline__ void gemm_phase(PG8_LAS unsigned char* lds, const Gemm g, const Sched& S, const Epi& E, int tid_in) {
;     int tid_ = tid_in; asm volatile("" : "+v"(tid_)); const int tid = tid_, wid = __builtin_amdgcn_readfirstlane(tid >> 6), lane = tid & 63, wr = wid >> 2, wc = wid & 3, fr = lane & 15, fq = lane >> 4;
;     const int K = g.K, nt = K / BK;
;     unsigned voffA[2], voffB[2];
; #pragma unroll
;     for (int i = 0; i < 2; ++i) { int R, C; stage_rc(tid * 16 + i * 8192, R, C); const int Rb = 2 * (R & ~31) + (Epi::PERM ? perm32(R & 31) : (R & 31));
;         voffA[i] = (unsigned)(R * g.lda + C) * 2u; voffB[i] = (unsigned)(Rb * K + C) * 2u; }
;     const size_t kstep = (size_t)(BK * 2);
;     const size_t hstep = (size_t)HALF * g.lda * 2;
;     const size_t hstepB = (size_t)32 * K * 2;
;     const size_t tstep = 2 * hstep, tstepB = (size_t)BM * K * 2;
;     const unsigned ldsw = (unsigned)wid * 1024u;
;     const int aoff = lds_byte(wr * 64 + fr, fq * 8), boff = lds_byte(wc * 32 + fr, fq * 8);
;     ...
;     Unit cur, nxt; int ui = 0;
;     if (!S.next(0, cur)) return;
;     f32x4 acc[2][2][4][2];
; #pragma unroll
;     for (int a = 0; a < 2; ++a)
; #pragma unroll
;         for (int b = 0; b < 2; ++b)
; #pragma unroll
;             for (int m = 0; m < 4; ++m)
; #pragma unroll
;                 for (int n = 0; n < 2; ++n) acc[a][b][m][n] = (f32x4){0.f, 0.f, 0.f, 0.f};
;     bf16x8 At[4][2], B0[2][2], B1[2][2];
;     const char* cA = (const char*)g.A + (size_t)cur.pm * tstep; const char* cB = (const char*)g.Bt + (size_t)cur.pn * tstepB;
;     S.a_ready(cur);
;     if constexpr (SP2) {
;         PG8_STAGE(PG8_SB(0, 0), cB, voffB); PG8_STAGE(PG8_SB(0, 1), cB + hstepB, voffB); PG8_STAGE(PG8_SA(0, 0), cA, voffA); PG8_STAGE(PG8_SA(0, 1), cA + hstep, voffA);
;         if (wr == 1) PG8_BAR;
;         PG8_WAIT_V(2); PG8_BAR;
.LBB0_754:
	s_add_u32 s12, s18, 0xc0000
	s_addc_u32 s13, s19, 0
	s_and_b64 vcc, exec, s[6:7]
	s_cbranch_vccnz .LBB0_790
	v_ashrrev_i32_e32 v1, 31, v8
	v_lshrrev_b32_e32 v1, 26, v1
	v_add_u32_e32 v1, v8, v1
	v_ashrrev_i32_e32 v9, 6, v1
	v_bfe_i32 v1, v8, 27, 1
	v_lshlrev_b32_e32 v0, 4, v8
	v_lshrrev_b32_e32 v1, 22, v1
	v_add_u32_e32 v1, v0, v1
	v_and_b32_e32 v1, 0xfffffc00, v1
	v_sub_u32_e32 v1, v0, v1
	v_lshrrev_b32_e32 v2, 4, v1
	v_bitop3_b32 v1, v2, v1, 32 bitop3:0x6c
	v_ashrrev_i32_e32 v3, 31, v1
	v_lshrrev_b32_e32 v3, 26, v3
	v_add_u32_e32 v3, v1, v3
	v_lshlrev_b32_e32 v2, 3, v9
	v_ashrrev_i32_e32 v10, 6, v3
	v_and_b32_e32 v3, 0xc0, v3
	v_and_b32_e32 v2, -16, v2
	v_sub_u32_e32 v1, v1, v3
	v_mov_b32_e32 v3, 1
	v_add_u32_e32 v2, v10, v2
	v_lshlrev_b32_e32 v4, 5, v9
	v_ashrrev_i16_sdwa v1, v3, sext(v1) dst_sel:DWORD dst_unused:UNUSED_PAD src0_sel:DWORD src1_sel:BYTE_0
	v_and_b32_e32 v4, 32, v4
	v_bfe_i32 v11, v1, 0, 16
	v_lshlrev_b32_e32 v1, 1, v2
	v_and_b32_e32 v5, 31, v2
	s_mov_b32 s9, 0x1fffc0
	v_and_or_b32 v1, v1, s9, v5
	v_add_lshl_u32 v4, v4, v11, 1
	v_add_u32_e32 v0, 0x2000, v0
	v_lshl_add_u32 v130, v1, 11, v4
	v_ashrrev_i32_e32 v1, 31, v0
	v_lshrrev_b32_e32 v1, 22, v1
	v_add_u32_e32 v1, v0, v1
	s_waitcnt vmcnt(8)
	v_ashrrev_i32_e32 v12, 10, v1
	v_mul_i32_i24_e32 v1, 0x400, v12
	v_sub_u32_e32 v0, v0, v1
	v_lshrrev_b32_e32 v1, 4, v0
	v_bitop3_b32 v0, v1, v0, 32 bitop3:0x6c
	v_lshl_add_u32 v128, v2, 11, v4
	v_ashrrev_i32_e32 v2, 31, v0
	v_lshrrev_b32_e32 v2, 26, v2
	v_add_u32_e32 v2, v0, v2
	v_lshlrev_b32_e32 v1, 3, v12
	v_ashrrev_i32_e32 v13, 6, v2
	v_and_b32_e32 v2, 0xc0, v2
	v_and_b32_e32 v1, -16, v1
	v_sub_u32_e32 v0, v0, v2
	v_add_u32_e32 v1, v13, v1
	v_ashrrev_i16_sdwa v0, v3, sext(v0) dst_sel:DWORD dst_unused:UNUSED_PAD src0_sel:DWORD src1_sel:BYTE_0
	s_ashr_i32 s8, s10, 6
	v_bfe_i32 v14, v0, 0, 16
	v_lshlrev_b32_e32 v0, 1, v1
	v_and_b32_e32 v2, 31, v1
	s_ashr_i32 s59, s58, 31
	s_ashr_i32 s61, s60, 31
	v_and_or_b32 v0, v0, s9, v2
	s_ashr_i32 s9, s10, 8
	s_lshl_b32 s68, s8, 10
	s_lshl_b64 s[26:27], s[58:59], 19
	s_lshl_b64 s[44:45], s[60:61], 19
	s_add_u32 s64, s36, s44
	v_lshlrev_b32_e32 v4, 5, v12
	s_addc_u32 s65, s37, s45
	s_add_i32 s61, s68, 0
	v_and_b32_e32 v4, 32, v4
	s_add_i32 m0, s61, 0x10000
	v_add_lshl_u32 v2, v4, v14, 1
	global_load_lds_dwordx4 v130, s[64:65]
	s_add_i32 m0, s61, 0x12000
	v_lshl_add_u32 v134, v0, 11, v2
	s_add_u32 s44, s64, 0x10000
	global_load_lds_dwordx4 v134, s[64:65]
	s_addc_u32 s45, s65, 0
	s_add_i32 m0, s61, 0x14000
	v_lshl_add_u32 v132, v1, 11, v2
	global_load_lds_dwordx4 v130, s[44:45]
	s_add_i32 m0, s61, 0x16000
	s_add_u32 s62, s38, s26
	s_addc_u32 s63, s39, s27
	s_add_i32 s69, s61, 0x2000
	global_load_lds_dwordx4 v134, s[44:45]
	s_mov_b32 m0, s61
	s_add_u32 s26, s62, 0x40000
	global_load_lds_dwordx4 v128, s[62:63]
	s_mov_b32 m0, s69
	s_addc_u32 s27, s63, 0
	s_add_i32 s70, s61, 0x4000
	global_load_lds_dwordx4 v132, s[62:63]
	s_mov_b32 m0, s70
	s_add_i32 s71, s61, 0x6000
	global_load_lds_dwordx4 v128, s[26:27]
	s_mov_b32 m0, s71
	v_mov_b32_e32 v131, 0
	global_load_lds_dwordx4 v132, s[26:27]
	v_mov_b32_e32 v135, v131
	v_mov_b32_e32 v129, v131
	v_mov_b32_e32 v133, v131
	s_cmp_eq_u32 s9, 1
	s_mov_b32 s72, 0
	v_lshl_add_u64 v[6:7], s[64:65], 0, v[130:131]
	v_lshl_add_u64 v[4:5], s[64:65], 0, v[134:135]
	v_lshl_add_u64 v[0:1], s[62:63], 0, v[128:129]
	s_cselect_b64 s[44:45], -1, 0
	s_cmp_lg_u32 s9, 1
	v_lshl_add_u64 v[2:3], s[62:63], 0, v[132:133]
	s_cbranch_scc1 .LBB0_757
	s_barrier
	s_setprio 1

; #define PG8_STAGE(bufoff, gbase, voff) do { _Pragma("unroll") for (int _i = 0; _i < 2; ++_i) \
;         __builtin_amdgcn_global_load_lds((const unsigned*)((const char*)(gbase) + (voff)[_i]), (PG8_LAS unsigned*)(lds + (bufoff) + ldsw + _i * 8192), 16, 0, 0); } while (0)
; #define PG8_LDA(dst, b, h) do { _Pragma("unroll") for (int m = 0; m < 4; ++m) _Pragma("unroll") for (int k = 0; k < 2; ++k) dst[m][k] = *(const PG8_LAS bf16x8*)(lds + PG8_SA(b, h) + aoff + m * 2048 + k * 1024); } while (0)
; #define PG8_LDB(dst, b, h) do { _Pragma("unroll") for (int n = 0; n < 2; ++n) _Pragma("unroll") for (int k = 0; k < 2; ++k) dst[n][k] = *(const PG8_LAS bf16x8*)(lds + PG8_SB(b, h) + boff + n * 2048 + k * 1024); } while (0)
; #define PG8_MMA(ai, bj, At, Bt) do { __builtin_amdgcn_s_setprio(1); _Pragma("unroll") for (int m = 0; m < 4; ++m) _Pragma("unroll") for (int n = 0; n < 2; ++n) _Pragma("unroll") for (int k = 0; k < 2; ++k) \
;         acc[ai][bj][m][n] = __builtin_amdgcn_mfma_f32_16x16x32_bf16(Bt[n][k], At[m][k], acc[ai][bj][m][n], 0, 0, 0); __builtin_amdgcn_s_setprio(0); } while (0)
; #define PG8_WAIT_V(n) asm volatile("s_waitcnt vmcnt(" #n ")" ::: "memory")
; #define PG8_WAIT_L(n) asm volatile("s_waitcnt lgkmcnt(" #n ")" ::: "memory")
; #define PG8_BAR __builtin_amdgcn_s_barrier()
; #define PG8_SCHED __builtin_amdgcn_sched_barrier(0)
; template <class Epi, class Sched, bool ALIGN_EPI = false, bool SP2 = false>
; __device__ __forceinline__ void gemm_phase(PG8_LAS unsigned char* lds, const Gemm g, const Sched& S, const Epi& E, int tid_in) {
;     ...
;             PG8_LDB(B0, 0, 0); PG8_LDB(B1, 0, 1); PG8_SCHED; PG8_LDA(At, 0, 0); PG8_STAGE(PG8_SA(1, 1), a1 + hstep, voffA);
;             PG8_WAIT_V(8); PG8_WAIT_L(0); PG8_BAR; PG8_MMA(0, 0, At, B0); PG8_MMA(0, 1, At, B1); PG8_BAR; PG8_SCHED;
;             PG8_LDA(At, 0, 1); PG8_STAGE(PG8_SB(0, 0), b2, voffB); PG8_STAGE(PG8_SB(0, 1), b2 + hstepB, voffB); PG8_STAGE(PG8_SA(0, 0), a2, voffA);
;             PG8_WAIT_V(8); PG8_WAIT_L(0); PG8_BAR; PG8_MMA(1, 0, At, B0); PG8_MMA(1, 1, At, B1); PG8_BAR; PG8_SCHED;
.Lkb_skip_5:
.LBB0_767:
	ds_read_b128 v[146:149], v153
	ds_read_b128 v[158:161], v153 offset:1024
	ds_read_b128 v[162:165], v153 offset:2048
	ds_read_b128 v[166:169], v153 offset:3072
	ds_read_b128 v[170:173], v154
	ds_read_b128 v[174:177], v154 offset:1024
	ds_read_b128 v[178:181], v154 offset:2048
	ds_read_b128 v[182:185], v154 offset:3072
	s_add_u32 s26, s62, 0xfffc0080
	s_addc_u32 s27, s63, -1
	s_cmp_eq_u32 s83, 12
	s_cselect_b32 s67, s53, s27
	s_cselect_b32 s66, s59, s26
	s_cselect_b32 s65, s51, s79
	s_cselect_b32 s64, s77, s78
	v_lshl_add_u64 v[218:219], s[62:63], 0, v[138:139]
	s_add_i32 m0, s61, 0xc000
	ds_read_b128 v[186:189], v155
	ds_read_b128 v[190:193], v155 offset:1024
	ds_read_b128 v[194:197], v155 offset:2048
	ds_read_b128 v[198:201], v155 offset:3072
	ds_read_b128 v[202:205], v155 offset:4096
	ds_read_b128 v[206:209], v155 offset:5120
	ds_read_b128 v[210:213], v155 offset:6144
	ds_read_b128 v[214:217], v155 offset:7168
	global_load_lds_dwordx4 v[218:219], off
	v_lshl_add_u64 v[218:219], s[62:63], 0, v[140:141]
	s_add_i32 m0, s61, 0xe000
	s_nop 0
	global_load_lds_dwordx4 v[218:219], off
	s_waitcnt vmcnt(8)
	s_waitcnt lgkmcnt(0)
	s_barrier
	s_waitcnt lgkmcnt(0)
	v_mfma_f32_16x16x32_bf16 v[124:127], v[146:149], v[186:189], v[124:127]
	v_mfma_f32_16x16x32_bf16 v[120:123], v[162:165], v[186:189], v[120:123]
	v_mfma_f32_16x16x32_bf16 v[108:111], v[146:149], v[194:197], v[108:111]
	v_mfma_f32_16x16x32_bf16 v[104:107], v[162:165], v[194:197], v[104:107]
	v_mfma_f32_16x16x32_bf16 v[92:95], v[146:149], v[202:205], v[92:95]
	v_mfma_f32_16x16x32_bf16 v[88:91], v[162:165], v[202:205], v[88:91]
	v_mfma_f32_16x16x32_bf16 v[76:79], v[146:149], v[210:213], v[76:79]
	v_mfma_f32_16x16x32_bf16 v[72:75], v[162:165], v[210:213], v[72:75]
	v_mfma_f32_16x16x32_bf16 v[124:127], v[158:161], v[190:193], v[124:127]
	v_mfma_f32_16x16x32_bf16 v[120:123], v[166:169], v[190:193], v[120:123]
	v_mfma_f32_16x16x32_bf16 v[108:111], v[158:161], v[198:201], v[108:111]
	v_mfma_f32_16x16x32_bf16 v[104:107], v[166:169], v[198:201], v[104:107]
	v_mfma_f32_16x16x32_bf16 v[92:95], v[158:161], v[206:209], v[92:95]
	v_mfma_f32_16x16x32_bf16 v[88:91], v[166:169], v[206:209], v[88:91]
	v_mfma_f32_16x16x32_bf16 v[76:79], v[158:161], v[214:217], v[76:79]
	v_mfma_f32_16x16x32_bf16 v[72:75], v[166:169], v[214:217], v[72:75]
	v_mfma_f32_16x16x32_bf16 v[116:119], v[170:173], v[186:189], v[116:119]
	v_mfma_f32_16x16x32_bf16 v[112:115], v[178:181], v[186:189], v[112:115]
	v_mfma_f32_16x16x32_bf16 v[100:103], v[170:173], v[194:197], v[100:103]
	v_mfma_f32_16x16x32_bf16 v[96:99], v[178:181], v[194:197], v[96:99]
	v_mfma_f32_16x16x32_bf16 v[84:87], v[170:173], v[202:205], v[84:87]
	v_mfma_f32_16x16x32_bf16 v[80:83], v[178:181], v[202:205], v[80:83]
	v_mfma_f32_16x16x32_bf16 v[68:71], v[170:173], v[210:213], v[68:71]
	v_mfma_f32_16x16x32_bf16 v[64:67], v[178:181], v[210:213], v[64:67]
	v_mfma_f32_16x16x32_bf16 v[116:119], v[174:177], v[190:193], v[116:119]
	v_mfma_f32_16x16x32_bf16 v[112:115], v[182:185], v[190:193], v[112:115]
	v_mfma_f32_16x16x32_bf16 v[100:103], v[174:177], v[198:201], v[100:103]
	v_mfma_f32_16x16x32_bf16 v[96:99], v[182:185], v[198:201], v[96:99]
	v_mfma_f32_16x16x32_bf16 v[84:87], v[174:177], v[206:209], v[84:87]
	v_mfma_f32_16x16x32_bf16 v[80:83], v[182:185], v[206:209], v[80:83]
	v_mfma_f32_16x16x32_bf16 v[68:71], v[174:177], v[214:217], v[68:71]
	v_mfma_f32_16x16x32_bf16 v[64:67], v[182:185], v[214:217], v[64:67]
	s_barrier
	s_add_i32 s26, s75, s68
	v_lshl_add_u64 v[218:219], s[64:65], 0, v[130:131]
	s_mov_b32 m0, s26
	ds_read_b128 v[186:189], v155 offset:16384
	ds_read_b128 v[190:193], v155 offset:17408
	ds_read_b128 v[194:197], v155 offset:18432
	ds_read_b128 v[198:201], v155 offset:19456
	ds_read_b128 v[202:205], v155 offset:20480
	ds_read_b128 v[206:209], v155 offset:21504
	ds_read_b128 v[210:213], v155 offset:22528
	ds_read_b128 v[214:217], v155 offset:23552
	global_load_lds_dwordx4 v[218:219], off
	s_add_i32 m0, s26, 0x2000
	s_add_u32 s26, s64, 0x10000
	v_lshl_add_u64 v[220:221], s[64:65], 0, v[134:135]
	s_addc_u32 s27, s65, 0
	s_add_i32 s33, s76, s68
	global_load_lds_dwordx4 v[220:221], off
	v_lshl_add_u64 v[222:223], s[26:27], 0, v[130:131]
	s_mov_b32 m0, s33
	v_lshl_add_u64 v[224:225], s[66:67], 0, v[132:133]
	global_load_lds_dwordx4 v[222:223], off
	v_lshl_add_u64 v[222:223], s[26:27], 0, v[134:135]
	s_add_i32 m0, s33, 0x2000
	s_nop 0
	global_load_lds_dwordx4 v[222:223], off
	v_lshl_add_u64 v[222:223], s[66:67], 0, v[128:129]
	s_mov_b32 m0, s61
	s_nop 0
	global_load_lds_dwordx4 v[222:223], off
	s_mov_b32 m0, s69
	s_nop 0
	global_load_lds_dwordx4 v[224:225], off
	s_waitcnt vmcnt(8)
	s_waitcnt lgkmcnt(0)
	s_barrier
; #define PG8_STAGE(bufoff, gbase, voff) do { _Pragma("unroll") for (int _i = 0; _i < 2; ++_i) \
;         __builtin_amdgcn_global_load_lds((const unsigned*)((const char*)(gbase) + (voff)[_i]), (PG8_LAS unsigned*)(lds + (bufoff) + ldsw + _i * 8192), 16, 0, 0); } while (0)
; #define PG8_LDA(dst, b, h) do { _Pragma("unroll") for (int m = 0; m < 4; ++m) _Pragma("unroll") for (int k = 0; k < 2; ++k) dst[m][k] = *(const PG8_LAS bf16x8*)(lds + PG8_SA(b, h) + aoff + m * 2048 + k * 1024); } while (0)
; #define PG8_LDB(dst, b, h) do { _Pragma("unroll") for (int n = 0; n < 2; ++n) _Pragma("unroll") for (int k = 0; k < 2; ++k) dst[n][k] = *(const PG8_LAS bf16x8*)(lds + PG8_SB(b, h) + boff + n * 2048 + k * 1024); } while (0)
; #define PG8_MMA(ai, bj, At, Bt) do { __builtin_amdgcn_s_setprio(1); _Pragma("unroll") for (int m = 0; m < 4; ++m) _Pragma("unroll") for (int n = 0; n < 2; ++n) _Pragma("unroll") for (int k = 0; k < 2; ++k) \
;         acc[ai][bj][m][n] = __builtin_amdgcn_mfma_f32_16x16x32_bf16(Bt[n][k], At[m][k], acc[ai][bj][m][n], 0, 0, 0); __builtin_amdgcn_s_setprio(0); } while (0)
; #define PG8_WAIT_V(n) asm volatile("s_waitcnt vmcnt(" #n ")" ::: "memory")
; #define PG8_WAIT_L(n) asm volatile("s_waitcnt lgkmcnt(" #n ")" ::: "memory")
; #define PG8_BAR __builtin_amdgcn_s_barrier()
; #define PG8_SCHED __builtin_amdgcn_sched_barrier(0)
; template <class Epi, class Sched, bool ALIGN_EPI = false, bool SP2 = false>
; __device__ __forceinline__ void gemm_phase(PG8_LAS unsigned char* lds, const Gemm g, const Sched& S, const Epi& E, int tid_in) {
;     ...
;             PG8_WAIT_V(8); PG8_WAIT_L(0); PG8_BAR; PG8_MMA(1, 0, At, B0); PG8_MMA(1, 1, At, B1); PG8_BAR; PG8_SCHED;
;             PG8_LDB(B0, 1, 0); PG8_LDB(B1, 1, 1); PG8_SCHED; PG8_LDA(At, 1, 0); PG8_STAGE(PG8_SA(0, 1), a2 + hstep, voffA);
;             PG8_WAIT_V(8); PG8_WAIT_L(0); PG8_BAR; PG8_MMA(0, 0, At, B0); PG8_MMA(0, 1, At, B1); PG8_BAR; PG8_SCHED;
	s_waitcnt lgkmcnt(0)
	v_mfma_f32_16x16x32_bf16 v[60:63], v[146:149], v[186:189], v[60:63]
	v_mfma_f32_16x16x32_bf16 v[56:59], v[162:165], v[186:189], v[56:59]
	v_mfma_f32_16x16x32_bf16 v[44:47], v[146:149], v[194:197], v[44:47]
	v_mfma_f32_16x16x32_bf16 v[40:43], v[162:165], v[194:197], v[40:43]
	v_mfma_f32_16x16x32_bf16 v[28:31], v[146:149], v[202:205], v[28:31]
	v_mfma_f32_16x16x32_bf16 v[24:27], v[162:165], v[202:205], v[24:27]
	v_mfma_f32_16x16x32_bf16 v[12:15], v[146:149], v[210:213], v[12:15]
	v_mfma_f32_16x16x32_bf16 v[8:11], v[162:165], v[210:213], v[8:11]
	v_mfma_f32_16x16x32_bf16 v[60:63], v[158:161], v[190:193], v[60:63]
	v_mfma_f32_16x16x32_bf16 v[56:59], v[166:169], v[190:193], v[56:59]
	v_mfma_f32_16x16x32_bf16 v[44:47], v[158:161], v[198:201], v[44:47]
	v_mfma_f32_16x16x32_bf16 v[40:43], v[166:169], v[198:201], v[40:43]
	v_mfma_f32_16x16x32_bf16 v[28:31], v[158:161], v[206:209], v[28:31]
	v_mfma_f32_16x16x32_bf16 v[24:27], v[166:169], v[206:209], v[24:27]
	v_mfma_f32_16x16x32_bf16 v[12:15], v[158:161], v[214:217], v[12:15]
	v_mfma_f32_16x16x32_bf16 v[8:11], v[166:169], v[214:217], v[8:11]
	v_mfma_f32_16x16x32_bf16 v[52:55], v[170:173], v[186:189], v[52:55]
	v_mfma_f32_16x16x32_bf16 v[48:51], v[178:181], v[186:189], v[48:51]
	v_mfma_f32_16x16x32_bf16 v[36:39], v[170:173], v[194:197], v[36:39]
	v_mfma_f32_16x16x32_bf16 v[32:35], v[178:181], v[194:197], v[32:35]
	v_mfma_f32_16x16x32_bf16 v[20:23], v[170:173], v[202:205], v[20:23]
	v_mfma_f32_16x16x32_bf16 v[16:19], v[178:181], v[202:205], v[16:19]
	v_mfma_f32_16x16x32_bf16 v[4:7], v[170:173], v[210:213], v[4:7]
	v_mfma_f32_16x16x32_bf16 v[0:3], v[178:181], v[210:213], v[0:3]
	v_mfma_f32_16x16x32_bf16 v[52:55], v[174:177], v[190:193], v[52:55]
	v_mfma_f32_16x16x32_bf16 v[48:51], v[182:185], v[190:193], v[48:51]
	v_mfma_f32_16x16x32_bf16 v[36:39], v[174:177], v[198:201], v[36:39]
	v_mfma_f32_16x16x32_bf16 v[32:35], v[182:185], v[198:201], v[32:35]
	v_mfma_f32_16x16x32_bf16 v[20:23], v[174:177], v[206:209], v[20:23]
	v_mfma_f32_16x16x32_bf16 v[16:19], v[182:185], v[206:209], v[16:19]
	v_mfma_f32_16x16x32_bf16 v[4:7], v[174:177], v[214:217], v[4:7]
	v_mfma_f32_16x16x32_bf16 v[0:3], v[182:185], v[214:217], v[0:3]
	s_barrier
	s_add_i32 s33, 0, 0x18000
	s_add_i32 s84, 0, 0x1c000
	v_add_u32_e32 v166, s33, v137
	v_add_u32_e32 v182, s84, v137
	ds_read_b128 v[146:149], v166
	ds_read_b128 v[158:161], v166 offset:1024
	ds_read_b128 v[162:165], v166 offset:2048
	ds_read_b128 v[166:169], v166 offset:3072
	ds_read_b128 v[170:173], v182
	ds_read_b128 v[174:177], v182 offset:1024
	ds_read_b128 v[178:181], v182 offset:2048
	ds_read_b128 v[182:185], v182 offset:3072
	s_add_u32 s26, s66, 0x40000
	s_addc_u32 s27, s67, 0
	s_mov_b32 m0, s70
	v_lshl_add_u64 v[226:227], s[26:27], 0, v[128:129]
	ds_read_b128 v[186:189], v155 offset:32768
	ds_read_b128 v[190:193], v155 offset:33792
	ds_read_b128 v[194:197], v155 offset:34816
	ds_read_b128 v[198:201], v155 offset:35840
	ds_read_b128 v[202:205], v155 offset:36864
	ds_read_b128 v[206:209], v155 offset:37888
	ds_read_b128 v[210:213], v155 offset:38912
	ds_read_b128 v[214:217], v155 offset:39936
	global_load_lds_dwordx4 v[226:227], off
	v_lshl_add_u64 v[226:227], s[26:27], 0, v[132:133]
	s_mov_b32 m0, s71
	s_nop 0
	global_load_lds_dwordx4 v[226:227], off
	s_waitcnt vmcnt(8)
	s_waitcnt lgkmcnt(0)
	s_barrier
	s_waitcnt lgkmcnt(0)
	v_mfma_f32_16x16x32_bf16 v[124:127], v[146:149], v[186:189], v[124:127]
	v_mfma_f32_16x16x32_bf16 v[120:123], v[162:165], v[186:189], v[120:123]
	v_mfma_f32_16x16x32_bf16 v[108:111], v[146:149], v[194:197], v[108:111]
	v_mfma_f32_16x16x32_bf16 v[104:107], v[162:165], v[194:197], v[104:107]
	v_mfma_f32_16x16x32_bf16 v[92:95], v[146:149], v[202:205], v[92:95]
	v_mfma_f32_16x16x32_bf16 v[88:91], v[162:165], v[202:205], v[88:91]
	v_mfma_f32_16x16x32_bf16 v[76:79], v[146:149], v[210:213], v[76:79]
	v_mfma_f32_16x16x32_bf16 v[72:75], v[162:165], v[210:213], v[72:75]
	v_mfma_f32_16x16x32_bf16 v[124:127], v[158:161], v[190:193], v[124:127]
	v_mfma_f32_16x16x32_bf16 v[120:123], v[166:169], v[190:193], v[120:123]
	v_mfma_f32_16x16x32_bf16 v[108:111], v[158:161], v[198:201], v[108:111]
	v_mfma_f32_16x16x32_bf16 v[104:107], v[166:169], v[198:201], v[104:107]
	v_mfma_f32_16x16x32_bf16 v[92:95], v[158:161], v[206:209], v[92:95]
	v_mfma_f32_16x16x32_bf16 v[88:91], v[166:169], v[206:209], v[88:91]
	v_mfma_f32_16x16x32_bf16 v[76:79], v[158:161], v[214:217], v[76:79]
	v_mfma_f32_16x16x32_bf16 v[72:75], v[166:169], v[214:217], v[72:75]
	v_mfma_f32_16x16x32_bf16 v[116:119], v[170:173], v[186:189], v[116:119]
	v_mfma_f32_16x16x32_bf16 v[112:115], v[178:181], v[186:189], v[112:115]
	v_mfma_f32_16x16x32_bf16 v[100:103], v[170:173], v[194:197], v[100:103]
	v_mfma_f32_16x16x32_bf16 v[96:99], v[178:181], v[194:197], v[96:99]
	v_mfma_f32_16x16x32_bf16 v[84:87], v[170:173], v[202:205], v[84:87]
	v_mfma_f32_16x16x32_bf16 v[80:83], v[178:181], v[202:205], v[80:83]
	v_mfma_f32_16x16x32_bf16 v[68:71], v[170:173], v[210:213], v[68:71]
	v_mfma_f32_16x16x32_bf16 v[64:67], v[178:181], v[210:213], v[64:67]
	v_mfma_f32_16x16x32_bf16 v[116:119], v[174:177], v[190:193], v[116:119]
	v_mfma_f32_16x16x32_bf16 v[112:115], v[182:185], v[190:193], v[112:115]
	v_mfma_f32_16x16x32_bf16 v[100:103], v[174:177], v[198:201], v[100:103]
	v_mfma_f32_16x16x32_bf16 v[96:99], v[182:185], v[198:201], v[96:99]
	v_mfma_f32_16x16x32_bf16 v[84:87], v[174:177], v[206:209], v[84:87]
	v_mfma_f32_16x16x32_bf16 v[80:83], v[182:185], v[206:209], v[80:83]
	v_mfma_f32_16x16x32_bf16 v[68:71], v[174:177], v[214:217], v[68:71]
	v_mfma_f32_16x16x32_bf16 v[64:67], v[182:185], v[214:217], v[64:67]
	s_barrier
; #define PG8_STAGE(bufoff, gbase, voff) do { _Pragma("unroll") for (int _i = 0; _i < 2; ++_i) \
;         __builtin_amdgcn_global_load_lds((const unsigned*)((const char*)(gbase) + (voff)[_i]), (PG8_LAS unsigned*)(lds + (bufoff) + ldsw + _i * 8192), 16, 0, 0); } while (0)
; #define PG8_LDA(dst, b, h) do { _Pragma("unroll") for (int m = 0; m < 4; ++m) _Pragma("unroll") for (int k = 0; k < 2; ++k) dst[m][k] = *(const PG8_LAS bf16x8*)(lds + PG8_SA(b, h) + aoff + m * 2048 + k * 1024); } while (0)
; #define PG8_MMA(ai, bj, At, Bt) do { __builtin_amdgcn_s_setprio(1); _Pragma("unroll") for (int m = 0; m < 4; ++m) _Pragma("unroll") for (int n = 0; n < 2; ++n) _Pragma("unroll") for (int k = 0; k < 2; ++k) \
;         acc[ai][bj][m][n] = __builtin_amdgcn_mfma_f32_16x16x32_bf16(Bt[n][k], At[m][k], acc[ai][bj][m][n], 0, 0, 0); __builtin_amdgcn_s_setprio(0); } while (0)
; #define PG8_WAIT_V(n) asm volatile("s_waitcnt vmcnt(" #n ")" ::: "memory")
; #define PG8_WAIT_L(n) asm volatile("s_waitcnt lgkmcnt(" #n ")" ::: "memory")
; #define PG8_BAR __builtin_amdgcn_s_barrier()
; template <class Epi, class Sched, bool ALIGN_EPI = false, bool SP2 = false>
; __device__ __forceinline__ void gemm_phase(PG8_LAS unsigned char* lds, const Gemm g, const Sched& S, const Epi& E, int tid_in) {
;     ...
;             PG8_LDA(At, 1, 1); PG8_STAGE(PG8_SB(1, 0), b3, voffB); PG8_STAGE(PG8_SB(1, 1), b3 + hstepB, voffB); PG8_STAGE(PG8_SA(1, 0), a3, voffA);
;             PG8_WAIT_V(8); PG8_WAIT_L(0); PG8_BAR; PG8_MMA(1, 0, At, B0); PG8_MMA(1, 1, At, B1); PG8_BAR; PG8_SCHED;
;     __device__ __forceinline__ void operator()(const f32x4 (&acc)[2][2][4][2], const Unit& u, int wr, int wc, int fr, int fq) const {
;     ...
;                     const size_t off = (size_t)row * 2048 + u.pn * BM + wc * 64 + bj * 32 + 8 * p;
;                     f32x4 b0, b1;
;                     if (BASE_F32) { b0 = *(const f32x4*)((const float*)base + off); b1 = *(const f32x4*)((const float*)base + off + 4); }
;                     else { const u32x4 bb = *(const u32x4*)((const bf16_t*)base + off);
;                         b0 = (f32x4){__uint_as_float(bb.x << 16), __uint_as_float(bb.x & 0xffff0000u), __uint_as_float(bb.y << 16), __uint_as_float(bb.y & 0xffff0000u)};
;                         b1 = (f32x4){__uint_as_float(bb.z << 16), __uint_as_float(bb.z & 0xffff0000u), __uint_as_float(bb.w << 16), __uint_as_float(bb.w & 0xffff0000u)}; }
	s_add_i32 s26, s33, s68
	v_lshl_add_u64 v[218:219], v[218:219], 0, s[46:47]
	s_mov_b32 m0, s26
	ds_read_b128 v[186:189], v155 offset:49152
	ds_read_b128 v[190:193], v155 offset:50176
	ds_read_b128 v[194:197], v155 offset:51200
	ds_read_b128 v[198:201], v155 offset:52224
	ds_read_b128 v[202:205], v155 offset:53248
	ds_read_b128 v[206:209], v155 offset:54272
	ds_read_b128 v[210:213], v155 offset:55296
	ds_read_b128 v[214:217], v155 offset:56320
	global_load_lds_dwordx4 v[218:219], off
	s_add_i32 m0, s26, 0x2000
	s_add_u32 s26, s64, 0x10080
	v_lshl_add_u64 v[218:219], v[220:221], 0, s[46:47]
	s_addc_u32 s27, s65, 0
	s_add_i32 s33, s84, s68
	global_load_lds_dwordx4 v[218:219], off
	v_lshl_add_u64 v[218:219], s[26:27], 0, v[130:131]
	s_mov_b32 m0, s33
	s_nop 0
	global_load_lds_dwordx4 v[218:219], off
	v_lshl_add_u64 v[218:219], s[26:27], 0, v[134:135]
	s_add_i32 m0, s33, 0x2000
	s_nop 0
	global_load_lds_dwordx4 v[218:219], off
	v_lshl_add_u64 v[218:219], v[222:223], 0, s[46:47]
	s_mov_b32 m0, s73
	s_nop 0
	global_load_lds_dwordx4 v[218:219], off
	v_lshl_add_u64 v[218:219], v[224:225], 0, s[46:47]
	s_mov_b32 m0, s74
	s_nop 0
	global_load_lds_dwordx4 v[218:219], off
	s_waitcnt vmcnt(8)
	s_waitcnt lgkmcnt(0)
	s_barrier
	s_waitcnt lgkmcnt(0)
	v_mfma_f32_16x16x32_bf16 v[60:63], v[146:149], v[186:189], v[60:63]
	v_mfma_f32_16x16x32_bf16 v[56:59], v[162:165], v[186:189], v[56:59]
	v_mfma_f32_16x16x32_bf16 v[44:47], v[146:149], v[194:197], v[44:47]
	v_mfma_f32_16x16x32_bf16 v[40:43], v[162:165], v[194:197], v[40:43]
	v_mfma_f32_16x16x32_bf16 v[28:31], v[146:149], v[202:205], v[28:31]
	v_mfma_f32_16x16x32_bf16 v[24:27], v[162:165], v[202:205], v[24:27]
	v_mfma_f32_16x16x32_bf16 v[12:15], v[146:149], v[210:213], v[12:15]
	v_mfma_f32_16x16x32_bf16 v[8:11], v[162:165], v[210:213], v[8:11]
	v_mfma_f32_16x16x32_bf16 v[60:63], v[158:161], v[190:193], v[60:63]
	v_mfma_f32_16x16x32_bf16 v[56:59], v[166:169], v[190:193], v[56:59]
	v_mfma_f32_16x16x32_bf16 v[44:47], v[158:161], v[198:201], v[44:47]
	v_mfma_f32_16x16x32_bf16 v[40:43], v[166:169], v[198:201], v[40:43]
	v_mfma_f32_16x16x32_bf16 v[28:31], v[158:161], v[206:209], v[28:31]
	v_mfma_f32_16x16x32_bf16 v[24:27], v[166:169], v[206:209], v[24:27]
	v_mfma_f32_16x16x32_bf16 v[12:15], v[158:161], v[214:217], v[12:15]
	v_mfma_f32_16x16x32_bf16 v[8:11], v[166:169], v[214:217], v[8:11]
	v_mfma_f32_16x16x32_bf16 v[52:55], v[170:173], v[186:189], v[52:55]
	v_mfma_f32_16x16x32_bf16 v[48:51], v[178:181], v[186:189], v[48:51]
	v_mfma_f32_16x16x32_bf16 v[36:39], v[170:173], v[194:197], v[36:39]
	v_mfma_f32_16x16x32_bf16 v[32:35], v[178:181], v[194:197], v[32:35]
	v_mfma_f32_16x16x32_bf16 v[20:23], v[170:173], v[202:205], v[20:23]
	v_mfma_f32_16x16x32_bf16 v[16:19], v[178:181], v[202:205], v[16:19]
	v_mfma_f32_16x16x32_bf16 v[4:7], v[170:173], v[210:213], v[4:7]
	v_mfma_f32_16x16x32_bf16 v[0:3], v[178:181], v[210:213], v[0:3]
	v_mfma_f32_16x16x32_bf16 v[52:55], v[174:177], v[190:193], v[52:55]
	v_mfma_f32_16x16x32_bf16 v[48:51], v[182:185], v[190:193], v[48:51]
	v_mfma_f32_16x16x32_bf16 v[36:39], v[174:177], v[198:201], v[36:39]
	v_mfma_f32_16x16x32_bf16 v[32:35], v[182:185], v[198:201], v[32:35]
	v_mfma_f32_16x16x32_bf16 v[20:23], v[174:177], v[206:209], v[20:23]
	v_mfma_f32_16x16x32_bf16 v[16:19], v[182:185], v[206:209], v[16:19]
	v_mfma_f32_16x16x32_bf16 v[4:7], v[174:177], v[214:217], v[4:7]
	v_mfma_f32_16x16x32_bf16 v[0:3], v[182:185], v[214:217], v[0:3]
	s_barrier
	s_add_i32 s83, s83, 2
	s_add_u32 s62, s62, 0x100
	s_addc_u32 s63, s63, 0
	s_add_u32 s78, s78, 0x100
	s_addc_u32 s79, s79, 0
	s_cmp_gt_u32 s83, 13
	s_cbranch_scc0 .LBB0_767
	v_lshl_add_u32 v148, s58, 8, v150
	v_lshl_or_b32 v146, s60, 8, v136
	v_lshl_add_u32 v147, v148, 11, v146
	v_lshlrev_b32_e32 v159, 1, v147
	v_lshlrev_b32_e32 v208, 3, v148
	global_load_dwordx4 v[160:163], v159, s[28:29]
	global_load_dwordx4 v[164:167], v159, s[28:29] offset:64
	v_add_u32_e32 v149, 0x10000, v159
	global_load_dwordx4 v[168:171], v149, s[28:29]
	global_load_dwordx4 v[172:175], v149, s[28:29] offset:64
	v_add_u32_e32 v209, 0x20000, v159
	global_load_dwordx4 v[176:179], v209, s[28:29]
	global_load_dwordx4 v[180:183], v209, s[28:29] offset:64
	v_add_u32_e32 v149, 0x30000, v159
	global_load_dwordx4 v[184:187], v149, s[28:29]
	global_load_dwordx4 v[188:191], v149, s[28:29] offset:64
	v_add_u32_e32 v209, 0x80000, v159
	global_load_dwordx4 v[192:195], v209, s[28:29]
	global_load_dwordx4 v[196:199], v209, s[28:29] offset:64
	v_add_u32_e32 v149, 0x90000, v159
	global_load_dwordx4 v[200:203], v149, s[28:29]
	global_load_dwordx4 v[204:207], v149, s[28:29] offset:64
	v_add_u32_e32 v209, 0xa0000, v159
	global_load_dwordx4 v[212:215], v209, s[28:29]
	global_load_dwordx4 v[216:219], v209, s[28:29] offset:64
	v_add_u32_e32 v149, 0xb0000, v159
	global_load_dwordx4 v[220:223], v149, s[28:29]
	global_load_dwordx4 v[224:227], v149, s[28:29] offset:64
	s_and_b64 vcc, exec, s[48:49]
	s_cbranch_vccz .LBB0_770
	s_barrier

;     __host__ __device__ bool next(int i, Unit& u) const {
;         const long L = (long)i * G + c; if (L >= nwg) return false;
;         int wgid = (int)L; { const int q = nwg / NXCD, r = nwg % NXCD, xcd = wgid % NXCD, off = wgid / NXCD; wgid = (xcd < r ? xcd * (q + 1) : r * (q + 1) + (xcd - r) * q) + off; }
;         const int nig = wgm * nN, gid = wgid / nig, fm = gid * wgm, gsz = (nM - fm) < wgm ? (nM - fm) : wgm;
;         u.pm = fm + ((wgid % nig) % gsz); u.pn = (wgid % nig) / gsz; return true;
.LBB0_852:
	s_setprio 0
	v_mov_b32_e32 v0, v252
	s_waitcnt lgkmcnt(0)
	s_barrier
	s_andn2_b64 vcc, exec, s[40:41]
	v_add_u32_e32 v8, s81, v0
	s_nop 0
	v_readfirstlane_b32 s36, v8
	s_cbranch_vccnz .LBB0_876
	s_lshr_b32 s8, s3, 29
	s_add_i32 s11, s2, s8
	s_and_b32 s8, s11, -8
	s_sub_i32 s12, s2, s8
	s_cmp_gt_i32 s12, -1
	s_cbranch_scc0 .LBB0_855
	s_lshl_b32 s10, s12, 9
	s_cbranch_execz .LBB0_856
	s_branch .LBB0_857

; #define PG8_STAGE(bufoff, gbase, voff) do { _Pragma("unroll") for (int _i = 0; _i < 2; ++_i) \
;         __builtin_amdgcn_global_load_lds((const unsigned*)((const char*)(gbase) + (voff)[_i]), (PG8_LAS unsigned*)(lds + (bufoff) + ldsw + _i * 8192), 16, 0, 0); } while (0)
; #define PG8_WAIT_V(n) asm volatile("s_waitcnt vmcnt(" #n ")" ::: "memory")
; #define PG8_BAR __builtin_amdgcn_s_barrier()
; template <class Epi, class Sched, bool ALIGN_EPI = false, bool SP2 = false>
; __device__ __forceinline__ void gemm_phase(PG8_LAS unsigned char* lds, const Gemm g, const Sched& S, const Epi& E, int tid_in) {
;     int tid_ = tid_in; asm volatile("" : "+v"(tid_)); const int tid = tid_, wid = __builtin_amdgcn_readfirstlane(tid >> 6), lane = tid & 63, wr = wid >> 2, wc = wid & 3, fr = lane & 15, fq = lane >> 4;
;     const int K = g.K, nt = K / BK;
;     unsigned voffA[2], voffB[2];
; #pragma unroll
;     for (int i = 0; i < 2; ++i) { int R, C; stage_rc(tid * 16 + i * 8192, R, C); const int Rb = 2 * (R & ~31) + (Epi::PERM ? perm32(R & 31) : (R & 31));
;         voffA[i] = (unsigned)(R * g.lda + C) * 2u; voffB[i] = (unsigned)(Rb * K + C) * 2u; }
;     const size_t kstep = (size_t)(BK * 2);
;     const size_t hstep = (size_t)HALF * g.lda * 2;
;     const size_t hstepB = (size_t)32 * K * 2;
;     const size_t tstep = 2 * hstep, tstepB = (size_t)BM * K * 2;
;     const unsigned ldsw = (unsigned)wid * 1024u;
;     const int aoff = lds_byte(wr * 64 + fr, fq * 8), boff = lds_byte(wc * 32 + fr, fq * 8);
;     ...
;     Unit cur, nxt; int ui = 0;
;     if (!S.next(0, cur)) return;
;     f32x4 acc[2][2][4][2];
; #pragma unroll
;     for (int a = 0; a < 2; ++a)
; #pragma unroll
;         for (int b = 0; b < 2; ++b)
; #pragma unroll
;             for (int m = 0; m < 4; ++m)
; #pragma unroll
;                 for (int n = 0; n < 2; ++n) acc[a][b][m][n] = (f32x4){0.f, 0.f, 0.f, 0.f};
;     bf16x8 At[4][2], B0[2][2], B1[2][2];
;     const char* cA = (const char*)g.A + (size_t)cur.pm * tstep; const char* cB = (const char*)g.Bt + (size_t)cur.pn * tstepB;
;     S.a_ready(cur);
;     if constexpr (SP2) {
;         PG8_STAGE(PG8_SB(0, 0), cB, voffB); PG8_STAGE(PG8_SB(0, 1), cB + hstepB, voffB); PG8_STAGE(PG8_SA(0, 0), cA, voffA); PG8_STAGE(PG8_SA(0, 1), cA + hstep, voffA);
;         if (wr == 1) PG8_BAR;
;         PG8_WAIT_V(2); PG8_BAR;
.LBB0_857:
	v_ashrrev_i32_e32 v0, 31, v8
	v_lshrrev_b32_e32 v0, 26, v0
	v_add_u32_e32 v0, v8, v0
	v_ashrrev_i32_e32 v9, 6, v0
	v_bfe_i32 v0, v8, 27, 1
	s_waitcnt vmcnt(8)
	v_lshlrev_b32_e32 v12, 4, v8
	v_lshrrev_b32_e32 v0, 22, v0
	v_add_u32_e32 v0, v12, v0
	v_and_b32_e32 v0, 0xfffffc00, v0
	v_sub_u32_e32 v0, v12, v0
	v_lshrrev_b32_e32 v1, 4, v0
	v_bitop3_b32 v0, v1, v0, 32 bitop3:0x6c
	v_ashrrev_i32_e32 v2, 31, v0
	v_lshrrev_b32_e32 v2, 26, v2
	v_add_u32_e32 v2, v0, v2
	v_lshlrev_b32_e32 v1, 3, v9
	v_ashrrev_i32_e32 v10, 6, v2
	v_and_b32_e32 v2, 0xc0, v2
	v_and_b32_e32 v1, -16, v1
	v_sub_u32_e32 v0, v0, v2
	v_mov_b32_e32 v2, 1
	v_add_u32_e32 v1, v10, v1
	v_ashrrev_i16_sdwa v0, v2, sext(v0) dst_sel:DWORD dst_unused:UNUSED_PAD src0_sel:DWORD src1_sel:BYTE_0
	v_lshlrev_b32_e32 v3, 5, v9
	v_bfe_i32 v11, v0, 0, 16
	v_lshlrev_b32_e32 v0, 1, v1
	v_lshrrev_b32_e32 v4, 2, v1
	s_ashr_i32 s8, s11, 3
	v_and_b32_e32 v3, 32, v3
	v_and_b32_e32 v4, 4, v4
	v_and_b32_e32 v5, 3, v10
	v_and_b32_e32 v0, 0xfffd8, v0
	v_or3_b32 v0, v5, v4, v0
	v_add_lshl_u32 v3, v3, v11, 1
	s_add_i32 s8, s10, s8
	v_lshl_add_u32 v130, v0, 12, v3
	v_add_u32_e32 v0, 0x2000, v12
	s_ashr_i32 s10, s8, 31
	v_lshl_add_u32 v128, v1, 12, v3
	v_ashrrev_i32_e32 v1, 31, v0
	s_lshr_b32 s10, s10, 24
	v_lshrrev_b32_e32 v1, 22, v1
	s_add_i32 s10, s8, s10
	v_add_u32_e32 v1, v0, v1
	s_ashr_i32 s11, s10, 8
	s_and_b32 s10, s10, 0xffffff00
	v_ashrrev_i32_e32 v13, 10, v1
	s_sub_i32 s10, s8, s10
	v_mul_i32_i24_e32 v1, 0x400, v13
	s_sext_i32_i16 s8, s10
	v_sub_u32_e32 v0, v0, v1
	s_bfe_u32 s8, s8, 0x3001c
	v_lshrrev_b32_e32 v1, 4, v0
	s_add_i32 s12, s10, s8
	v_bitop3_b32 v0, v1, v0, 32 bitop3:0x6c
	s_sext_i32_i16 s8, s12
	s_and_b32 s12, s12, 0xfff8
	v_ashrrev_i32_e32 v3, 31, v0
	s_sub_i32 s10, s10, s12
	v_lshrrev_b32_e32 v3, 26, v3
	s_lshl_b32 s11, s11, 3
	s_sext_i32_i16 s10, s10
	s_ashr_i32 s9, s36, 6
	v_add_u32_e32 v3, v0, v3
	s_lshr_b32 s8, s8, 3
	s_add_i32 s48, s11, s10
	v_lshlrev_b32_e32 v1, 3, v13
	v_ashrrev_i32_e32 v14, 6, v3
	v_and_b32_e32 v3, 0xc0, v3
	s_ashr_i32 s49, s48, 31
	s_bfe_i64 s[12:13], s[8:9], 0x100000
	v_and_b32_e32 v1, -16, v1
	v_sub_u32_e32 v0, v0, v3
	s_ashr_i32 s33, s36, 8
	s_lshl_b32 s56, s9, 10
	s_lshl_b64 s[10:11], s[48:49], 20
	s_lshl_b64 s[12:13], s[12:13], 20
	v_add_u32_e32 v1, v14, v1
	v_ashrrev_i16_sdwa v0, v2, sext(v0) dst_sel:DWORD dst_unused:UNUSED_PAD src0_sel:DWORD src1_sel:BYTE_0
	s_add_u32 s52, s42, s12
	v_lshlrev_b32_e32 v4, 5, v13
	v_bfe_i32 v15, v0, 0, 16
	v_lshlrev_b32_e32 v0, 1, v1
	v_lshrrev_b32_e32 v2, 2, v1
	s_addc_u32 s53, s43, s13
	s_add_i32 s49, s56, 0
	v_and_b32_e32 v4, 32, v4
	v_and_b32_e32 v2, 4, v2
	v_and_b32_e32 v3, 3, v14
	v_and_b32_e32 v0, 0xfffd8, v0
	s_add_i32 m0, s49, 0x10000
	v_or3_b32 v0, v3, v2, v0
	v_add_lshl_u32 v2, v4, v15, 1
	global_load_lds_dwordx4 v130, s[52:53]
	s_add_i32 m0, s49, 0x12000
	v_lshl_add_u32 v134, v0, 12, v2
	s_add_u32 s12, s52, 0x20000
	global_load_lds_dwordx4 v134, s[52:53]
	s_addc_u32 s13, s53, 0
	s_add_i32 m0, s49, 0x14000
	v_lshl_add_u32 v132, v1, 12, v2
	global_load_lds_dwordx4 v130, s[12:13]
	s_add_i32 m0, s49, 0x16000
	s_add_u32 s50, s28, s10
	s_addc_u32 s51, s29, s11
	s_add_i32 s57, s49, 0x2000
	global_load_lds_dwordx4 v134, s[12:13]
	s_mov_b32 m0, s49
	s_add_u32 s10, s50, 0x80000
	global_load_lds_dwordx4 v128, s[50:51]
	s_mov_b32 m0, s57
	s_addc_u32 s11, s51, 0
	s_add_i32 s58, s49, 0x4000
	global_load_lds_dwordx4 v132, s[50:51]
	s_mov_b32 m0, s58
	s_add_i32 s59, s49, 0x6000
	global_load_lds_dwordx4 v128, s[10:11]
	s_mov_b32 m0, s59
	v_mov_b32_e32 v131, 0
	global_load_lds_dwordx4 v132, s[10:11]
	v_mov_b32_e32 v135, v131
	v_mov_b32_e32 v129, v131
	v_mov_b32_e32 v133, v131
	s_cmp_eq_u32 s33, 1
	s_mov_b32 s60, 0
	v_lshl_add_u64 v[6:7], s[52:53], 0, v[130:131]
	v_lshl_add_u64 v[4:5], s[52:53], 0, v[134:135]
	v_lshl_add_u64 v[0:1], s[50:51], 0, v[128:129]
	s_cselect_b64 s[10:11], -1, 0
	s_cmp_lg_u32 s33, 1
	v_lshl_add_u64 v[2:3], s[50:51], 0, v[132:133]
	s_cbranch_scc1 .LBB0_859
	s_barrier
	s_setprio 1

; #define PG8_STAGE(bufoff, gbase, voff) do { _Pragma("unroll") for (int _i = 0; _i < 2; ++_i) \
;         __builtin_amdgcn_global_load_lds((const unsigned*)((const char*)(gbase) + (voff)[_i]), (PG8_LAS unsigned*)(lds + (bufoff) + ldsw + _i * 8192), 16, 0, 0); } while (0)
; #define PG8_LDA(dst, b, h) do { _Pragma("unroll") for (int m = 0; m < 4; ++m) _Pragma("unroll") for (int k = 0; k < 2; ++k) dst[m][k] = *(const PG8_LAS bf16x8*)(lds + PG8_SA(b, h) + aoff + m * 2048 + k * 1024); } while (0)
; #define PG8_LDB(dst, b, h) do { _Pragma("unroll") for (int n = 0; n < 2; ++n) _Pragma("unroll") for (int k = 0; k < 2; ++k) dst[n][k] = *(const PG8_LAS bf16x8*)(lds + PG8_SB(b, h) + boff + n * 2048 + k * 1024); } while (0)
; #define PG8_MMA(ai, bj, At, Bt) do { __builtin_amdgcn_s_setprio(1); _Pragma("unroll") for (int m = 0; m < 4; ++m) _Pragma("unroll") for (int n = 0; n < 2; ++n) _Pragma("unroll") for (int k = 0; k < 2; ++k) \
;         acc[ai][bj][m][n] = __builtin_amdgcn_mfma_f32_16x16x32_bf16(Bt[n][k], At[m][k], acc[ai][bj][m][n], 0, 0, 0); __builtin_amdgcn_s_setprio(0); } while (0)
; #define PG8_WAIT_V(n) asm volatile("s_waitcnt vmcnt(" #n ")" ::: "memory")
; #define PG8_WAIT_L(n) asm volatile("s_waitcnt lgkmcnt(" #n ")" ::: "memory")
; #define PG8_BAR __builtin_amdgcn_s_barrier()
; #define PG8_SCHED __builtin_amdgcn_sched_barrier(0)
; template <class Epi, class Sched, bool ALIGN_EPI = false, bool SP2 = false>
; __device__ __forceinline__ void gemm_phase(PG8_LAS unsigned char* lds, const Gemm g, const Sched& S, const Epi& E, int tid_in) {
;     ...
;             PG8_LDB(B0, 0, 0); PG8_LDB(B1, 0, 1); PG8_SCHED; PG8_LDA(At, 0, 0); PG8_STAGE(PG8_SA(1, 1), a1 + hstep, voffA);
;             PG8_WAIT_V(8); PG8_WAIT_L(0); PG8_BAR; PG8_MMA(0, 0, At, B0); PG8_MMA(0, 1, At, B1); PG8_BAR; PG8_SCHED;
;             PG8_LDA(At, 0, 1); PG8_STAGE(PG8_SB(0, 0), b2, voffB); PG8_STAGE(PG8_SB(0, 1), b2 + hstepB, voffB); PG8_STAGE(PG8_SA(0, 0), a2, voffA);
;             PG8_WAIT_V(8); PG8_WAIT_L(0); PG8_BAR; PG8_MMA(1, 0, At, B0); PG8_MMA(1, 1, At, B1); PG8_BAR; PG8_SCHED;
.Lkb_skip_6:
.LBB0_869:
	ds_read_b128 v[156:159], v150
	ds_read_b128 v[160:163], v150 offset:1024
	ds_read_b128 v[164:167], v150 offset:2048
	ds_read_b128 v[168:171], v150 offset:3072
	ds_read_b128 v[172:175], v151
	ds_read_b128 v[176:179], v151 offset:1024
	ds_read_b128 v[180:183], v151 offset:2048
	ds_read_b128 v[184:187], v151 offset:3072
	s_add_u32 s26, s50, 0xfff80080
	s_addc_u32 s27, s51, -1
	s_cmp_eq_u32 s72, 28
	s_cselect_b32 s55, s41, s27
	s_cselect_b32 s54, s68, s26
	s_cselect_b32 s53, s39, s71
	s_cselect_b32 s52, s69, s70
	v_lshl_add_u64 v[220:221], s[50:51], 0, v[138:139]
	s_add_i32 m0, s49, 0xc000
	ds_read_b128 v[188:191], v152
	ds_read_b128 v[192:195], v152 offset:1024
	ds_read_b128 v[196:199], v152 offset:2048
	ds_read_b128 v[200:203], v152 offset:3072
	ds_read_b128 v[204:207], v152 offset:4096
	ds_read_b128 v[208:211], v152 offset:5120
	ds_read_b128 v[212:215], v152 offset:6144
	ds_read_b128 v[216:219], v152 offset:7168
	global_load_lds_dwordx4 v[220:221], off
	v_lshl_add_u64 v[220:221], s[50:51], 0, v[140:141]
	s_add_i32 m0, s49, 0xe000
	s_nop 0
	global_load_lds_dwordx4 v[220:221], off
	s_waitcnt vmcnt(8)
	s_waitcnt lgkmcnt(0)
	s_barrier
	s_waitcnt lgkmcnt(0)
	v_mfma_f32_16x16x32_bf16 v[124:127], v[156:159], v[188:191], v[124:127]
	v_mfma_f32_16x16x32_bf16 v[120:123], v[164:167], v[188:191], v[120:123]
	v_mfma_f32_16x16x32_bf16 v[108:111], v[156:159], v[196:199], v[108:111]
	v_mfma_f32_16x16x32_bf16 v[104:107], v[164:167], v[196:199], v[104:107]
	v_mfma_f32_16x16x32_bf16 v[92:95], v[156:159], v[204:207], v[92:95]
	v_mfma_f32_16x16x32_bf16 v[88:91], v[164:167], v[204:207], v[88:91]
	v_mfma_f32_16x16x32_bf16 v[76:79], v[156:159], v[212:215], v[76:79]
	v_mfma_f32_16x16x32_bf16 v[72:75], v[164:167], v[212:215], v[72:75]
	v_mfma_f32_16x16x32_bf16 v[124:127], v[160:163], v[192:195], v[124:127]
	v_mfma_f32_16x16x32_bf16 v[120:123], v[168:171], v[192:195], v[120:123]
	v_mfma_f32_16x16x32_bf16 v[108:111], v[160:163], v[200:203], v[108:111]
	v_mfma_f32_16x16x32_bf16 v[104:107], v[168:171], v[200:203], v[104:107]
	v_mfma_f32_16x16x32_bf16 v[92:95], v[160:163], v[208:211], v[92:95]
	v_mfma_f32_16x16x32_bf16 v[88:91], v[168:171], v[208:211], v[88:91]
	v_mfma_f32_16x16x32_bf16 v[76:79], v[160:163], v[216:219], v[76:79]
	v_mfma_f32_16x16x32_bf16 v[72:75], v[168:171], v[216:219], v[72:75]
	v_mfma_f32_16x16x32_bf16 v[116:119], v[172:175], v[188:191], v[116:119]
	v_mfma_f32_16x16x32_bf16 v[112:115], v[180:183], v[188:191], v[112:115]
	v_mfma_f32_16x16x32_bf16 v[100:103], v[172:175], v[196:199], v[100:103]
	v_mfma_f32_16x16x32_bf16 v[96:99], v[180:183], v[196:199], v[96:99]
	v_mfma_f32_16x16x32_bf16 v[84:87], v[172:175], v[204:207], v[84:87]
	v_mfma_f32_16x16x32_bf16 v[80:83], v[180:183], v[204:207], v[80:83]
	v_mfma_f32_16x16x32_bf16 v[68:71], v[172:175], v[212:215], v[68:71]
	v_mfma_f32_16x16x32_bf16 v[64:67], v[180:183], v[212:215], v[64:67]
	v_mfma_f32_16x16x32_bf16 v[116:119], v[176:179], v[192:195], v[116:119]
	v_mfma_f32_16x16x32_bf16 v[112:115], v[184:187], v[192:195], v[112:115]
	v_mfma_f32_16x16x32_bf16 v[100:103], v[176:179], v[200:203], v[100:103]
	v_mfma_f32_16x16x32_bf16 v[96:99], v[184:187], v[200:203], v[96:99]
	v_mfma_f32_16x16x32_bf16 v[84:87], v[176:179], v[208:211], v[84:87]
	v_mfma_f32_16x16x32_bf16 v[80:83], v[184:187], v[208:211], v[80:83]
	v_mfma_f32_16x16x32_bf16 v[68:71], v[176:179], v[216:219], v[68:71]
	v_mfma_f32_16x16x32_bf16 v[64:67], v[184:187], v[216:219], v[64:67]
	s_barrier
	s_add_i32 s26, s64, s56
	v_lshl_add_u64 v[220:221], s[52:53], 0, v[130:131]
	s_mov_b32 m0, s26
	ds_read_b128 v[188:191], v152 offset:16384
	ds_read_b128 v[192:195], v152 offset:17408
	ds_read_b128 v[196:199], v152 offset:18432
	ds_read_b128 v[200:203], v152 offset:19456
	ds_read_b128 v[204:207], v152 offset:20480
	ds_read_b128 v[208:211], v152 offset:21504
	ds_read_b128 v[212:215], v152 offset:22528
	ds_read_b128 v[216:219], v152 offset:23552
	global_load_lds_dwordx4 v[220:221], off
	s_add_i32 m0, s26, 0x2000
	s_add_u32 s26, s52, 0x20000
	v_lshl_add_u64 v[222:223], s[52:53], 0, v[134:135]
	s_addc_u32 s27, s53, 0
	s_add_i32 s33, s65, s56
	global_load_lds_dwordx4 v[222:223], off
	v_lshl_add_u64 v[224:225], s[26:27], 0, v[130:131]
	s_mov_b32 m0, s33
	v_lshl_add_u64 v[226:227], s[54:55], 0, v[132:133]
	global_load_lds_dwordx4 v[224:225], off
	v_lshl_add_u64 v[224:225], s[26:27], 0, v[134:135]
	s_add_i32 m0, s33, 0x2000
	s_nop 0
	global_load_lds_dwordx4 v[224:225], off
	v_lshl_add_u64 v[224:225], s[54:55], 0, v[128:129]
	s_mov_b32 m0, s49
	s_nop 0
	global_load_lds_dwordx4 v[224:225], off
	s_mov_b32 m0, s57
	s_nop 0
	global_load_lds_dwordx4 v[226:227], off
	s_waitcnt vmcnt(8)
	s_waitcnt lgkmcnt(0)
	s_barrier
; #define PG8_STAGE(bufoff, gbase, voff) do { _Pragma("unroll") for (int _i = 0; _i < 2; ++_i) \
;         __builtin_amdgcn_global_load_lds((const unsigned*)((const char*)(gbase) + (voff)[_i]), (PG8_LAS unsigned*)(lds + (bufoff) + ldsw + _i * 8192), 16, 0, 0); } while (0)
; #define PG8_LDA(dst, b, h) do { _Pragma("unroll") for (int m = 0; m < 4; ++m) _Pragma("unroll") for (int k = 0; k < 2; ++k) dst[m][k] = *(const PG8_LAS bf16x8*)(lds + PG8_SA(b, h) + aoff + m * 2048 + k * 1024); } while (0)
; #define PG8_LDB(dst, b, h) do { _Pragma("unroll") for (int n = 0; n < 2; ++n) _Pragma("unroll") for (int k = 0; k < 2; ++k) dst[n][k] = *(const PG8_LAS bf16x8*)(lds + PG8_SB(b, h) + boff + n * 2048 + k * 1024); } while (0)
; #define PG8_MMA(ai, bj, At, Bt) do { __builtin_amdgcn_s_setprio(1); _Pragma("unroll") for (int m = 0; m < 4; ++m) _Pragma("unroll") for (int n = 0; n < 2; ++n) _Pragma("unroll") for (int k = 0; k < 2; ++k) \
;         acc[ai][bj][m][n] = __builtin_amdgcn_mfma_f32_16x16x32_bf16(Bt[n][k], At[m][k], acc[ai][bj][m][n], 0, 0, 0); __builtin_amdgcn_s_setprio(0); } while (0)
; #define PG8_WAIT_V(n) asm volatile("s_waitcnt vmcnt(" #n ")" ::: "memory")
; #define PG8_WAIT_L(n) asm volatile("s_waitcnt lgkmcnt(" #n ")" ::: "memory")
; #define PG8_BAR __builtin_amdgcn_s_barrier()
; #define PG8_SCHED __builtin_amdgcn_sched_barrier(0)
; template <class Epi, class Sched, bool ALIGN_EPI = false, bool SP2 = false>
; __device__ __forceinline__ void gemm_phase(PG8_LAS unsigned char* lds, const Gemm g, const Sched& S, const Epi& E, int tid_in) {
;     ...
;             PG8_WAIT_V(8); PG8_WAIT_L(0); PG8_BAR; PG8_MMA(1, 0, At, B0); PG8_MMA(1, 1, At, B1); PG8_BAR; PG8_SCHED;
;             PG8_LDB(B0, 1, 0); PG8_LDB(B1, 1, 1); PG8_SCHED; PG8_LDA(At, 1, 0); PG8_STAGE(PG8_SA(0, 1), a2 + hstep, voffA);
;             PG8_WAIT_V(8); PG8_WAIT_L(0); PG8_BAR; PG8_MMA(0, 0, At, B0); PG8_MMA(0, 1, At, B1); PG8_BAR; PG8_SCHED;
	s_waitcnt lgkmcnt(0)
	v_mfma_f32_16x16x32_bf16 v[60:63], v[156:159], v[188:191], v[60:63]
	v_mfma_f32_16x16x32_bf16 v[56:59], v[164:167], v[188:191], v[56:59]
	v_mfma_f32_16x16x32_bf16 v[44:47], v[156:159], v[196:199], v[44:47]
	v_mfma_f32_16x16x32_bf16 v[40:43], v[164:167], v[196:199], v[40:43]
	v_mfma_f32_16x16x32_bf16 v[28:31], v[156:159], v[204:207], v[28:31]
	v_mfma_f32_16x16x32_bf16 v[24:27], v[164:167], v[204:207], v[24:27]
	v_mfma_f32_16x16x32_bf16 v[12:15], v[156:159], v[212:215], v[12:15]
	v_mfma_f32_16x16x32_bf16 v[8:11], v[164:167], v[212:215], v[8:11]
	v_mfma_f32_16x16x32_bf16 v[60:63], v[160:163], v[192:195], v[60:63]
	v_mfma_f32_16x16x32_bf16 v[56:59], v[168:171], v[192:195], v[56:59]
	v_mfma_f32_16x16x32_bf16 v[44:47], v[160:163], v[200:203], v[44:47]
	v_mfma_f32_16x16x32_bf16 v[40:43], v[168:171], v[200:203], v[40:43]
	v_mfma_f32_16x16x32_bf16 v[28:31], v[160:163], v[208:211], v[28:31]
	v_mfma_f32_16x16x32_bf16 v[24:27], v[168:171], v[208:211], v[24:27]
	v_mfma_f32_16x16x32_bf16 v[12:15], v[160:163], v[216:219], v[12:15]
	v_mfma_f32_16x16x32_bf16 v[8:11], v[168:171], v[216:219], v[8:11]
	v_mfma_f32_16x16x32_bf16 v[52:55], v[172:175], v[188:191], v[52:55]
	v_mfma_f32_16x16x32_bf16 v[48:51], v[180:183], v[188:191], v[48:51]
	v_mfma_f32_16x16x32_bf16 v[36:39], v[172:175], v[196:199], v[36:39]
	v_mfma_f32_16x16x32_bf16 v[32:35], v[180:183], v[196:199], v[32:35]
	v_mfma_f32_16x16x32_bf16 v[20:23], v[172:175], v[204:207], v[20:23]
	v_mfma_f32_16x16x32_bf16 v[16:19], v[180:183], v[204:207], v[16:19]
	v_mfma_f32_16x16x32_bf16 v[4:7], v[172:175], v[212:215], v[4:7]
	v_mfma_f32_16x16x32_bf16 v[0:3], v[180:183], v[212:215], v[0:3]
	v_mfma_f32_16x16x32_bf16 v[52:55], v[176:179], v[192:195], v[52:55]
	v_mfma_f32_16x16x32_bf16 v[48:51], v[184:187], v[192:195], v[48:51]
	v_mfma_f32_16x16x32_bf16 v[36:39], v[176:179], v[200:203], v[36:39]
	v_mfma_f32_16x16x32_bf16 v[32:35], v[184:187], v[200:203], v[32:35]
	v_mfma_f32_16x16x32_bf16 v[20:23], v[176:179], v[208:211], v[20:23]
	v_mfma_f32_16x16x32_bf16 v[16:19], v[184:187], v[208:211], v[16:19]
	v_mfma_f32_16x16x32_bf16 v[4:7], v[176:179], v[216:219], v[4:7]
	v_mfma_f32_16x16x32_bf16 v[0:3], v[184:187], v[216:219], v[0:3]
	s_barrier
	s_add_i32 s33, 0, 0x18000
	v_add_u32_e32 v155, s33, v146
	s_add_i32 s73, 0, 0x1c000
	ds_read_b128 v[156:159], v155
	ds_read_b128 v[160:163], v155 offset:1024
	ds_read_b128 v[164:167], v155 offset:2048
	ds_read_b128 v[168:171], v155 offset:3072
	v_add_u32_e32 v155, s73, v146
	ds_read_b128 v[172:175], v155
	ds_read_b128 v[176:179], v155 offset:1024
	ds_read_b128 v[180:183], v155 offset:2048
	ds_read_b128 v[184:187], v155 offset:3072
	s_add_u32 s26, s54, 0x80000
	s_addc_u32 s27, s55, 0
	s_mov_b32 m0, s58
	v_lshl_add_u64 v[228:229], s[26:27], 0, v[128:129]
	ds_read_b128 v[188:191], v152 offset:32768
	ds_read_b128 v[192:195], v152 offset:33792
	ds_read_b128 v[196:199], v152 offset:34816
	ds_read_b128 v[200:203], v152 offset:35840
	ds_read_b128 v[204:207], v152 offset:36864
	ds_read_b128 v[208:211], v152 offset:37888
	ds_read_b128 v[212:215], v152 offset:38912
	ds_read_b128 v[216:219], v152 offset:39936
	global_load_lds_dwordx4 v[228:229], off
	v_lshl_add_u64 v[228:229], s[26:27], 0, v[132:133]
	s_mov_b32 m0, s59
	s_nop 0
	global_load_lds_dwordx4 v[228:229], off
	s_waitcnt vmcnt(8)
	s_waitcnt lgkmcnt(0)
	s_barrier
	s_waitcnt lgkmcnt(0)
	v_mfma_f32_16x16x32_bf16 v[124:127], v[156:159], v[188:191], v[124:127]
	v_mfma_f32_16x16x32_bf16 v[120:123], v[164:167], v[188:191], v[120:123]
	v_mfma_f32_16x16x32_bf16 v[108:111], v[156:159], v[196:199], v[108:111]
	v_mfma_f32_16x16x32_bf16 v[104:107], v[164:167], v[196:199], v[104:107]
	v_mfma_f32_16x16x32_bf16 v[92:95], v[156:159], v[204:207], v[92:95]
	v_mfma_f32_16x16x32_bf16 v[88:91], v[164:167], v[204:207], v[88:91]
	v_mfma_f32_16x16x32_bf16 v[76:79], v[156:159], v[212:215], v[76:79]
	v_mfma_f32_16x16x32_bf16 v[72:75], v[164:167], v[212:215], v[72:75]
	v_mfma_f32_16x16x32_bf16 v[124:127], v[160:163], v[192:195], v[124:127]
	v_mfma_f32_16x16x32_bf16 v[120:123], v[168:171], v[192:195], v[120:123]
	v_mfma_f32_16x16x32_bf16 v[108:111], v[160:163], v[200:203], v[108:111]
	v_mfma_f32_16x16x32_bf16 v[104:107], v[168:171], v[200:203], v[104:107]
	v_mfma_f32_16x16x32_bf16 v[92:95], v[160:163], v[208:211], v[92:95]
	v_mfma_f32_16x16x32_bf16 v[88:91], v[168:171], v[208:211], v[88:91]
	v_mfma_f32_16x16x32_bf16 v[76:79], v[160:163], v[216:219], v[76:79]
	v_mfma_f32_16x16x32_bf16 v[72:75], v[168:171], v[216:219], v[72:75]
	v_mfma_f32_16x16x32_bf16 v[116:119], v[172:175], v[188:191], v[116:119]
	v_mfma_f32_16x16x32_bf16 v[112:115], v[180:183], v[188:191], v[112:115]
	v_mfma_f32_16x16x32_bf16 v[100:103], v[172:175], v[196:199], v[100:103]
	v_mfma_f32_16x16x32_bf16 v[96:99], v[180:183], v[196:199], v[96:99]
	v_mfma_f32_16x16x32_bf16 v[84:87], v[172:175], v[204:207], v[84:87]
	v_mfma_f32_16x16x32_bf16 v[80:83], v[180:183], v[204:207], v[80:83]
	v_mfma_f32_16x16x32_bf16 v[68:71], v[172:175], v[212:215], v[68:71]
	v_mfma_f32_16x16x32_bf16 v[64:67], v[180:183], v[212:215], v[64:67]
	v_mfma_f32_16x16x32_bf16 v[116:119], v[176:179], v[192:195], v[116:119]
	v_mfma_f32_16x16x32_bf16 v[112:115], v[184:187], v[192:195], v[112:115]
	v_mfma_f32_16x16x32_bf16 v[100:103], v[176:179], v[200:203], v[100:103]
	v_mfma_f32_16x16x32_bf16 v[96:99], v[184:187], v[200:203], v[96:99]
	v_mfma_f32_16x16x32_bf16 v[84:87], v[176:179], v[208:211], v[84:87]
	v_mfma_f32_16x16x32_bf16 v[80:83], v[184:187], v[208:211], v[80:83]
	v_mfma_f32_16x16x32_bf16 v[68:71], v[176:179], v[216:219], v[68:71]
	v_mfma_f32_16x16x32_bf16 v[64:67], v[184:187], v[216:219], v[64:67]
	s_barrier
; #define PG8_STAGE(bufoff, gbase, voff) do { _Pragma("unroll") for (int _i = 0; _i < 2; ++_i) \
;         __builtin_amdgcn_global_load_lds((const unsigned*)((const char*)(gbase) + (voff)[_i]), (PG8_LAS unsigned*)(lds + (bufoff) + ldsw + _i * 8192), 16, 0, 0); } while (0)
; #define PG8_LDA(dst, b, h) do { _Pragma("unroll") for (int m = 0; m < 4; ++m) _Pragma("unroll") for (int k = 0; k < 2; ++k) dst[m][k] = *(const PG8_LAS bf16x8*)(lds + PG8_SA(b, h) + aoff + m * 2048 + k * 1024); } while (0)
; #define PG8_BAR __builtin_amdgcn_s_barrier()
; template <class Epi, class Sched, bool ALIGN_EPI = false, bool SP2 = false>
; __device__ __forceinline__ void gemm_phase(PG8_LAS unsigned char* lds, const Gemm g, const Sched& S, const Epi& E, int tid_in) {
;     ...
;             PG8_LDA(At, 1, 1); PG8_STAGE(PG8_SB(1, 0), b3, voffB); PG8_STAGE(PG8_SB(1, 1), b3 + hstepB, voffB); PG8_STAGE(PG8_SA(1, 0), a3, voffA);
;             PG8_WAIT_V(8); PG8_WAIT_L(0); PG8_BAR; PG8_MMA(1, 0, At, B0); PG8_MMA(1, 1, At, B1); PG8_BAR; PG8_SCHED;
;             } else {
;             PG8_LDB(B0, 0, 0); PG8_SCHED; PG8_LDA(At, 0, 0); PG8_STAGE(PG8_SA(1, 1), a1 + hstep, voffA);
;             PG8_WAIT_L(8); PG8_BAR; PG8_WAIT_L(0); PG8_MMA(0, 0, At, B0); PG8_BAR; PG8_SCHED;
;             PG8_LDB(B1, 0, 1); PG8_STAGE(PG8_SB(0, 0), b2, voffB);
;             PG8_BAR; PG8_WAIT_L(0); PG8_MMA(0, 1, At, B1); PG8_BAR;
;             PG8_LDA(At, 0, 1); PG8_STAGE(PG8_SA(0, 0), a2, voffA);
;             PG8_BAR; PG8_WAIT_L(0); PG8_MMA(1, 0, At, B0); PG8_BAR; PG8_SCHED;
;             PG8_STAGE(PG8_SB(0, 1), b2 + hstepB, voffB);
;             PG8_WAIT_V(6); PG8_BAR; PG8_MMA(1, 1, At, B1); PG8_BAR;
;             PG8_LDB(B0, 1, 0); PG8_SCHED; PG8_LDA(At, 1, 0); PG8_STAGE(PG8_SA(0, 1), a2 + hstep, voffA);
;             PG8_WAIT_L(8); PG8_BAR; PG8_WAIT_L(0); PG8_MMA(0, 0, At, B0); PG8_BAR; PG8_SCHED;
;             PG8_LDB(B1, 1, 1); PG8_STAGE(PG8_SB(1, 0), b3, voffB);
;             PG8_BAR; PG8_WAIT_L(0); PG8_MMA(0, 1, At, B1); PG8_BAR;
;             PG8_LDA(At, 1, 1); PG8_STAGE(PG8_SA(1, 0), a3, voffA);
;             PG8_BAR; PG8_WAIT_L(0); PG8_MMA(1, 0, At, B0); PG8_BAR; PG8_SCHED;
;             PG8_STAGE(PG8_SB(1, 1), b3 + hstepB, voffB);
;             PG8_WAIT_V(6); PG8_BAR; PG8_MMA(1, 1, At, B1); PG8_BAR;
;             }
;         }
;         if constexpr (ALIGN_EPI) { if (wr == 0) PG8_BAR; }
	s_add_i32 s26, s33, s56
	v_lshl_add_u64 v[220:221], v[220:221], 0, s[12:13]
	s_mov_b32 m0, s26
	ds_read_b128 v[188:191], v152 offset:49152
	ds_read_b128 v[192:195], v152 offset:50176
	ds_read_b128 v[196:199], v152 offset:51200
	ds_read_b128 v[200:203], v152 offset:52224
	ds_read_b128 v[204:207], v152 offset:53248
	ds_read_b128 v[208:211], v152 offset:54272
	ds_read_b128 v[212:215], v152 offset:55296
	ds_read_b128 v[216:219], v152 offset:56320
	global_load_lds_dwordx4 v[220:221], off
	s_add_i32 m0, s26, 0x2000
	s_add_u32 s26, s52, 0x20080
	v_lshl_add_u64 v[220:221], v[222:223], 0, s[12:13]
	s_addc_u32 s27, s53, 0
	s_add_i32 s33, s73, s56
	global_load_lds_dwordx4 v[220:221], off
	v_lshl_add_u64 v[220:221], s[26:27], 0, v[130:131]
	s_mov_b32 m0, s33
	s_nop 0
	global_load_lds_dwordx4 v[220:221], off
	v_lshl_add_u64 v[220:221], s[26:27], 0, v[134:135]
	s_add_i32 m0, s33, 0x2000
	s_nop 0
	global_load_lds_dwordx4 v[220:221], off
	v_lshl_add_u64 v[220:221], v[224:225], 0, s[12:13]
	s_mov_b32 m0, s62
	s_nop 0
	global_load_lds_dwordx4 v[220:221], off
	v_lshl_add_u64 v[220:221], v[226:227], 0, s[12:13]
	s_mov_b32 m0, s63
	s_nop 0
	global_load_lds_dwordx4 v[220:221], off
	s_waitcnt vmcnt(8)
	s_waitcnt lgkmcnt(0)
	s_barrier
	s_waitcnt lgkmcnt(0)
	v_mfma_f32_16x16x32_bf16 v[60:63], v[156:159], v[188:191], v[60:63]
	v_mfma_f32_16x16x32_bf16 v[56:59], v[164:167], v[188:191], v[56:59]
	v_mfma_f32_16x16x32_bf16 v[44:47], v[156:159], v[196:199], v[44:47]
	v_mfma_f32_16x16x32_bf16 v[40:43], v[164:167], v[196:199], v[40:43]
	v_mfma_f32_16x16x32_bf16 v[28:31], v[156:159], v[204:207], v[28:31]
	v_mfma_f32_16x16x32_bf16 v[24:27], v[164:167], v[204:207], v[24:27]
	v_mfma_f32_16x16x32_bf16 v[12:15], v[156:159], v[212:215], v[12:15]
	v_mfma_f32_16x16x32_bf16 v[8:11], v[164:167], v[212:215], v[8:11]
	v_mfma_f32_16x16x32_bf16 v[60:63], v[160:163], v[192:195], v[60:63]
	v_mfma_f32_16x16x32_bf16 v[56:59], v[168:171], v[192:195], v[56:59]
	v_mfma_f32_16x16x32_bf16 v[44:47], v[160:163], v[200:203], v[44:47]
	v_mfma_f32_16x16x32_bf16 v[40:43], v[168:171], v[200:203], v[40:43]
	v_mfma_f32_16x16x32_bf16 v[28:31], v[160:163], v[208:211], v[28:31]
	v_mfma_f32_16x16x32_bf16 v[24:27], v[168:171], v[208:211], v[24:27]
	v_mfma_f32_16x16x32_bf16 v[12:15], v[160:163], v[216:219], v[12:15]
	v_mfma_f32_16x16x32_bf16 v[8:11], v[168:171], v[216:219], v[8:11]
	v_mfma_f32_16x16x32_bf16 v[52:55], v[172:175], v[188:191], v[52:55]
	v_mfma_f32_16x16x32_bf16 v[48:51], v[180:183], v[188:191], v[48:51]
	v_mfma_f32_16x16x32_bf16 v[36:39], v[172:175], v[196:199], v[36:39]
	v_mfma_f32_16x16x32_bf16 v[32:35], v[180:183], v[196:199], v[32:35]
	v_mfma_f32_16x16x32_bf16 v[20:23], v[172:175], v[204:207], v[20:23]
	v_mfma_f32_16x16x32_bf16 v[16:19], v[180:183], v[204:207], v[16:19]
	v_mfma_f32_16x16x32_bf16 v[4:7], v[172:175], v[212:215], v[4:7]
	v_mfma_f32_16x16x32_bf16 v[0:3], v[180:183], v[212:215], v[0:3]
	v_mfma_f32_16x16x32_bf16 v[52:55], v[176:179], v[192:195], v[52:55]
	v_mfma_f32_16x16x32_bf16 v[48:51], v[184:187], v[192:195], v[48:51]
	v_mfma_f32_16x16x32_bf16 v[36:39], v[176:179], v[200:203], v[36:39]
	v_mfma_f32_16x16x32_bf16 v[32:35], v[184:187], v[200:203], v[32:35]
	v_mfma_f32_16x16x32_bf16 v[20:23], v[176:179], v[208:211], v[20:23]
	v_mfma_f32_16x16x32_bf16 v[16:19], v[184:187], v[208:211], v[16:19]
	v_mfma_f32_16x16x32_bf16 v[4:7], v[176:179], v[216:219], v[4:7]
	v_mfma_f32_16x16x32_bf16 v[0:3], v[184:187], v[216:219], v[0:3]
	s_barrier
	s_add_i32 s72, s72, 2
	s_add_u32 s50, s50, 0x100
	s_addc_u32 s51, s51, 0
	s_add_u32 s70, s70, 0x100
	s_addc_u32 s71, s71, 0
	s_cmp_gt_u32 s72, 29
	s_cbranch_scc0 .LBB0_869
	s_and_b64 vcc, exec, s[36:37]
	s_cbranch_vccz .LBB0_872
	s_barrier

; #define TID() fresh_tid(wave)
;     __host__ __device__ bool next(int i, Unit& u) const {
;         const long L = (long)i * G + c; if (L >= nwg) return false;
;         int wgid = (int)L; { const int q = nwg / NXCD, r = nwg % NXCD, xcd = wgid % NXCD, off = wgid / NXCD; wgid = (xcd < r ? xcd * (q + 1) : r * (q + 1) + (xcd - r) * q) + off; }
;         const int nig = wgm * nN, gid = wgid / nig, fm = gid * wgm, gsz = (nM - fm) < wgm ? (nM - fm) : wgm;
;         u.pm = fm + ((wgid % nig) % gsz); u.pn = (wgid % nig) / gsz; return true;
; __global__ void __launch_bounds__(NWAVES * 64, 2) mk_fwd(Args args) {
;     ...
;     xcd_barrier(xbar);
;     {
;         pg8::Gemm g{BIG, (const bf16*)(ws + WS_W21), TOK, DM, DFF, LDH}; pg8::StaticOrder S; S.init(TOK, DM, G, bx); S.wgm = 4;
;         pg8::EpiResid<false> E{XA, XA, ss + 4 * TOK, L};
;         pg8::gemm_phase<pg8::EpiResid<false>, pg8::StaticOrder, true, true>(L, g, S, E, TID());
.LBB0_928:
	s_or_b64 exec, exec, s[8:9]
	s_waitcnt lgkmcnt(0)
	s_setprio 0
	v_mov_b32_e32 v0, v252
	s_barrier
	s_and_b64 vcc, exec, s[6:7]
	v_add_u32_e32 v8, s81, v0
	s_nop 0
	v_readfirstlane_b32 s10, v8
	s_cbranch_vccnz .LBB0_934
	s_lshr_b32 s8, s3, 29
	s_add_i32 s13, s2, s8
	s_and_b32 s8, s13, -8
	s_sub_i32 s11, s2, s8
	s_cmp_gt_i32 s11, -1
	s_cbranch_scc0 .LBB0_931
	s_lshl_b32 s12, s11, 7
	s_ashr_i32 s8, s13, 3
	s_cbranch_execz .LBB0_932
	s_branch .LBB0_933

; #define PG8_STAGE(bufoff, gbase, voff) do { _Pragma("unroll") for (int _i = 0; _i < 2; ++_i) \
;         __builtin_amdgcn_global_load_lds((const unsigned*)((const char*)(gbase) + (voff)[_i]), (PG8_LAS unsigned*)(lds + (bufoff) + ldsw + _i * 8192), 16, 0, 0); } while (0)
; #define PG8_BAR __builtin_amdgcn_s_barrier()
; template <class Epi, class Sched, bool ALIGN_EPI = false, bool SP2 = false>
; __device__ __forceinline__ void gemm_phase(PG8_LAS unsigned char* lds, const Gemm g, const Sched& S, const Epi& E, int tid_in) {
;     int tid_ = tid_in; asm volatile("" : "+v"(tid_)); const int tid = tid_, wid = __builtin_amdgcn_readfirstlane(tid >> 6), lane = tid & 63, wr = wid >> 2, wc = wid & 3, fr = lane & 15, fq = lane >> 4;
;     const int K = g.K, nt = K / BK;
;     unsigned voffA[2], voffB[2];
; #pragma unroll
;     for (int i = 0; i < 2; ++i) { int R, C; stage_rc(tid * 16 + i * 8192, R, C); const int Rb = 2 * (R & ~31) + (Epi::PERM ? perm32(R & 31) : (R & 31));
;         voffA[i] = (unsigned)(R * g.lda + C) * 2u; voffB[i] = (unsigned)(Rb * K + C) * 2u; }
;     const size_t kstep = (size_t)(BK * 2);
;     const size_t hstep = (size_t)HALF * g.lda * 2;
;     const size_t hstepB = (size_t)32 * K * 2;
;     const size_t tstep = 2 * hstep, tstepB = (size_t)BM * K * 2;
;     const unsigned ldsw = (unsigned)wid * 1024u;
;     const int aoff = lds_byte(wr * 64 + fr, fq * 8), boff = lds_byte(wc * 32 + fr, fq * 8);
;     ...
;     Unit cur, nxt; int ui = 0;
;     if (!S.next(0, cur)) return;
;     f32x4 acc[2][2][4][2];
; #pragma unroll
;     for (int a = 0; a < 2; ++a)
; #pragma unroll
;         for (int b = 0; b < 2; ++b)
; #pragma unroll
;             for (int m = 0; m < 4; ++m)
; #pragma unroll
;                 for (int n = 0; n < 2; ++n) acc[a][b][m][n] = (f32x4){0.f, 0.f, 0.f, 0.f};
;     bf16x8 At[4][2], B0[2][2], B1[2][2];
;     const char* cA = (const char*)g.A + (size_t)cur.pm * tstep; const char* cB = (const char*)g.Bt + (size_t)cur.pn * tstepB;
;     S.a_ready(cur);
;     if constexpr (SP2) {
;         PG8_STAGE(PG8_SB(0, 0), cB, voffB); PG8_STAGE(PG8_SB(0, 1), cB + hstepB, voffB); PG8_STAGE(PG8_SA(0, 0), cA, voffA); PG8_STAGE(PG8_SA(0, 1), cA + hstep, voffA);
;         if (wr == 1) PG8_BAR;
.LBB0_934:
	s_add_u32 s12, s18, 0x100000
	s_addc_u32 s13, s19, 0
	s_and_b64 vcc, exec, s[6:7]
	s_cbranch_vccnz .LBB0_972
	v_ashrrev_i32_e32 v1, 31, v8
	v_lshrrev_b32_e32 v1, 26, v1
	v_add_u32_e32 v1, v8, v1
	v_ashrrev_i32_e32 v9, 6, v1
	v_bfe_i32 v1, v8, 27, 1
	v_lshlrev_b32_e32 v0, 4, v8
	v_lshrrev_b32_e32 v1, 22, v1
	v_add_u32_e32 v1, v0, v1
	v_and_b32_e32 v1, 0xfffffc00, v1
	v_sub_u32_e32 v1, v0, v1
	v_lshrrev_b32_e32 v2, 4, v1
	v_bitop3_b32 v1, v2, v1, 32 bitop3:0x6c
	v_ashrrev_i32_e32 v3, 31, v1
	v_lshrrev_b32_e32 v3, 26, v3
	v_add_u32_e32 v3, v1, v3
	v_ashrrev_i32_e32 v11, 6, v3
	v_and_b32_e32 v3, 0xc0, v3
	v_lshlrev_b32_e32 v2, 3, v9
	v_sub_u32_e32 v1, v1, v3
	v_mov_b32_e32 v3, 1
	v_and_b32_e32 v2, -16, v2
	v_lshlrev_b32_e32 v4, 5, v9
	v_ashrrev_i16_sdwa v1, v3, sext(v1) dst_sel:DWORD dst_unused:UNUSED_PAD src0_sel:DWORD src1_sel:BYTE_0
	v_add_u32_e32 v2, v11, v2
	v_and_b32_e32 v10, 32, v4
	v_bfe_i32 v12, v1, 0, 16
	s_movk_i32 s8, 0x2040
	v_add_u32_e32 v1, v10, v12
	v_lshlrev_b32_e32 v4, 1, v2
	v_and_b32_e32 v5, 31, v2
	s_mov_b32 s7, 0x3ffc0
	v_mul_lo_u32 v2, v2, s8
	v_and_or_b32 v4, v4, s7, v5
	v_add_lshl_u32 v128, v1, v2, 1
	v_lshlrev_b32_e32 v1, 1, v1
	v_add_u32_e32 v0, 0x2000, v0
	v_lshl_add_u32 v130, v4, 14, v1
	v_ashrrev_i32_e32 v1, 31, v0
	v_lshrrev_b32_e32 v1, 22, v1
	v_add_u32_e32 v1, v0, v1
	v_ashrrev_i32_e32 v13, 10, v1
	v_mul_i32_i24_e32 v1, 0x400, v13
	v_sub_u32_e32 v0, v0, v1
	v_lshrrev_b32_e32 v1, 4, v0
	v_bitop3_b32 v0, v1, v0, 32 bitop3:0x6c
	v_ashrrev_i32_e32 v2, 31, v0
	v_lshrrev_b32_e32 v2, 26, v2
	v_lshlrev_b32_e32 v1, 3, v13
	v_add_u32_e32 v2, v0, v2
	v_and_b32_e32 v1, -16, v1
	v_ashrrev_i32_e32 v14, 6, v2
	v_and_b32_e32 v2, 0xc0, v2
	v_add_u32_e32 v1, v14, v1
	v_sub_u32_e32 v0, v0, v2
	s_ashr_i32 s6, s10, 6
	v_ashrrev_i16_sdwa v0, v3, sext(v0) dst_sel:DWORD dst_unused:UNUSED_PAD src0_sel:DWORD src1_sel:BYTE_0
	v_lshlrev_b32_e32 v2, 1, v1
	v_and_b32_e32 v3, 31, v1
	s_ashr_i32 s49, s48, 31
	v_and_or_b32 v2, v2, s7, v3
	s_ashr_i32 s7, s10, 8
	s_lshl_b32 s56, s6, 10
	s_lshl_b64 s[26:27], s[48:49], 22
	v_lshlrev_b32_e32 v4, 5, v13
	s_add_u32 s52, s14, s26
	v_and_b32_e32 v15, 32, v4
	v_bfe_i32 v16, v0, 0, 16
	s_addc_u32 s53, s15, s27
	s_add_i32 s49, s56, 0
	v_add_u32_e32 v0, v15, v16
	v_mul_lo_u32 v1, v1, s8
	s_add_i32 m0, s49, 0x10000
	v_add_lshl_u32 v132, v0, v1, 1
	v_lshlrev_b32_e32 v0, 1, v0
	global_load_lds_dwordx4 v130, s[52:53]
	s_add_i32 m0, s49, 0x12000
	v_lshl_add_u32 v134, v2, 14, v0
	s_add_u32 s26, s52, 0x80000
	global_load_lds_dwordx4 v134, s[52:53]
	s_addc_u32 s27, s53, 0
	s_add_i32 m0, s49, 0x14000
	s_mul_i32 s11, s66, 0x408000
	global_load_lds_dwordx4 v130, s[26:27]
	s_add_i32 m0, s49, 0x16000
	s_mul_hi_i32 s9, s66, 0x408000
	s_add_u32 s50, s34, s11
	s_addc_u32 s51, s35, s9
	s_add_i32 s57, s49, 0x2000
	global_load_lds_dwordx4 v134, s[26:27]
	s_mov_b32 m0, s49
	s_add_u32 s26, s50, 0x204000
	global_load_lds_dwordx4 v128, s[50:51]
	s_mov_b32 m0, s57
	s_addc_u32 s27, s51, 0
	s_add_i32 s58, s49, 0x4000
	global_load_lds_dwordx4 v132, s[50:51]
	s_mov_b32 m0, s58
	s_add_i32 s59, s49, 0x6000
	global_load_lds_dwordx4 v128, s[26:27]
	s_mov_b32 m0, s59
	v_mov_b32_e32 v131, 0
	global_load_lds_dwordx4 v132, s[26:27]
	v_mov_b32_e32 v135, v131
	v_mov_b32_e32 v129, v131
	v_mov_b32_e32 v133, v131
	s_cmp_eq_u32 s7, 1
	s_mov_b32 s60, 0
	v_lshl_add_u64 v[6:7], s[52:53], 0, v[130:131]
	v_lshl_add_u64 v[4:5], s[52:53], 0, v[134:135]
	v_lshl_add_u64 v[0:1], s[50:51], 0, v[128:129]
	s_cselect_b64 s[36:37], -1, 0
	s_cmp_lg_u32 s7, 1
	v_lshl_add_u64 v[2:3], s[50:51], 0, v[132:133]
	s_cbranch_scc1 .LBB0_937
	s_barrier
	s_setprio 1

; #define PG8_STAGE(bufoff, gbase, voff) do { _Pragma("unroll") for (int _i = 0; _i < 2; ++_i) \
;         __builtin_amdgcn_global_load_lds((const unsigned*)((const char*)(gbase) + (voff)[_i]), (PG8_LAS unsigned*)(lds + (bufoff) + ldsw + _i * 8192), 16, 0, 0); } while (0)
; #define PG8_LDA(dst, b, h) do { _Pragma("unroll") for (int m = 0; m < 4; ++m) _Pragma("unroll") for (int k = 0; k < 2; ++k) dst[m][k] = *(const PG8_LAS bf16x8*)(lds + PG8_SA(b, h) + aoff + m * 2048 + k * 1024); } while (0)
; #define PG8_LDB(dst, b, h) do { _Pragma("unroll") for (int n = 0; n < 2; ++n) _Pragma("unroll") for (int k = 0; k < 2; ++k) dst[n][k] = *(const PG8_LAS bf16x8*)(lds + PG8_SB(b, h) + boff + n * 2048 + k * 1024); } while (0)
; #define PG8_WAIT_V(n) asm volatile("s_waitcnt vmcnt(" #n ")" ::: "memory")
; #define PG8_WAIT_L(n) asm volatile("s_waitcnt lgkmcnt(" #n ")" ::: "memory")
; #define PG8_BAR __builtin_amdgcn_s_barrier()
; #define PG8_SCHED __builtin_amdgcn_sched_barrier(0)
; template <class Epi, class Sched, bool ALIGN_EPI = false, bool SP2 = false>
; __device__ __forceinline__ void gemm_phase(PG8_LAS unsigned char* lds, const Gemm g, const Sched& S, const Epi& E, int tid_in) {
;     ...
;         const char* nA = has_next ? (const char*)g.A + (size_t)nxt.pm * tstep : cA; const char* nB = has_next ? (const char*)g.Bt + (size_t)nxt.pn * tstepB : cB;
;         for (int t = 0; t < nt; t += 2) {
;             const bool last = (t == nt - 2);
;             const char* a1 = cA + (size_t)(t + 1) * kstep;
;             const char* a2 = last ? nA : cA + (size_t)(t + 2) * kstep; const char* b2 = last ? nB : cB + (size_t)(t + 2) * kstep;
;             const char* a3 = a2 + kstep; const char* b3 = b2 + kstep;
;             if (last && has_next) S.a_ready(nxt);
;             if constexpr (SP2) {
;             PG8_LDB(B0, 0, 0); PG8_LDB(B1, 0, 1); PG8_SCHED; PG8_LDA(At, 0, 0); PG8_STAGE(PG8_SA(1, 1), a1 + hstep, voffA);
;             PG8_WAIT_V(8); PG8_WAIT_L(0); PG8_BAR; PG8_MMA(0, 0, At, B0); PG8_MMA(0, 1, At, B1); PG8_BAR; PG8_SCHED;
;             PG8_LDA(At, 0, 1); PG8_STAGE(PG8_SB(0, 0), b2, voffB); PG8_STAGE(PG8_SB(0, 1), b2 + hstepB, voffB); PG8_STAGE(PG8_SA(0, 0), a2, voffA);
;             PG8_WAIT_V(8); PG8_WAIT_L(0); PG8_BAR; PG8_MMA(1, 0, At, B0); PG8_MMA(1, 1, At, B1); PG8_BAR; PG8_SCHED;
.Lkb_skip_7:
.LBB0_949:
	ds_read_b128 v[146:149], v153
	ds_read_b128 v[158:161], v153 offset:1024
	ds_read_b128 v[162:165], v153 offset:2048
	ds_read_b128 v[166:169], v153 offset:3072
	ds_read_b128 v[170:173], v154
	ds_read_b128 v[174:177], v154 offset:1024
	ds_read_b128 v[178:181], v154 offset:2048
	ds_read_b128 v[182:185], v154 offset:3072
	s_add_u32 s10, s50, 0x100
	s_addc_u32 s11, s51, 0
	s_cmpk_eq_i32 s70, 0x7c
	s_cselect_b32 s55, s45, s11
	s_cselect_b32 s54, s44, s10
	s_cselect_b32 s53, s43, s69
	s_cselect_b32 s52, s67, s68
	v_lshl_add_u64 v[218:219], s[50:51], 0, v[138:139]
	s_add_i32 m0, s49, 0xc000
	ds_read_b128 v[186:189], v155
	ds_read_b128 v[190:193], v155 offset:1024
	ds_read_b128 v[194:197], v155 offset:2048
	ds_read_b128 v[198:201], v155 offset:3072
	ds_read_b128 v[202:205], v155 offset:4096
	ds_read_b128 v[206:209], v155 offset:5120
	ds_read_b128 v[210:213], v155 offset:6144
	ds_read_b128 v[214:217], v155 offset:7168
	global_load_lds_dwordx4 v[218:219], off
	v_lshl_add_u64 v[218:219], s[50:51], 0, v[140:141]
	s_add_i32 m0, s49, 0xe000
	s_nop 0
	global_load_lds_dwordx4 v[218:219], off
	s_waitcnt vmcnt(8)
	s_waitcnt lgkmcnt(0)
	s_barrier
	s_waitcnt lgkmcnt(0)
	v_mfma_f32_16x16x32_bf16 v[124:127], v[146:149], v[186:189], v[124:127]
	v_mfma_f32_16x16x32_bf16 v[120:123], v[162:165], v[186:189], v[120:123]
	v_mfma_f32_16x16x32_bf16 v[108:111], v[146:149], v[194:197], v[108:111]
	v_mfma_f32_16x16x32_bf16 v[104:107], v[162:165], v[194:197], v[104:107]
	v_mfma_f32_16x16x32_bf16 v[92:95], v[146:149], v[202:205], v[92:95]
	v_mfma_f32_16x16x32_bf16 v[88:91], v[162:165], v[202:205], v[88:91]
	v_mfma_f32_16x16x32_bf16 v[76:79], v[146:149], v[210:213], v[76:79]
	v_mfma_f32_16x16x32_bf16 v[72:75], v[162:165], v[210:213], v[72:75]
	v_mfma_f32_16x16x32_bf16 v[124:127], v[158:161], v[190:193], v[124:127]
	v_mfma_f32_16x16x32_bf16 v[120:123], v[166:169], v[190:193], v[120:123]
	v_mfma_f32_16x16x32_bf16 v[108:111], v[158:161], v[198:201], v[108:111]
	v_mfma_f32_16x16x32_bf16 v[104:107], v[166:169], v[198:201], v[104:107]
	v_mfma_f32_16x16x32_bf16 v[92:95], v[158:161], v[206:209], v[92:95]
	v_mfma_f32_16x16x32_bf16 v[88:91], v[166:169], v[206:209], v[88:91]
	v_mfma_f32_16x16x32_bf16 v[76:79], v[158:161], v[214:217], v[76:79]
	v_mfma_f32_16x16x32_bf16 v[72:75], v[166:169], v[214:217], v[72:75]
	v_mfma_f32_16x16x32_bf16 v[116:119], v[170:173], v[186:189], v[116:119]
	v_mfma_f32_16x16x32_bf16 v[112:115], v[178:181], v[186:189], v[112:115]
	v_mfma_f32_16x16x32_bf16 v[100:103], v[170:173], v[194:197], v[100:103]
	v_mfma_f32_16x16x32_bf16 v[96:99], v[178:181], v[194:197], v[96:99]
	v_mfma_f32_16x16x32_bf16 v[84:87], v[170:173], v[202:205], v[84:87]
	v_mfma_f32_16x16x32_bf16 v[80:83], v[178:181], v[202:205], v[80:83]
	v_mfma_f32_16x16x32_bf16 v[68:71], v[170:173], v[210:213], v[68:71]
	v_mfma_f32_16x16x32_bf16 v[64:67], v[178:181], v[210:213], v[64:67]
	v_mfma_f32_16x16x32_bf16 v[116:119], v[174:177], v[190:193], v[116:119]
	v_mfma_f32_16x16x32_bf16 v[112:115], v[182:185], v[190:193], v[112:115]
	v_mfma_f32_16x16x32_bf16 v[100:103], v[174:177], v[198:201], v[100:103]
	v_mfma_f32_16x16x32_bf16 v[96:99], v[182:185], v[198:201], v[96:99]
	v_mfma_f32_16x16x32_bf16 v[84:87], v[174:177], v[206:209], v[84:87]
	v_mfma_f32_16x16x32_bf16 v[80:83], v[182:185], v[206:209], v[80:83]
	v_mfma_f32_16x16x32_bf16 v[68:71], v[174:177], v[214:217], v[68:71]
	v_mfma_f32_16x16x32_bf16 v[64:67], v[182:185], v[214:217], v[64:67]
	s_barrier
	s_add_i32 s26, s63, s56
	v_lshl_add_u64 v[218:219], s[52:53], 0, v[130:131]
	s_mov_b32 m0, s26
	ds_read_b128 v[186:189], v155 offset:16384
	ds_read_b128 v[190:193], v155 offset:17408
	ds_read_b128 v[194:197], v155 offset:18432
	ds_read_b128 v[198:201], v155 offset:19456
	ds_read_b128 v[202:205], v155 offset:20480
	ds_read_b128 v[206:209], v155 offset:21504
	ds_read_b128 v[210:213], v155 offset:22528
	ds_read_b128 v[214:217], v155 offset:23552
	global_load_lds_dwordx4 v[218:219], off
	s_add_i32 m0, s26, 0x2000
	s_add_u32 s26, s52, 0x80000
	v_lshl_add_u64 v[220:221], s[52:53], 0, v[134:135]
	s_addc_u32 s27, s53, 0
	s_add_i32 s33, s64, s56
	global_load_lds_dwordx4 v[220:221], off
	v_lshl_add_u64 v[222:223], s[26:27], 0, v[130:131]
	s_mov_b32 m0, s33
	v_lshl_add_u64 v[224:225], s[54:55], 0, v[132:133]
	global_load_lds_dwordx4 v[222:223], off
	v_lshl_add_u64 v[222:223], s[26:27], 0, v[134:135]
	s_add_i32 m0, s33, 0x2000
	s_nop 0
	global_load_lds_dwordx4 v[222:223], off
	v_lshl_add_u64 v[222:223], s[54:55], 0, v[128:129]
	s_mov_b32 m0, s49
	s_nop 0
	global_load_lds_dwordx4 v[222:223], off
	s_mov_b32 m0, s57
	s_nop 0
	global_load_lds_dwordx4 v[224:225], off
	s_waitcnt vmcnt(8)
	s_waitcnt lgkmcnt(0)
	s_barrier
; #define PG8_STAGE(bufoff, gbase, voff) do { _Pragma("unroll") for (int _i = 0; _i < 2; ++_i) \
;         __builtin_amdgcn_global_load_lds((const unsigned*)((const char*)(gbase) + (voff)[_i]), (PG8_LAS unsigned*)(lds + (bufoff) + ldsw + _i * 8192), 16, 0, 0); } while (0)
; #define PG8_LDA(dst, b, h) do { _Pragma("unroll") for (int m = 0; m < 4; ++m) _Pragma("unroll") for (int k = 0; k < 2; ++k) dst[m][k] = *(const PG8_LAS bf16x8*)(lds + PG8_SA(b, h) + aoff + m * 2048 + k * 1024); } while (0)
; #define PG8_LDB(dst, b, h) do { _Pragma("unroll") for (int n = 0; n < 2; ++n) _Pragma("unroll") for (int k = 0; k < 2; ++k) dst[n][k] = *(const PG8_LAS bf16x8*)(lds + PG8_SB(b, h) + boff + n * 2048 + k * 1024); } while (0)
; #define PG8_MMA(ai, bj, At, Bt) do { __builtin_amdgcn_s_setprio(1); _Pragma("unroll") for (int m = 0; m < 4; ++m) _Pragma("unroll") for (int n = 0; n < 2; ++n) _Pragma("unroll") for (int k = 0; k < 2; ++k) \
;         acc[ai][bj][m][n] = __builtin_amdgcn_mfma_f32_16x16x32_bf16(Bt[n][k], At[m][k], acc[ai][bj][m][n], 0, 0, 0); __builtin_amdgcn_s_setprio(0); } while (0)
; #define PG8_WAIT_V(n) asm volatile("s_waitcnt vmcnt(" #n ")" ::: "memory")
; #define PG8_WAIT_L(n) asm volatile("s_waitcnt lgkmcnt(" #n ")" ::: "memory")
; #define PG8_BAR __builtin_amdgcn_s_barrier()
; #define PG8_SCHED __builtin_amdgcn_sched_barrier(0)
; template <class Epi, class Sched, bool ALIGN_EPI = false, bool SP2 = false>
; __device__ __forceinline__ void gemm_phase(PG8_LAS unsigned char* lds, const Gemm g, const Sched& S, const Epi& E, int tid_in) {
;     ...
;             PG8_WAIT_V(8); PG8_WAIT_L(0); PG8_BAR; PG8_MMA(1, 0, At, B0); PG8_MMA(1, 1, At, B1); PG8_BAR; PG8_SCHED;
;             PG8_LDB(B0, 1, 0); PG8_LDB(B1, 1, 1); PG8_SCHED; PG8_LDA(At, 1, 0); PG8_STAGE(PG8_SA(0, 1), a2 + hstep, voffA);
;             PG8_WAIT_V(8); PG8_WAIT_L(0); PG8_BAR; PG8_MMA(0, 0, At, B0); PG8_MMA(0, 1, At, B1); PG8_BAR; PG8_SCHED;
	s_waitcnt lgkmcnt(0)
	v_mfma_f32_16x16x32_bf16 v[60:63], v[146:149], v[186:189], v[60:63]
	v_mfma_f32_16x16x32_bf16 v[56:59], v[162:165], v[186:189], v[56:59]
	v_mfma_f32_16x16x32_bf16 v[44:47], v[146:149], v[194:197], v[44:47]
	v_mfma_f32_16x16x32_bf16 v[40:43], v[162:165], v[194:197], v[40:43]
	v_mfma_f32_16x16x32_bf16 v[28:31], v[146:149], v[202:205], v[28:31]
	v_mfma_f32_16x16x32_bf16 v[24:27], v[162:165], v[202:205], v[24:27]
	v_mfma_f32_16x16x32_bf16 v[12:15], v[146:149], v[210:213], v[12:15]
	v_mfma_f32_16x16x32_bf16 v[8:11], v[162:165], v[210:213], v[8:11]
	v_mfma_f32_16x16x32_bf16 v[60:63], v[158:161], v[190:193], v[60:63]
	v_mfma_f32_16x16x32_bf16 v[56:59], v[166:169], v[190:193], v[56:59]
	v_mfma_f32_16x16x32_bf16 v[44:47], v[158:161], v[198:201], v[44:47]
	v_mfma_f32_16x16x32_bf16 v[40:43], v[166:169], v[198:201], v[40:43]
	v_mfma_f32_16x16x32_bf16 v[28:31], v[158:161], v[206:209], v[28:31]
	v_mfma_f32_16x16x32_bf16 v[24:27], v[166:169], v[206:209], v[24:27]
	v_mfma_f32_16x16x32_bf16 v[12:15], v[158:161], v[214:217], v[12:15]
	v_mfma_f32_16x16x32_bf16 v[8:11], v[166:169], v[214:217], v[8:11]
	v_mfma_f32_16x16x32_bf16 v[52:55], v[170:173], v[186:189], v[52:55]
	v_mfma_f32_16x16x32_bf16 v[48:51], v[178:181], v[186:189], v[48:51]
	v_mfma_f32_16x16x32_bf16 v[36:39], v[170:173], v[194:197], v[36:39]
	v_mfma_f32_16x16x32_bf16 v[32:35], v[178:181], v[194:197], v[32:35]
	v_mfma_f32_16x16x32_bf16 v[20:23], v[170:173], v[202:205], v[20:23]
	v_mfma_f32_16x16x32_bf16 v[16:19], v[178:181], v[202:205], v[16:19]
	v_mfma_f32_16x16x32_bf16 v[4:7], v[170:173], v[210:213], v[4:7]
	v_mfma_f32_16x16x32_bf16 v[0:3], v[178:181], v[210:213], v[0:3]
	v_mfma_f32_16x16x32_bf16 v[52:55], v[174:177], v[190:193], v[52:55]
	v_mfma_f32_16x16x32_bf16 v[48:51], v[182:185], v[190:193], v[48:51]
	v_mfma_f32_16x16x32_bf16 v[36:39], v[174:177], v[198:201], v[36:39]
	v_mfma_f32_16x16x32_bf16 v[32:35], v[182:185], v[198:201], v[32:35]
	v_mfma_f32_16x16x32_bf16 v[20:23], v[174:177], v[206:209], v[20:23]
	v_mfma_f32_16x16x32_bf16 v[16:19], v[182:185], v[206:209], v[16:19]
	v_mfma_f32_16x16x32_bf16 v[4:7], v[174:177], v[214:217], v[4:7]
	v_mfma_f32_16x16x32_bf16 v[0:3], v[182:185], v[214:217], v[0:3]
	s_barrier
	s_add_i32 s33, 0, 0x18000
	s_add_i32 s50, 0, 0x1c000
	v_add_u32_e32 v166, s33, v137
	v_add_u32_e32 v182, s50, v137
	ds_read_b128 v[146:149], v166
	ds_read_b128 v[158:161], v166 offset:1024
	ds_read_b128 v[162:165], v166 offset:2048
	ds_read_b128 v[166:169], v166 offset:3072
	ds_read_b128 v[170:173], v182
	ds_read_b128 v[174:177], v182 offset:1024
	ds_read_b128 v[178:181], v182 offset:2048
	ds_read_b128 v[182:185], v182 offset:3072
	s_add_u32 s26, s54, 0x204000
	s_addc_u32 s27, s55, 0
	s_mov_b32 m0, s58
	v_lshl_add_u64 v[226:227], s[26:27], 0, v[128:129]
	ds_read_b128 v[186:189], v155 offset:32768
	ds_read_b128 v[190:193], v155 offset:33792
	ds_read_b128 v[194:197], v155 offset:34816
	ds_read_b128 v[198:201], v155 offset:35840
	ds_read_b128 v[202:205], v155 offset:36864
	ds_read_b128 v[206:209], v155 offset:37888
	ds_read_b128 v[210:213], v155 offset:38912
	ds_read_b128 v[214:217], v155 offset:39936
	global_load_lds_dwordx4 v[226:227], off
	v_lshl_add_u64 v[226:227], s[26:27], 0, v[132:133]
	s_mov_b32 m0, s59
	s_nop 0
	global_load_lds_dwordx4 v[226:227], off
	s_waitcnt vmcnt(8)
	s_waitcnt lgkmcnt(0)
	s_barrier
	s_waitcnt lgkmcnt(0)
	v_mfma_f32_16x16x32_bf16 v[124:127], v[146:149], v[186:189], v[124:127]
	v_mfma_f32_16x16x32_bf16 v[120:123], v[162:165], v[186:189], v[120:123]
	v_mfma_f32_16x16x32_bf16 v[108:111], v[146:149], v[194:197], v[108:111]
	v_mfma_f32_16x16x32_bf16 v[104:107], v[162:165], v[194:197], v[104:107]
	v_mfma_f32_16x16x32_bf16 v[92:95], v[146:149], v[202:205], v[92:95]
	v_mfma_f32_16x16x32_bf16 v[88:91], v[162:165], v[202:205], v[88:91]
	v_mfma_f32_16x16x32_bf16 v[76:79], v[146:149], v[210:213], v[76:79]
	v_mfma_f32_16x16x32_bf16 v[72:75], v[162:165], v[210:213], v[72:75]
	v_mfma_f32_16x16x32_bf16 v[124:127], v[158:161], v[190:193], v[124:127]
	v_mfma_f32_16x16x32_bf16 v[120:123], v[166:169], v[190:193], v[120:123]
	v_mfma_f32_16x16x32_bf16 v[108:111], v[158:161], v[198:201], v[108:111]
	v_mfma_f32_16x16x32_bf16 v[104:107], v[166:169], v[198:201], v[104:107]
	v_mfma_f32_16x16x32_bf16 v[92:95], v[158:161], v[206:209], v[92:95]
	v_mfma_f32_16x16x32_bf16 v[88:91], v[166:169], v[206:209], v[88:91]
	v_mfma_f32_16x16x32_bf16 v[76:79], v[158:161], v[214:217], v[76:79]
	v_mfma_f32_16x16x32_bf16 v[72:75], v[166:169], v[214:217], v[72:75]
	v_mfma_f32_16x16x32_bf16 v[116:119], v[170:173], v[186:189], v[116:119]
	v_mfma_f32_16x16x32_bf16 v[112:115], v[178:181], v[186:189], v[112:115]
	v_mfma_f32_16x16x32_bf16 v[100:103], v[170:173], v[194:197], v[100:103]
	v_mfma_f32_16x16x32_bf16 v[96:99], v[178:181], v[194:197], v[96:99]
	v_mfma_f32_16x16x32_bf16 v[84:87], v[170:173], v[202:205], v[84:87]
	v_mfma_f32_16x16x32_bf16 v[80:83], v[178:181], v[202:205], v[80:83]
	v_mfma_f32_16x16x32_bf16 v[68:71], v[170:173], v[210:213], v[68:71]
	v_mfma_f32_16x16x32_bf16 v[64:67], v[178:181], v[210:213], v[64:67]
	v_mfma_f32_16x16x32_bf16 v[116:119], v[174:177], v[190:193], v[116:119]
	v_mfma_f32_16x16x32_bf16 v[112:115], v[182:185], v[190:193], v[112:115]
	v_mfma_f32_16x16x32_bf16 v[100:103], v[174:177], v[198:201], v[100:103]
	v_mfma_f32_16x16x32_bf16 v[96:99], v[182:185], v[198:201], v[96:99]
	v_mfma_f32_16x16x32_bf16 v[84:87], v[174:177], v[206:209], v[84:87]
	v_mfma_f32_16x16x32_bf16 v[80:83], v[182:185], v[206:209], v[80:83]
	v_mfma_f32_16x16x32_bf16 v[68:71], v[174:177], v[214:217], v[68:71]
	v_mfma_f32_16x16x32_bf16 v[64:67], v[182:185], v[214:217], v[64:67]
	s_barrier
; #define PG8_STAGE(bufoff, gbase, voff) do { _Pragma("unroll") for (int _i = 0; _i < 2; ++_i) \
;         __builtin_amdgcn_global_load_lds((const unsigned*)((const char*)(gbase) + (voff)[_i]), (PG8_LAS unsigned*)(lds + (bufoff) + ldsw + _i * 8192), 16, 0, 0); } while (0)
; #define PG8_LDA(dst, b, h) do { _Pragma("unroll") for (int m = 0; m < 4; ++m) _Pragma("unroll") for (int k = 0; k < 2; ++k) dst[m][k] = *(const PG8_LAS bf16x8*)(lds + PG8_SA(b, h) + aoff + m * 2048 + k * 1024); } while (0)
; #define PG8_MMA(ai, bj, At, Bt) do { __builtin_amdgcn_s_setprio(1); _Pragma("unroll") for (int m = 0; m < 4; ++m) _Pragma("unroll") for (int n = 0; n < 2; ++n) _Pragma("unroll") for (int k = 0; k < 2; ++k) \
;         acc[ai][bj][m][n] = __builtin_amdgcn_mfma_f32_16x16x32_bf16(Bt[n][k], At[m][k], acc[ai][bj][m][n], 0, 0, 0); __builtin_amdgcn_s_setprio(0); } while (0)
; template <class Epi, class Sched, bool ALIGN_EPI = false, bool SP2 = false>
; __device__ __forceinline__ void gemm_phase(PG8_LAS unsigned char* lds, const Gemm g, const Sched& S, const Epi& E, int tid_in) {
;     ...
;             PG8_LDA(At, 1, 1); PG8_STAGE(PG8_SB(1, 0), b3, voffB); PG8_STAGE(PG8_SB(1, 1), b3 + hstepB, voffB); PG8_STAGE(PG8_SA(1, 0), a3, voffA);
;             PG8_WAIT_V(8); PG8_WAIT_L(0); PG8_BAR; PG8_MMA(1, 0, At, B0); PG8_MMA(1, 1, At, B1); PG8_BAR; PG8_SCHED;
;     __device__ __forceinline__ void operator()(const f32x4 (&acc)[2][2][4][2], const Unit& u, int wr, int wc, int fr, int fq) const {
;     ...
;                 const int row = u.pm * BM + ai * HALF + wr * 64 + m * 16 + r; float q = 0.f;
; #pragma unroll
;                 for (int bj = 0; bj < 2; ++bj) {
;                     const size_t off = (size_t)row * 2048 + u.pn * BM + wc * 64 + bj * 32 + 8 * p;
;                     f32x4 b0, b1;
;                     if (BASE_F32) { b0 = *(const f32x4*)((const float*)base + off); b1 = *(const f32x4*)((const float*)base + off + 4); }
;                     else { const u32x4 bb = *(const u32x4*)((const bf16_t*)base + off);
;                         b0 = (f32x4){__uint_as_float(bb.x << 16), __uint_as_float(bb.x & 0xffff0000u), __uint_as_float(bb.y << 16), __uint_as_float(bb.y & 0xffff0000u)};
;                         b1 = (f32x4){__uint_as_float(bb.z << 16), __uint_as_float(bb.z & 0xffff0000u), __uint_as_float(bb.w << 16), __uint_as_float(bb.w & 0xffff0000u)}; }
	s_add_i32 s26, s33, s56
	v_lshl_add_u64 v[218:219], v[218:219], 0, s[38:39]
	s_mov_b32 m0, s26
	ds_read_b128 v[186:189], v155 offset:49152
	ds_read_b128 v[190:193], v155 offset:50176
	ds_read_b128 v[194:197], v155 offset:51200
	ds_read_b128 v[198:201], v155 offset:52224
	ds_read_b128 v[202:205], v155 offset:53248
	ds_read_b128 v[206:209], v155 offset:54272
	ds_read_b128 v[210:213], v155 offset:55296
	ds_read_b128 v[214:217], v155 offset:56320
	global_load_lds_dwordx4 v[218:219], off
	s_add_i32 m0, s26, 0x2000
	s_add_u32 s26, s52, 0x80080
	v_lshl_add_u64 v[218:219], v[220:221], 0, s[38:39]
	s_addc_u32 s27, s53, 0
	s_add_i32 s33, s50, s56
	global_load_lds_dwordx4 v[218:219], off
	v_lshl_add_u64 v[218:219], s[26:27], 0, v[130:131]
	s_mov_b32 m0, s33
	s_nop 0
	global_load_lds_dwordx4 v[218:219], off
	v_lshl_add_u64 v[218:219], s[26:27], 0, v[134:135]
	s_add_i32 m0, s33, 0x2000
	s_nop 0
	global_load_lds_dwordx4 v[218:219], off
	v_lshl_add_u64 v[218:219], v[222:223], 0, s[38:39]
	s_mov_b32 m0, s61
	s_nop 0
	global_load_lds_dwordx4 v[218:219], off
	v_lshl_add_u64 v[218:219], v[224:225], 0, s[38:39]
	s_mov_b32 m0, s62
	s_nop 0
	global_load_lds_dwordx4 v[218:219], off
	s_waitcnt vmcnt(8)
	s_waitcnt lgkmcnt(0)
	s_barrier
	s_waitcnt lgkmcnt(0)
	v_mfma_f32_16x16x32_bf16 v[60:63], v[146:149], v[186:189], v[60:63]
	v_mfma_f32_16x16x32_bf16 v[56:59], v[162:165], v[186:189], v[56:59]
	v_mfma_f32_16x16x32_bf16 v[44:47], v[146:149], v[194:197], v[44:47]
	v_mfma_f32_16x16x32_bf16 v[40:43], v[162:165], v[194:197], v[40:43]
	v_mfma_f32_16x16x32_bf16 v[28:31], v[146:149], v[202:205], v[28:31]
	v_mfma_f32_16x16x32_bf16 v[24:27], v[162:165], v[202:205], v[24:27]
	v_mfma_f32_16x16x32_bf16 v[12:15], v[146:149], v[210:213], v[12:15]
	v_mfma_f32_16x16x32_bf16 v[8:11], v[162:165], v[210:213], v[8:11]
	v_mfma_f32_16x16x32_bf16 v[60:63], v[158:161], v[190:193], v[60:63]
	v_mfma_f32_16x16x32_bf16 v[56:59], v[166:169], v[190:193], v[56:59]
	v_mfma_f32_16x16x32_bf16 v[44:47], v[158:161], v[198:201], v[44:47]
	v_mfma_f32_16x16x32_bf16 v[40:43], v[166:169], v[198:201], v[40:43]
	v_mfma_f32_16x16x32_bf16 v[28:31], v[158:161], v[206:209], v[28:31]
	v_mfma_f32_16x16x32_bf16 v[24:27], v[166:169], v[206:209], v[24:27]
	v_mfma_f32_16x16x32_bf16 v[12:15], v[158:161], v[214:217], v[12:15]
	v_mfma_f32_16x16x32_bf16 v[8:11], v[166:169], v[214:217], v[8:11]
	v_mfma_f32_16x16x32_bf16 v[52:55], v[170:173], v[186:189], v[52:55]
	v_mfma_f32_16x16x32_bf16 v[48:51], v[178:181], v[186:189], v[48:51]
	v_mfma_f32_16x16x32_bf16 v[36:39], v[170:173], v[194:197], v[36:39]
	v_mfma_f32_16x16x32_bf16 v[32:35], v[178:181], v[194:197], v[32:35]
	v_mfma_f32_16x16x32_bf16 v[20:23], v[170:173], v[202:205], v[20:23]
	v_mfma_f32_16x16x32_bf16 v[16:19], v[178:181], v[202:205], v[16:19]
	v_mfma_f32_16x16x32_bf16 v[4:7], v[170:173], v[210:213], v[4:7]
	v_mfma_f32_16x16x32_bf16 v[0:3], v[178:181], v[210:213], v[0:3]
	v_mfma_f32_16x16x32_bf16 v[52:55], v[174:177], v[190:193], v[52:55]
	v_mfma_f32_16x16x32_bf16 v[48:51], v[182:185], v[190:193], v[48:51]
	v_mfma_f32_16x16x32_bf16 v[36:39], v[174:177], v[198:201], v[36:39]
	v_mfma_f32_16x16x32_bf16 v[32:35], v[182:185], v[198:201], v[32:35]
	v_mfma_f32_16x16x32_bf16 v[20:23], v[174:177], v[206:209], v[20:23]
	v_mfma_f32_16x16x32_bf16 v[16:19], v[182:185], v[206:209], v[16:19]
	v_mfma_f32_16x16x32_bf16 v[4:7], v[174:177], v[214:217], v[4:7]
	v_mfma_f32_16x16x32_bf16 v[0:3], v[182:185], v[214:217], v[0:3]
	s_barrier
	s_add_i32 s70, s70, 2
	s_add_u32 s68, s68, 0x100
	s_addc_u32 s69, s69, 0
	s_cmpk_gt_u32 s70, 0x7d
	s_mov_b64 s[50:51], s[10:11]
	s_cbranch_scc0 .LBB0_949
	v_lshl_add_u32 v148, s66, 8, v150
	v_lshl_or_b32 v146, s48, 8, v136
	v_lshl_add_u32 v147, v148, 11, v146
	v_lshlrev_b32_e32 v159, 1, v147
	v_lshlrev_b32_e32 v208, 3, v148
	global_load_dwordx4 v[160:163], v159, s[28:29]
	global_load_dwordx4 v[164:167], v159, s[28:29] offset:64
	v_add_u32_e32 v149, 0x10000, v159
	global_load_dwordx4 v[168:171], v149, s[28:29]
	global_load_dwordx4 v[172:175], v149, s[28:29] offset:64
	v_add_u32_e32 v209, 0x20000, v159
	global_load_dwordx4 v[176:179], v209, s[28:29]
	global_load_dwordx4 v[180:183], v209, s[28:29] offset:64
	v_add_u32_e32 v149, 0x30000, v159
	global_load_dwordx4 v[184:187], v149, s[28:29]
	global_load_dwordx4 v[188:191], v149, s[28:29] offset:64
	v_add_u32_e32 v209, 0x80000, v159
	global_load_dwordx4 v[192:195], v209, s[28:29]
	global_load_dwordx4 v[196:199], v209, s[28:29] offset:64
	v_add_u32_e32 v149, 0x90000, v159
	global_load_dwordx4 v[200:203], v149, s[28:29]
	global_load_dwordx4 v[204:207], v149, s[28:29] offset:64
	v_add_u32_e32 v209, 0xa0000, v159
	global_load_dwordx4 v[212:215], v209, s[28:29]
	global_load_dwordx4 v[216:219], v209, s[28:29] offset:64
	v_add_u32_e32 v149, 0xb0000, v159
	global_load_dwordx4 v[220:223], v149, s[28:29]
	global_load_dwordx4 v[224:227], v149, s[28:29] offset:64
	s_and_b64 vcc, exec, s[40:41]
	s_cbranch_vccz .LBB0_952
	s_barrier
